# non-temporal hint on read-once streaming loads (widen gate values, f32 weights in conversion tiles, residual stream reads in the resid epilogue)
# speedup vs baseline: 1.0000x; 1.0000x over previous
; template <bool MAP = false>
; DI void conv_tile(const float* __restrict__ src, int N, int K, bfu* __restrict__ dst, const float* __restrict__ g,
;                   int tk, int tn, char* smem, int ldk = -1) {
;     ...
;   for (int j = 0; j < 4; ++j) {
;     int k = (tid >> 4) + 16 * j, n4 = (tid & 15) * 4;
;     int gn = tn * 64 + n4, gk = tk * 64 + k;
;     float4 v = make_float4(0.f, 0.f, 0.f, 0.f);
;     const int og = MAP ? in_colmap(gn) : (gn < N ? gn : -1);
;     if (og >= 0) v = *(const float4*)(src + (size_t)gk * N + og);
;     float gg = g ? g[gk] : 1.f;
;     T[k * 65 + n4 + 0] = v.x * gg; T[k * 65 + n4 + 1] = v.y * gg; T[k * 65 + n4 + 2] = v.z * gg; T[k * 65 + n4 + 3] = v.w * gg;
; DI void conv_item_B(const Params& p, int L, int it, char* smem) {
;     ...
;   else if (it < 52) { int t = it - 36; conv_tile(p.mla_w_ukv + (size_t)L * 128 * 512, 512, 128, p.wt_ukv, p.mla_ckv_g + L * 128, t / 8, t % 8, smem); }
.LBB0_47:
	s_add_i32 s2, s6, 0xfffff91c
	v_mov_b32_e32 v11, v224
	s_lshl_b32 s3, s2, 6
	v_lshlrev_b32_e32 v0, 2, v11
	s_lshl_b32 s2, s2, 3
	v_ashrrev_i32_e32 v13, 4, v11
	v_and_b32_e32 v14, 60, v0
	s_and_b32 s4, s3, 0x1c0
	s_and_b32 s5, s2, 0x7fffffc0
	v_or_b32_e32 v0, s4, v14
	v_add_u32_e32 v8, s5, v13
	v_lshlrev_b32_e32 v188, 2, v0
	v_ashrrev_i32_e32 v9, 31, v8
	v_lshl_add_u64 v[6:7], s[10:11], 0, v[188:189]
	v_lshlrev_b64 v[0:1], 11, v[8:9]
	v_lshl_add_u64 v[0:1], v[6:7], 0, v[0:1]
	s_barrier
	v_add_u32_e32 v210, 16, v8
	v_ashrrev_i32_e32 v211, 31, v210
	v_lshlrev_b64 v[210:211], 11, v[210:211]
	v_lshl_add_u64 v[210:211], v[6:7], 0, v[210:211]
	global_load_dwordx4 v[240:243], v[210:211], off nt
	v_add_u32_e32 v210, 32, v8
	v_ashrrev_i32_e32 v211, 31, v210
	v_lshlrev_b64 v[210:211], 11, v[210:211]
	v_lshl_add_u64 v[210:211], v[6:7], 0, v[210:211]
	global_load_dwordx4 v[244:247], v[210:211], off nt
	v_add_u32_e32 v210, 48, v8
	v_ashrrev_i32_e32 v211, 31, v210
	v_lshlrev_b64 v[210:211], 11, v[210:211]
	v_lshl_add_u64 v[210:211], v[6:7], 0, v[210:211]
	global_load_dwordx4 v[248:251], v[210:211], off nt
	global_load_dwordx4 v[0:3], v[0:1], off
	v_readlane_b32 s16, v254, 42
	v_readlane_b32 s17, v254, 43
	v_mov_b32_e32 v10, 1.0
	s_andn2_b64 vcc, exec, s[16:17]
	v_cndmask_b32_e64 v4, 0, 1, s[16:17]
	v_cmp_ne_u32_e64 s[2:3], 1, v4
	v_lshl_add_u64 v[4:5], v[8:9], 2, s[14:15]
	v_mov_b32_e32 v12, 1.0
	s_cbranch_vccnz .LBB0_49
	global_load_dword v12, v[4:5], off

; DI int TID() { int t = threadIdx.x; asm volatile("" : "+v"(t)); return t; }
; DI int in_colmap(int n) {
;   if (n < 1280) return n;
;   if (n < 1920) return n + 32;
;   if (n < 2688) return n + 44;
;   if (n < 2720) return n - 2688 + 1280;
;   if (n < 2732) return n - 2720 + 1952;
;   if (n < 2736) return n;
;   if (n < 2752) return -1;
;   if (n < 6848) return n - 16;
;   return -1;
; }
; template <bool MAP = false>
; DI void conv_tile(const float* __restrict__ src, int N, int K, bfu* __restrict__ dst, const float* __restrict__ g,
;                   int tk, int tn, char* smem, int ldk = -1) {
;   const int LK = ldk < 0 ? K : ldk;
;   float* T = (float*)smem;
;   const int tid = TID();
;   __syncthreads();
; #pragma unroll
;   for (int j = 0; j < 4; ++j) {
;     int k = (tid >> 4) + 16 * j, n4 = (tid & 15) * 4;
;     int gn = tn * 64 + n4, gk = tk * 64 + k;
;     float4 v = make_float4(0.f, 0.f, 0.f, 0.f);
;     const int og = MAP ? in_colmap(gn) : (gn < N ? gn : -1);
;     if (og >= 0) v = *(const float4*)(src + (size_t)gk * N + og);
;     float gg = g ? g[gk] : 1.f;
;     T[k * 65 + n4 + 0] = v.x * gg; T[k * 65 + n4 + 1] = v.y * gg; T[k * 65 + n4 + 2] = v.z * gg; T[k * 65 + n4 + 3] = v.w * gg;
.LBB0_68:
	s_andn2_b64 vcc, exec, s[2:3]
	s_cbranch_vccnz .LBB0_26
	s_mul_hi_i32 s2, s6, 0x4bda12f7
	s_lshr_b32 s3, s2, 31
	s_ashr_i32 s2, s2, 5
	s_add_i32 s2, s2, s3
	s_mul_i32 s3, s2, 0x6c
	v_mov_b32_e32 v9, v224
	s_sub_i32 s3, s6, s3
	s_lshl_b32 s7, s3, 6
	v_lshlrev_b32_e32 v0, 2, v9
	v_and_b32_e32 v5, 60, v0
	s_lshl_b32 s34, s2, 6
	v_or_b32_e32 v0, s7, v5
	s_movk_i32 s2, 0x500
	s_cmpk_lt_u32 s7, 0xa80
	v_cmp_gt_i32_e32 vcc, s2, v0
	s_cselect_b64 s[4:5], -1, 0
	s_add_i32 s2, s7, 0xfffff540
	s_cmpk_lt_u32 s2, 0x1000
	v_add_u32_e32 v1, -16, v0
	s_cselect_b64 s[2:3], -1, 0
	v_cndmask_b32_e64 v1, -1, v1, s[2:3]
	s_movk_i32 s2, 0xab0
	v_cmp_gt_u32_e64 s[2:3], s2, v0
	v_add_u32_e32 v2, 0xfffffd00, v0
	v_add_u32_e32 v3, 0xfffffa80, v0
	v_cndmask_b32_e64 v1, v1, v0, s[2:3]
	s_movk_i32 s2, 0xaac
	v_cmp_gt_u32_e64 s[2:3], s2, v0
	v_ashrrev_i32_e32 v4, 4, v9
	v_add_u32_e32 v6, s34, v4
	v_cndmask_b32_e64 v1, v1, v2, s[2:3]
	s_movk_i32 s2, 0xaa0
	v_cmp_gt_u32_e64 s[2:3], s2, v0
	s_barrier
	s_nop 0
	v_cndmask_b32_e64 v1, v1, v3, s[2:3]
	s_or_b64 s[2:3], vcc, s[4:5]
	s_cmpk_lt_u32 s7, 0x780
	s_cselect_b32 s4, 32, 44
	v_mov_b32_e32 v2, s4
	v_cndmask_b32_e64 v2, v2, 0, vcc
	v_add_u32_e32 v0, v2, v0
	v_cndmask_b32_e64 v188, v1, v0, s[2:3]
	v_mov_b32_e32 v0, 0
	v_cmp_lt_i32_e64 s[2:3], -1, v188
	v_mov_b32_e32 v1, v0
	v_mov_b32_e32 v2, v0
	v_mov_b32_e32 v3, v0
	s_and_saveexec_b64 s[4:5], s[2:3]
	s_cbranch_execz .LBB0_71
	v_mov_b64_e32 v[0:1], s[92:93]
	s_movk_i32 s12, 0x6ac0
	v_mad_i64_i32 v[0:1], s[28:29], v6, s12, v[0:1]
	v_lshl_add_u64 v[0:1], v[188:189], 2, v[0:1]
	v_add_u32_e32 v210, 16, v6
	v_mov_b64_e32 v[212:213], s[92:93]
	v_mad_i64_i32 v[212:213], s[98:99], v210, s12, v[212:213]
	v_lshl_add_u64 v[212:213], v[188:189], 2, v[212:213]
	global_load_dwordx4 v[240:243], v[212:213], off nt
	v_add_u32_e32 v210, 32, v6
	v_mov_b64_e32 v[212:213], s[92:93]
	v_mad_i64_i32 v[212:213], s[98:99], v210, s12, v[212:213]
	v_lshl_add_u64 v[212:213], v[188:189], 2, v[212:213]
	global_load_dwordx4 v[244:247], v[212:213], off nt
	v_add_u32_e32 v210, 48, v6
	v_mov_b64_e32 v[212:213], s[92:93]
	v_mad_i64_i32 v[212:213], s[98:99], v210, s12, v[212:213]
	v_lshl_add_u64 v[212:213], v[188:189], 2, v[212:213]
	global_load_dwordx4 v[248:251], v[212:213], off nt
	global_load_dwordx4 v[0:3], v[0:1], off

; template <bool NORM, bool DEEP, int MTW, int KSEG, class HOOK>
; DI void gemm_core_h(const bfu* __restrict__ A, int lda, const bfu* __restrict__ Bt, int ldb, int K, int m0, int n0,
;                     f32x16 (&acc)[MTW][2], char* smem, HOOK hook) {
;     ...
;   if (DEEP) {
;     for (int kt = 0; kt < nk; kt += 2) {
;       GEMM_STEP(ra0, rb0, kt, 2)
;       GEMM_STEP(ra1, rb1, kt + 1, 2)
;     }
;   } else {
;     for (int kt = 0; kt < nk; ++kt) {
;       GEMM_STEP(ra0, rb0, kt, 1)
.LBB0_96:
	s_waitcnt lgkmcnt(0)
	s_barrier
	s_waitcnt vmcnt(11)
	ds_write_b128 v183, v[140:143] offset:36864
	v_add_u32_e32 v188, s5, v178
	v_add_u32_e32 v188, 0x40, v188
	v_lshl_add_u64 v[140:141], v[188:189], 1, s[26:27]
	global_load_dwordx4 v[140:143], v[140:141], off
	s_waitcnt vmcnt(11)
	ds_write_b128 v183, v[136:139] offset:41472
	v_add_u32_e32 v188, s5, v178
	v_add_u32_e32 v188, 0x20040, v188
	v_lshl_add_u64 v[136:137], v[188:189], 1, s[26:27]
	global_load_dwordx4 v[136:139], v[136:137], off
	s_waitcnt vmcnt(11)
	ds_write_b128 v183, v[128:131] offset:46080
	v_add_u32_e32 v188, s5, v178
	v_add_u32_e32 v188, 0x40040, v188
	v_lshl_add_u64 v[128:129], v[188:189], 1, s[26:27]
	global_load_dwordx4 v[128:131], v[128:129], off
	s_waitcnt vmcnt(11)
	ds_write_b128 v183, v[132:135] offset:50688
	v_add_u32_e32 v188, s5, v178
	v_add_u32_e32 v188, 0x60040, v188
	v_lshl_add_u64 v[132:133], v[188:189], 1, s[26:27]
	global_load_dwordx4 v[132:135], v[132:133], off
	s_waitcnt vmcnt(11)
	ds_write_b128 v183, v[148:151]
	v_add_u32_e32 v188, s5, v176
	v_add_u32_e32 v188, 0x40, v188
	v_lshl_add_u64 v[148:149], v[188:189], 1, s[72:73]
	global_load_dwordx4 v[148:151], v[148:149], off
	s_waitcnt vmcnt(11)
	ds_write_b128 v183, v[144:147] offset:4608
	v_add_u32_e32 v188, s5, v176
	v_add_u32_e32 v188, 0x20040, v188
	v_lshl_add_u64 v[144:145], v[188:189], 1, s[72:73]
	global_load_dwordx4 v[144:147], v[144:145], off
	s_waitcnt vmcnt(11)
	ds_write_b128 v183, v[156:159] offset:9216
	v_add_u32_e32 v188, s5, v176
	v_add_u32_e32 v188, 0x40040, v188
	v_lshl_add_u64 v[156:157], v[188:189], 1, s[72:73]
	global_load_dwordx4 v[156:159], v[156:157], off
	s_waitcnt vmcnt(11)
	ds_write_b128 v183, v[152:155] offset:13824
	v_add_u32_e32 v188, s5, v176
	v_add_u32_e32 v188, 0x60040, v188
	v_lshl_add_u64 v[152:153], v[188:189], 1, s[72:73]
	global_load_dwordx4 v[152:155], v[152:153], off
	s_waitcnt vmcnt(11)
	ds_write_b128 v183, v[164:167] offset:18432
	v_add_u32_e32 v188, s5, v176
	v_add_u32_e32 v188, 0x80040, v188
	v_lshl_add_u64 v[164:165], v[188:189], 1, s[72:73]
	global_load_dwordx4 v[164:167], v[164:165], off
	s_waitcnt vmcnt(11)
	ds_write_b128 v183, v[160:163] offset:23040
	v_add_u32_e32 v188, s5, v176
	v_add_u32_e32 v188, 0xa0040, v188
	v_lshl_add_u64 v[160:161], v[188:189], 1, s[72:73]
	global_load_dwordx4 v[160:163], v[160:161], off
	s_waitcnt vmcnt(11)
	ds_write_b128 v183, v[168:171] offset:27648
	v_add_u32_e32 v188, s5, v176
	v_add_u32_e32 v188, 0xc0040, v188
	v_lshl_add_u64 v[168:169], v[188:189], 1, s[72:73]
	global_load_dwordx4 v[168:171], v[168:169], off
	s_waitcnt vmcnt(11)
	ds_write_b128 v183, v[172:175] offset:32256
	v_add_u32_e32 v188, s5, v176
	v_add_u32_e32 v188, 0xe0040, v188
	v_lshl_add_u64 v[172:173], v[188:189], 1, s[72:73]
	global_load_dwordx4 v[172:175], v[172:173], off
	s_waitcnt lgkmcnt(0)
	s_barrier
	ds_read_b128 v[202:205], v182 offset:36864
	ds_read_b128 v[206:209], v182 offset:41472
	ds_read_b128 v[218:221], v179
	ds_read_b128 v[232:235], v179 offset:4608
	s_waitcnt lgkmcnt(1)
	v_mfma_f32_32x32x16_bf16 v[112:127], v[218:221], v[202:205], v[112:127]
	v_mfma_f32_32x32x16_bf16 v[96:111], v[218:221], v[206:209], v[96:111]
	ds_read_b128 v[218:221], v179 offset:9216
	s_waitcnt lgkmcnt(1)
	v_mfma_f32_32x32x16_bf16 v[80:95], v[232:235], v[202:205], v[80:95]
	v_mfma_f32_32x32x16_bf16 v[64:79], v[232:235], v[206:209], v[64:79]
	ds_read_b128 v[232:235], v177
	ds_read_b128 v[210:213], v182 offset:36896
	ds_read_b128 v[214:217], v182 offset:41504
	s_waitcnt lgkmcnt(3)
	v_mfma_f32_32x32x16_bf16 v[48:63], v[218:221], v[202:205], v[48:63]
	v_mfma_f32_32x32x16_bf16 v[32:47], v[218:221], v[206:209], v[32:47]
	ds_read_b128 v[218:221], v179 offset:32
	s_waitcnt lgkmcnt(3)
	v_mfma_f32_32x32x16_bf16 v[16:31], v[232:235], v[202:205], v[16:31]
	v_mfma_f32_32x32x16_bf16 v[0:15], v[232:235], v[206:209], v[0:15]
	ds_read_b128 v[232:235], v179 offset:4640
	s_waitcnt lgkmcnt(1)
	v_mfma_f32_32x32x16_bf16 v[112:127], v[218:221], v[210:213], v[112:127]
	v_mfma_f32_32x32x16_bf16 v[96:111], v[218:221], v[214:217], v[96:111]
	ds_read_b128 v[218:221], v179 offset:9248
	s_waitcnt lgkmcnt(1)
	v_mfma_f32_32x32x16_bf16 v[80:95], v[232:235], v[210:213], v[80:95]
	v_mfma_f32_32x32x16_bf16 v[64:79], v[232:235], v[214:217], v[64:79]
	ds_read_b128 v[232:235], v177 offset:32
	ds_read_b128 v[202:205], v182 offset:36928
	ds_read_b128 v[206:209], v182 offset:41536
	s_waitcnt lgkmcnt(3)
	v_mfma_f32_32x32x16_bf16 v[48:63], v[218:221], v[210:213], v[48:63]
	v_mfma_f32_32x32x16_bf16 v[32:47], v[218:221], v[214:217], v[32:47]
	ds_read_b128 v[218:221], v179 offset:64
	s_waitcnt lgkmcnt(3)
	v_mfma_f32_32x32x16_bf16 v[16:31], v[232:235], v[210:213], v[16:31]
	v_mfma_f32_32x32x16_bf16 v[0:15], v[232:235], v[214:217], v[0:15]
	ds_read_b128 v[232:235], v179 offset:4672
	s_waitcnt lgkmcnt(1)
	v_mfma_f32_32x32x16_bf16 v[112:127], v[218:221], v[202:205], v[112:127]
	v_mfma_f32_32x32x16_bf16 v[96:111], v[218:221], v[206:209], v[96:111]
	ds_read_b128 v[218:221], v179 offset:9280
	s_waitcnt lgkmcnt(1)
	v_mfma_f32_32x32x16_bf16 v[80:95], v[232:235], v[202:205], v[80:95]
	v_mfma_f32_32x32x16_bf16 v[64:79], v[232:235], v[206:209], v[64:79]
	ds_read_b128 v[232:235], v177 offset:64
	ds_read_b128 v[210:213], v182 offset:36960
	ds_read_b128 v[214:217], v182 offset:41568
	s_waitcnt lgkmcnt(3)
	v_mfma_f32_32x32x16_bf16 v[48:63], v[218:221], v[202:205], v[48:63]
	v_mfma_f32_32x32x16_bf16 v[32:47], v[218:221], v[206:209], v[32:47]
	ds_read_b128 v[218:221], v179 offset:96
	s_waitcnt lgkmcnt(3)
	v_mfma_f32_32x32x16_bf16 v[16:31], v[232:235], v[202:205], v[16:31]
	v_mfma_f32_32x32x16_bf16 v[0:15], v[232:235], v[206:209], v[0:15]
	ds_read_b128 v[232:235], v179 offset:4704
	s_waitcnt lgkmcnt(1)
	v_mfma_f32_32x32x16_bf16 v[112:127], v[218:221], v[210:213], v[112:127]
	v_mfma_f32_32x32x16_bf16 v[96:111], v[218:221], v[214:217], v[96:111]
	ds_read_b128 v[218:221], v179 offset:9312
	s_waitcnt lgkmcnt(1)
	v_mfma_f32_32x32x16_bf16 v[80:95], v[232:235], v[210:213], v[80:95]
	v_mfma_f32_32x32x16_bf16 v[64:79], v[232:235], v[214:217], v[64:79]
	ds_read_b128 v[232:235], v177 offset:96
	s_waitcnt lgkmcnt(1)
	v_mfma_f32_32x32x16_bf16 v[48:63], v[218:221], v[210:213], v[48:63]
	v_mfma_f32_32x32x16_bf16 v[32:47], v[218:221], v[214:217], v[32:47]
	s_waitcnt lgkmcnt(0)
	v_mfma_f32_32x32x16_bf16 v[16:31], v[232:235], v[210:213], v[16:31]
	v_mfma_f32_32x32x16_bf16 v[0:15], v[232:235], v[214:217], v[0:15]
	s_add_i32 s5, s5, 64
	s_cmpk_lg_i32 s5, 0xfc0
	s_cbranch_scc1 .LBB0_96
; template <bool NORM, bool DEEP, int MTW, int KSEG, class HOOK>
; DI void gemm_core_h(const bfu* __restrict__ A, int lda, const bfu* __restrict__ Bt, int ldb, int K, int m0, int n0,
;                     f32x16 (&acc)[MTW][2], char* smem, HOOK hook) {
;     ...
;   if (DEEP) {
;     for (int kt = 0; kt < nk; kt += 2) {
;       GEMM_STEP(ra0, rb0, kt, 2)
;       GEMM_STEP(ra1, rb1, kt + 1, 2)
;     }
;   } else {
;     for (int kt = 0; kt < nk; ++kt) {
;       GEMM_STEP(ra0, rb0, kt, 1)
;       if (KSEG > 0) { if (((kt + 1) % (KSEG > 0 ? KSEG : 1)) == 0) hook((kt + 1) / (KSEG > 0 ? KSEG : 1) - 1); }
;     }
;   }
;     ...
;   if (NORM) {
; #pragma unroll
;     for (int j = 0; j < NA; ++j) {
;       float v = ssq[j];
;       v += __shfl_xor(v, 1); v += __shfl_xor(v, 2); v += __shfl_xor(v, 4);
;       if (lkc == 0) rstd_s[lrow + 32 * j] = rsqrtf(v / (float)K + EPS);
;     }
;   }
;   __syncthreads();
	s_waitcnt vmcnt(0)
	s_waitcnt lgkmcnt(0)
	s_barrier
	s_waitcnt vmcnt(11)
	ds_write_b128 v183, v[148:151]
	s_waitcnt vmcnt(10)
	ds_write_b128 v183, v[144:147] offset:4608
	s_waitcnt vmcnt(9)
	ds_write_b128 v183, v[156:159] offset:9216
	s_waitcnt vmcnt(8)
	ds_write_b128 v183, v[152:155] offset:13824
	s_waitcnt vmcnt(7)
	ds_write_b128 v183, v[164:167] offset:18432
	s_waitcnt vmcnt(6)
	ds_write_b128 v183, v[160:163] offset:23040
	s_waitcnt vmcnt(5)
	ds_write_b128 v183, v[168:171] offset:27648
	s_waitcnt vmcnt(4)
	ds_write_b128 v183, v[172:175] offset:32256
	s_waitcnt vmcnt(3)
	ds_write_b128 v183, v[140:143] offset:36864
	s_waitcnt vmcnt(2)
	ds_write_b128 v183, v[136:139] offset:41472
	s_waitcnt vmcnt(1)
	ds_write_b128 v183, v[128:131] offset:46080
	s_waitcnt vmcnt(0)
	ds_write_b128 v183, v[132:135] offset:50688
	s_waitcnt lgkmcnt(0)
	s_barrier
	ds_read_b128 v[128:131], v182 offset:41472
	ds_read_b128 v[132:135], v182 offset:36864
	ds_read_b128 v[136:139], v182 offset:36896
	ds_read_b128 v[140:143], v179
	ds_read_b128 v[144:147], v179 offset:32
	s_waitcnt lgkmcnt(1)
	v_mfma_f32_32x32x16_bf16 v[112:127], v[140:143], v[132:135], v[112:127]
	v_readlane_b32 s16, v253, 32
	v_readlane_b32 s28, v253, 44
	v_readlane_b32 s29, v253, 45
	v_readlane_b32 s17, v253, 33
	v_readlane_b32 s18, v253, 34
	v_readlane_b32 s19, v253, 35
	v_readlane_b32 s20, v253, 36
	v_mfma_f32_32x32x16_bf16 v[96:111], v[140:143], v[128:131], v[96:111]
	ds_read_b128 v[140:143], v179 offset:4608
	v_readlane_b32 s21, v253, 37
	v_readlane_b32 s22, v253, 38
	v_readlane_b32 s23, v253, 39
	v_readlane_b32 s24, v253, 40
	v_readlane_b32 s25, v253, 41
	v_readlane_b32 s26, v253, 42
	s_waitcnt lgkmcnt(0)
	v_mfma_f32_32x32x16_bf16 v[80:95], v[140:143], v[132:135], v[80:95]
	v_readlane_b32 s27, v253, 43
	v_readlane_b32 s30, v253, 46
	v_readlane_b32 s31, v253, 47
	v_mfma_f32_32x32x16_bf16 v[64:79], v[140:143], v[128:131], v[64:79]
	ds_read_b128 v[140:143], v179 offset:9216
	s_waitcnt lgkmcnt(0)
	v_mfma_f32_32x32x16_bf16 v[48:63], v[140:143], v[132:135], v[48:63]
	v_mfma_f32_32x32x16_bf16 v[32:47], v[140:143], v[128:131], v[32:47]
	ds_read_b128 v[140:143], v177
	ds_read_b128 v[148:151], v177 offset:32
	s_waitcnt lgkmcnt(1)
	v_mfma_f32_32x32x16_bf16 v[16:31], v[140:143], v[132:135], v[16:31]
	ds_read_b128 v[132:135], v179 offset:4640
	v_mfma_f32_32x32x16_bf16 v[0:15], v[140:143], v[128:131], v[0:15]
	ds_read_b128 v[128:131], v182 offset:41504
	s_waitcnt lgkmcnt(1)
	v_mfma_f32_32x32x16_bf16 v[80:95], v[132:135], v[136:139], v[80:95]
	s_waitcnt lgkmcnt(0)
	v_mfma_f32_32x32x16_bf16 v[64:79], v[132:135], v[128:131], v[64:79]
	ds_read_b128 v[132:135], v179 offset:9248
	v_mfma_f32_32x32x16_bf16 v[112:127], v[144:147], v[136:139], v[112:127]
	v_mfma_f32_32x32x16_bf16 v[96:111], v[144:147], v[128:131], v[96:111]
	s_waitcnt lgkmcnt(0)
	v_mfma_f32_32x32x16_bf16 v[48:63], v[132:135], v[136:139], v[48:63]
	v_mfma_f32_32x32x16_bf16 v[32:47], v[132:135], v[128:131], v[32:47]
	v_mfma_f32_32x32x16_bf16 v[16:31], v[148:151], v[136:139], v[16:31]
	v_mfma_f32_32x32x16_bf16 v[0:15], v[148:151], v[128:131], v[0:15]
	ds_read_b128 v[128:131], v182 offset:36928
	ds_read_b128 v[132:135], v182 offset:41536
	ds_read_b128 v[136:139], v179 offset:64
	s_waitcnt lgkmcnt(0)
	v_mfma_f32_32x32x16_bf16 v[112:127], v[136:139], v[128:131], v[112:127]
	v_mfma_f32_32x32x16_bf16 v[96:111], v[136:139], v[132:135], v[96:111]
	ds_read_b128 v[136:139], v179 offset:4672
	s_waitcnt lgkmcnt(0)
	v_mfma_f32_32x32x16_bf16 v[80:95], v[136:139], v[128:131], v[80:95]
	v_mfma_f32_32x32x16_bf16 v[64:79], v[136:139], v[132:135], v[64:79]
	ds_read_b128 v[136:139], v179 offset:9280
	s_waitcnt lgkmcnt(0)
	v_mfma_f32_32x32x16_bf16 v[48:63], v[136:139], v[128:131], v[48:63]
	v_mfma_f32_32x32x16_bf16 v[32:47], v[136:139], v[132:135], v[32:47]
	ds_read_b128 v[136:139], v177 offset:64
	s_waitcnt lgkmcnt(0)
	v_mfma_f32_32x32x16_bf16 v[16:31], v[136:139], v[128:131], v[16:31]
	v_mfma_f32_32x32x16_bf16 v[0:15], v[136:139], v[132:135], v[0:15]
	ds_read_b128 v[128:131], v182 offset:36960
	ds_read_b128 v[132:135], v182 offset:41568
	ds_read_b128 v[136:139], v179 offset:96
	s_waitcnt lgkmcnt(0)
	v_mfma_f32_32x32x16_bf16 v[112:127], v[136:139], v[128:131], v[112:127]
	v_mfma_f32_32x32x16_bf16 v[96:111], v[136:139], v[132:135], v[96:111]
	ds_read_b128 v[136:139], v179 offset:4704
	s_waitcnt lgkmcnt(0)
	v_mfma_f32_32x32x16_bf16 v[80:95], v[136:139], v[128:131], v[80:95]
	v_mfma_f32_32x32x16_bf16 v[64:79], v[136:139], v[132:135], v[64:79]
	ds_read_b128 v[136:139], v179 offset:9312
	s_waitcnt lgkmcnt(0)
	v_mfma_f32_32x32x16_bf16 v[48:63], v[136:139], v[128:131], v[48:63]
	v_mfma_f32_32x32x16_bf16 v[32:47], v[136:139], v[132:135], v[32:47]
	ds_read_b128 v[136:139], v177 offset:96
	s_waitcnt lgkmcnt(0)
	s_barrier
; DI void phase_resid(const Params& p, const bfu* A, int lda, const bfu* Bt, int K, char* smem) {
;     ...
;     EPI_BEGINM(acc, 4)
;       float* xp = p.out + (size_t)row * 1024 + col;
;       float nv = *xp + v; *xp = nv; p.xb[(size_t)row * 1024 + col] = f2bf(nv);
;     EPI_END
	v_mfma_f32_32x32x16_bf16 v[16:31], v[136:139], v[128:131], v[16:31]
	v_mfma_f32_32x32x16_bf16 v[0:15], v[136:139], v[132:135], v[0:15]
	v_add_u32_e32 v176, s3, v180
	v_or_b32_e32 v177, s4, v181
	v_lshlrev_b32_e32 v176, 12, v176
	v_lshl_add_u32 v176, v177, 2, v176
	v_lshrrev_b32_e32 v177, 1, v176
	v_readlane_b32 s4, v254, 38
	v_readlane_b32 s5, v254, 39
	global_load_dword v128, v176, s[28:29] nt
	global_load_dword v129, v176, s[28:29] offset:128 nt
	v_add_u32_e32 v178, 0x1000, v176
	global_load_dword v130, v178, s[28:29] nt
	global_load_dword v131, v178, s[28:29] offset:128 nt
	v_add_u32_e32 v178, 0x2000, v176
	global_load_dword v132, v178, s[28:29] nt
	global_load_dword v133, v178, s[28:29] offset:128 nt
	v_add_u32_e32 v178, 0x3000, v176
	global_load_dword v134, v178, s[28:29] nt
	global_load_dword v135, v178, s[28:29] offset:128 nt
	v_add_u32_e32 v178, 0x8000, v176
	global_load_dword v136, v178, s[28:29] nt
	global_load_dword v137, v178, s[28:29] offset:128 nt
	v_add_u32_e32 v178, 0x9000, v176
	global_load_dword v138, v178, s[28:29] nt
	global_load_dword v139, v178, s[28:29] offset:128 nt
	v_add_u32_e32 v178, 0xa000, v176
	global_load_dword v140, v178, s[28:29] nt
	global_load_dword v141, v178, s[28:29] offset:128 nt
	v_add_u32_e32 v178, 0xb000, v176
	global_load_dword v142, v178, s[28:29] nt
	global_load_dword v143, v178, s[28:29] offset:128 nt
	v_add_u32_e32 v178, 0x10000, v176
	global_load_dword v144, v178, s[28:29] nt
	global_load_dword v145, v178, s[28:29] offset:128 nt
	v_add_u32_e32 v178, 0x11000, v176
	global_load_dword v146, v178, s[28:29] nt
	global_load_dword v147, v178, s[28:29] offset:128 nt
	v_add_u32_e32 v178, 0x12000, v176
	global_load_dword v148, v178, s[28:29] nt
	global_load_dword v149, v178, s[28:29] offset:128 nt
	v_add_u32_e32 v178, 0x13000, v176
	global_load_dword v150, v178, s[28:29] nt
	global_load_dword v151, v178, s[28:29] offset:128 nt
	v_add_u32_e32 v178, 0x18000, v176
	global_load_dword v152, v178, s[28:29] nt
	global_load_dword v153, v178, s[28:29] offset:128 nt
	v_add_u32_e32 v178, 0x19000, v176
	global_load_dword v154, v178, s[28:29] nt
	global_load_dword v155, v178, s[28:29] offset:128 nt
	v_add_u32_e32 v178, 0x1a000, v176
	global_load_dword v156, v178, s[28:29] nt
	global_load_dword v157, v178, s[28:29] offset:128 nt
	v_add_u32_e32 v178, 0x1b000, v176
	global_load_dword v158, v178, s[28:29] nt
	global_load_dword v159, v178, s[28:29] offset:128 nt
	v_add_u32_e32 v178, 0x20000, v176
	global_load_dword v160, v178, s[28:29] nt
	global_load_dword v161, v178, s[28:29] offset:128 nt
	v_add_u32_e32 v178, 0x21000, v176
	global_load_dword v162, v178, s[28:29] nt
	global_load_dword v163, v178, s[28:29] offset:128 nt
	v_add_u32_e32 v178, 0x22000, v176
	global_load_dword v164, v178, s[28:29] nt
	global_load_dword v165, v178, s[28:29] offset:128 nt
	v_add_u32_e32 v178, 0x23000, v176
	global_load_dword v166, v178, s[28:29] nt
	global_load_dword v167, v178, s[28:29] offset:128 nt
	v_add_u32_e32 v178, 0x28000, v176
	global_load_dword v168, v178, s[28:29] nt
	global_load_dword v169, v178, s[28:29] offset:128 nt
	v_add_u32_e32 v178, 0x29000, v176
	global_load_dword v170, v178, s[28:29] nt
	global_load_dword v171, v178, s[28:29] offset:128 nt
	v_add_u32_e32 v178, 0x2a000, v176
	global_load_dword v172, v178, s[28:29] nt
	global_load_dword v173, v178, s[28:29] offset:128 nt
	v_add_u32_e32 v178, 0x2b000, v176
	global_load_dword v174, v178, s[28:29] nt
	global_load_dword v175, v178, s[28:29] offset:128 nt
	v_add_u32_e32 v178, 0x30000, v176
	global_load_dword v184, v178, s[28:29] nt
	global_load_dword v185, v178, s[28:29] offset:128 nt
	v_add_u32_e32 v178, 0x31000, v176
	global_load_dword v186, v178, s[28:29] nt
	global_load_dword v187, v178, s[28:29] offset:128 nt
	v_add_u32_e32 v178, 0x32000, v176
	global_load_dword v190, v178, s[28:29] nt
	global_load_dword v191, v178, s[28:29] offset:128 nt
	v_add_u32_e32 v178, 0x33000, v176
	global_load_dword v192, v178, s[28:29] nt
	global_load_dword v193, v178, s[28:29] offset:128 nt
	v_add_u32_e32 v178, 0x38000, v176
	global_load_dword v194, v178, s[28:29] nt
	global_load_dword v195, v178, s[28:29] offset:128 nt
	v_add_u32_e32 v178, 0x39000, v176
	global_load_dword v196, v178, s[28:29] nt
	global_load_dword v197, v178, s[28:29] offset:128 nt
	v_add_u32_e32 v178, 0x3a000, v176
	global_load_dword v198, v178, s[28:29] nt
	global_load_dword v199, v178, s[28:29] offset:128 nt
	v_add_u32_e32 v178, 0x3b000, v176
	global_load_dword v200, v178, s[28:29] nt
	global_load_dword v201, v178, s[28:29] offset:128 nt
	s_waitcnt vmcnt(32)
; DI void phase_resid(const Params& p, const bfu* A, int lda, const bfu* Bt, int K, char* smem) {
;     ...
;     EPI_BEGINM(acc, 4)
;       float* xp = p.out + (size_t)row * 1024 + col;
;       float nv = *xp + v; *xp = nv; p.xb[(size_t)row * 1024 + col] = f2bf(nv);
;     EPI_END
	v_add_f32_e32 v112, v112, v128
	global_store_dword v176, v112, s[28:29]
	v_cvt_pk_bf16_f32 v128, v112, v112
	global_store_short v177, v128, s[36:37]
	v_add_f32_e32 v96, v96, v129
	global_store_dword v176, v96, s[28:29] offset:128
	v_cvt_pk_bf16_f32 v129, v96, v96
	global_store_short v177, v129, s[36:37] offset:64
	v_add_u32_e32 v178, 0x1000, v176
	v_add_u32_e32 v179, 0x800, v177
	v_add_f32_e32 v113, v113, v130
	global_store_dword v178, v113, s[28:29]
	v_cvt_pk_bf16_f32 v130, v113, v113
	global_store_short v179, v130, s[36:37]
	v_add_f32_e32 v97, v97, v131
	global_store_dword v178, v97, s[28:29] offset:128
	v_cvt_pk_bf16_f32 v131, v97, v97
	global_store_short v179, v131, s[36:37] offset:64
	v_add_u32_e32 v178, 0x2000, v176
	v_add_u32_e32 v179, 0x1000, v177
	v_add_f32_e32 v114, v114, v132
	global_store_dword v178, v114, s[28:29]
	v_cvt_pk_bf16_f32 v132, v114, v114
	global_store_short v179, v132, s[36:37]
	v_add_f32_e32 v98, v98, v133
	global_store_dword v178, v98, s[28:29] offset:128
	v_cvt_pk_bf16_f32 v133, v98, v98
	global_store_short v179, v133, s[36:37] offset:64
	v_add_u32_e32 v178, 0x3000, v176
	v_add_u32_e32 v179, 0x1800, v177
	v_add_f32_e32 v115, v115, v134
	global_store_dword v178, v115, s[28:29]
	v_cvt_pk_bf16_f32 v134, v115, v115
	global_store_short v179, v134, s[36:37]
	v_add_f32_e32 v99, v99, v135
	global_store_dword v178, v99, s[28:29] offset:128
	v_cvt_pk_bf16_f32 v135, v99, v99
	global_store_short v179, v135, s[36:37] offset:64
	v_add_u32_e32 v178, 0x8000, v176
	v_add_u32_e32 v179, 0x4000, v177
	v_add_f32_e32 v116, v116, v136
	global_store_dword v178, v116, s[28:29]
	v_cvt_pk_bf16_f32 v136, v116, v116
	global_store_short v179, v136, s[36:37]
	v_add_f32_e32 v100, v100, v137
	global_store_dword v178, v100, s[28:29] offset:128
	v_cvt_pk_bf16_f32 v137, v100, v100
	global_store_short v179, v137, s[36:37] offset:64
	v_add_u32_e32 v178, 0x9000, v176
	v_add_u32_e32 v179, 0x4800, v177
	v_add_f32_e32 v117, v117, v138
	global_store_dword v178, v117, s[28:29]
	v_cvt_pk_bf16_f32 v138, v117, v117
	global_store_short v179, v138, s[36:37]
	v_add_f32_e32 v101, v101, v139
	global_store_dword v178, v101, s[28:29] offset:128
	v_cvt_pk_bf16_f32 v139, v101, v101
	global_store_short v179, v139, s[36:37] offset:64
	v_add_u32_e32 v178, 0xa000, v176
	v_add_u32_e32 v179, 0x5000, v177
	v_add_f32_e32 v118, v118, v140
	global_store_dword v178, v118, s[28:29]
	v_cvt_pk_bf16_f32 v140, v118, v118
	global_store_short v179, v140, s[36:37]
	v_add_f32_e32 v102, v102, v141
	global_store_dword v178, v102, s[28:29] offset:128
	v_cvt_pk_bf16_f32 v141, v102, v102
	global_store_short v179, v141, s[36:37] offset:64
	v_add_u32_e32 v178, 0xb000, v176
	v_add_u32_e32 v179, 0x5800, v177
	v_add_f32_e32 v119, v119, v142
	global_store_dword v178, v119, s[28:29]
	v_cvt_pk_bf16_f32 v142, v119, v119
	global_store_short v179, v142, s[36:37]
	v_add_f32_e32 v103, v103, v143
	global_store_dword v178, v103, s[28:29] offset:128
	v_cvt_pk_bf16_f32 v143, v103, v103
	global_store_short v179, v143, s[36:37] offset:64
	v_add_u32_e32 v178, 0x10000, v176
	v_add_u32_e32 v179, 0x8000, v177
	v_add_f32_e32 v120, v120, v144
	global_store_dword v178, v120, s[28:29]
	v_cvt_pk_bf16_f32 v144, v120, v120
	global_store_short v179, v144, s[36:37]
	v_add_f32_e32 v104, v104, v145
	global_store_dword v178, v104, s[28:29] offset:128
	v_cvt_pk_bf16_f32 v145, v104, v104
	global_store_short v179, v145, s[36:37] offset:64
	v_add_u32_e32 v178, 0x11000, v176
	v_add_u32_e32 v179, 0x8800, v177
	v_add_f32_e32 v121, v121, v146
	global_store_dword v178, v121, s[28:29]
	v_cvt_pk_bf16_f32 v146, v121, v121
	global_store_short v179, v146, s[36:37]
	v_add_f32_e32 v105, v105, v147
	global_store_dword v178, v105, s[28:29] offset:128
	v_cvt_pk_bf16_f32 v147, v105, v105
	global_store_short v179, v147, s[36:37] offset:64
	v_add_u32_e32 v178, 0x12000, v176
	v_add_u32_e32 v179, 0x9000, v177
	v_add_f32_e32 v122, v122, v148
	global_store_dword v178, v122, s[28:29]
	v_cvt_pk_bf16_f32 v148, v122, v122
	global_store_short v179, v148, s[36:37]
	v_add_f32_e32 v106, v106, v149
	global_store_dword v178, v106, s[28:29] offset:128
	v_cvt_pk_bf16_f32 v149, v106, v106
	global_store_short v179, v149, s[36:37] offset:64
	v_add_u32_e32 v178, 0x13000, v176
	v_add_u32_e32 v179, 0x9800, v177
	v_add_f32_e32 v123, v123, v150
	global_store_dword v178, v123, s[28:29]
	v_cvt_pk_bf16_f32 v150, v123, v123
	global_store_short v179, v150, s[36:37]
	v_add_f32_e32 v107, v107, v151
	global_store_dword v178, v107, s[28:29] offset:128
	v_cvt_pk_bf16_f32 v151, v107, v107
	global_store_short v179, v151, s[36:37] offset:64
	v_add_u32_e32 v178, 0x18000, v176
	v_add_u32_e32 v179, 0xc000, v177
	v_add_f32_e32 v124, v124, v152
	global_store_dword v178, v124, s[28:29]
	v_cvt_pk_bf16_f32 v152, v124, v124
	global_store_short v179, v152, s[36:37]
	v_add_f32_e32 v108, v108, v153
	global_store_dword v178, v108, s[28:29] offset:128
	v_cvt_pk_bf16_f32 v153, v108, v108
	global_store_short v179, v153, s[36:37] offset:64
	v_add_u32_e32 v178, 0x19000, v176
	v_add_u32_e32 v179, 0xc800, v177
	v_add_f32_e32 v125, v125, v154
	global_store_dword v178, v125, s[28:29]
	v_cvt_pk_bf16_f32 v154, v125, v125
	global_store_short v179, v154, s[36:37]
	v_add_f32_e32 v109, v109, v155
	global_store_dword v178, v109, s[28:29] offset:128
	v_cvt_pk_bf16_f32 v155, v109, v109
	global_store_short v179, v155, s[36:37] offset:64
	v_add_u32_e32 v178, 0x1a000, v176
	v_add_u32_e32 v179, 0xd000, v177
	v_add_f32_e32 v126, v126, v156
	global_store_dword v178, v126, s[28:29]
	v_cvt_pk_bf16_f32 v156, v126, v126
	global_store_short v179, v156, s[36:37]
	v_add_f32_e32 v110, v110, v157
; DI void phase_resid(const Params& p, const bfu* A, int lda, const bfu* Bt, int K, char* smem) {
;     ...
;     EPI_BEGINM(acc, 4)
;       float* xp = p.out + (size_t)row * 1024 + col;
;       float nv = *xp + v; *xp = nv; p.xb[(size_t)row * 1024 + col] = f2bf(nv);
;     EPI_END
	global_store_dword v178, v110, s[28:29] offset:128
	v_cvt_pk_bf16_f32 v157, v110, v110
	global_store_short v179, v157, s[36:37] offset:64
	v_add_u32_e32 v178, 0x1b000, v176
	v_add_u32_e32 v179, 0xd800, v177
	v_add_f32_e32 v127, v127, v158
	global_store_dword v178, v127, s[28:29]
	v_cvt_pk_bf16_f32 v158, v127, v127
	global_store_short v179, v158, s[36:37]
	v_add_f32_e32 v111, v111, v159
	global_store_dword v178, v111, s[28:29] offset:128
	v_cvt_pk_bf16_f32 v159, v111, v111
	global_store_short v179, v159, s[36:37] offset:64
	v_add_u32_e32 v178, 0x40000, v176
	global_load_dword v128, v178, s[28:29] nt
	global_load_dword v129, v178, s[28:29] offset:128 nt
	v_add_u32_e32 v178, 0x41000, v176
	global_load_dword v130, v178, s[28:29] nt
	global_load_dword v131, v178, s[28:29] offset:128 nt
	v_add_u32_e32 v178, 0x42000, v176
	global_load_dword v132, v178, s[28:29] nt
	global_load_dword v133, v178, s[28:29] offset:128 nt
	v_add_u32_e32 v178, 0x43000, v176
	global_load_dword v134, v178, s[28:29] nt
	global_load_dword v135, v178, s[28:29] offset:128 nt
	v_add_u32_e32 v178, 0x48000, v176
	global_load_dword v136, v178, s[28:29] nt
	global_load_dword v137, v178, s[28:29] offset:128 nt
	v_add_u32_e32 v178, 0x49000, v176
	global_load_dword v138, v178, s[28:29] nt
	global_load_dword v139, v178, s[28:29] offset:128 nt
	v_add_u32_e32 v178, 0x4a000, v176
	global_load_dword v140, v178, s[28:29] nt
	global_load_dword v141, v178, s[28:29] offset:128 nt
	v_add_u32_e32 v178, 0x4b000, v176
	global_load_dword v142, v178, s[28:29] nt
	global_load_dword v143, v178, s[28:29] offset:128 nt
	v_add_u32_e32 v178, 0x50000, v176
	global_load_dword v144, v178, s[28:29] nt
	global_load_dword v145, v178, s[28:29] offset:128 nt
	v_add_u32_e32 v178, 0x51000, v176
	global_load_dword v146, v178, s[28:29] nt
	global_load_dword v147, v178, s[28:29] offset:128 nt
	v_add_u32_e32 v178, 0x52000, v176
	global_load_dword v148, v178, s[28:29] nt
	global_load_dword v149, v178, s[28:29] offset:128 nt
	v_add_u32_e32 v178, 0x53000, v176
	global_load_dword v150, v178, s[28:29] nt
	global_load_dword v151, v178, s[28:29] offset:128 nt
	v_add_u32_e32 v178, 0x58000, v176
	global_load_dword v152, v178, s[28:29] nt
	global_load_dword v153, v178, s[28:29] offset:128 nt
	v_add_u32_e32 v178, 0x59000, v176
	global_load_dword v154, v178, s[28:29] nt
	global_load_dword v155, v178, s[28:29] offset:128 nt
	v_add_u32_e32 v178, 0x5a000, v176
	global_load_dword v156, v178, s[28:29] nt
	global_load_dword v157, v178, s[28:29] offset:128 nt
	v_add_u32_e32 v178, 0x5b000, v176
	global_load_dword v158, v178, s[28:29] nt
	global_load_dword v159, v178, s[28:29] offset:128 nt
	s_waitcnt vmcnt(63)
	v_add_u32_e32 v178, 0x20000, v176
	v_add_u32_e32 v179, 0x10000, v177
	v_add_f32_e32 v80, v80, v160
	global_store_dword v178, v80, s[28:29]
	v_cvt_pk_bf16_f32 v160, v80, v80
	global_store_short v179, v160, s[36:37]
	v_add_f32_e32 v64, v64, v161
	global_store_dword v178, v64, s[28:29] offset:128
	v_cvt_pk_bf16_f32 v161, v64, v64
	global_store_short v179, v161, s[36:37] offset:64
	v_add_u32_e32 v178, 0x21000, v176
	v_add_u32_e32 v179, 0x10800, v177
	v_add_f32_e32 v81, v81, v162
	global_store_dword v178, v81, s[28:29]
	v_cvt_pk_bf16_f32 v162, v81, v81
	global_store_short v179, v162, s[36:37]
	v_add_f32_e32 v65, v65, v163
	global_store_dword v178, v65, s[28:29] offset:128
	v_cvt_pk_bf16_f32 v163, v65, v65
	global_store_short v179, v163, s[36:37] offset:64
	v_add_u32_e32 v178, 0x22000, v176
	v_add_u32_e32 v179, 0x11000, v177
	v_add_f32_e32 v82, v82, v164
	global_store_dword v178, v82, s[28:29]
	v_cvt_pk_bf16_f32 v164, v82, v82
	global_store_short v179, v164, s[36:37]
	v_add_f32_e32 v66, v66, v165
	global_store_dword v178, v66, s[28:29] offset:128
	v_cvt_pk_bf16_f32 v165, v66, v66
	global_store_short v179, v165, s[36:37] offset:64
	v_add_u32_e32 v178, 0x23000, v176
	v_add_u32_e32 v179, 0x11800, v177
	v_add_f32_e32 v83, v83, v166
	global_store_dword v178, v83, s[28:29]
	v_cvt_pk_bf16_f32 v166, v83, v83
	global_store_short v179, v166, s[36:37]
	v_add_f32_e32 v67, v67, v167
	global_store_dword v178, v67, s[28:29] offset:128
	v_cvt_pk_bf16_f32 v167, v67, v67
	global_store_short v179, v167, s[36:37] offset:64
	v_add_u32_e32 v178, 0x28000, v176
	v_add_u32_e32 v179, 0x14000, v177
	v_add_f32_e32 v84, v84, v168
	global_store_dword v178, v84, s[28:29]
	v_cvt_pk_bf16_f32 v168, v84, v84
	global_store_short v179, v168, s[36:37]
	v_add_f32_e32 v68, v68, v169
	global_store_dword v178, v68, s[28:29] offset:128
	v_cvt_pk_bf16_f32 v169, v68, v68
	global_store_short v179, v169, s[36:37] offset:64
	v_add_u32_e32 v178, 0x29000, v176
	v_add_u32_e32 v179, 0x14800, v177
	v_add_f32_e32 v85, v85, v170
	global_store_dword v178, v85, s[28:29]
	v_cvt_pk_bf16_f32 v170, v85, v85
	global_store_short v179, v170, s[36:37]
	v_add_f32_e32 v69, v69, v171
	global_store_dword v178, v69, s[28:29] offset:128
	v_cvt_pk_bf16_f32 v171, v69, v69
	global_store_short v179, v171, s[36:37] offset:64
	v_add_u32_e32 v178, 0x2a000, v176
	v_add_u32_e32 v179, 0x15000, v177
	v_add_f32_e32 v86, v86, v172
	global_store_dword v178, v86, s[28:29]
	v_cvt_pk_bf16_f32 v172, v86, v86
	global_store_short v179, v172, s[36:37]
	v_add_f32_e32 v70, v70, v173
	global_store_dword v178, v70, s[28:29] offset:128
	v_cvt_pk_bf16_f32 v173, v70, v70
	global_store_short v179, v173, s[36:37] offset:64
	v_add_u32_e32 v178, 0x2b000, v176
	v_add_u32_e32 v179, 0x15800, v177
	v_add_f32_e32 v87, v87, v174
	global_store_dword v178, v87, s[28:29]
	v_cvt_pk_bf16_f32 v174, v87, v87
	global_store_short v179, v174, s[36:37]
	v_add_f32_e32 v71, v71, v175
	global_store_dword v178, v71, s[28:29] offset:128
; DI void phase_resid(const Params& p, const bfu* A, int lda, const bfu* Bt, int K, char* smem) {
;     ...
;     EPI_BEGINM(acc, 4)
;       float* xp = p.out + (size_t)row * 1024 + col;
;       float nv = *xp + v; *xp = nv; p.xb[(size_t)row * 1024 + col] = f2bf(nv);
;     EPI_END
	v_cvt_pk_bf16_f32 v175, v71, v71
	global_store_short v179, v175, s[36:37] offset:64
	v_add_u32_e32 v178, 0x30000, v176
	v_add_u32_e32 v179, 0x18000, v177
	v_add_f32_e32 v88, v88, v184
	global_store_dword v178, v88, s[28:29]
	v_cvt_pk_bf16_f32 v184, v88, v88
	global_store_short v179, v184, s[36:37]
	v_add_f32_e32 v72, v72, v185
	global_store_dword v178, v72, s[28:29] offset:128
	v_cvt_pk_bf16_f32 v185, v72, v72
	global_store_short v179, v185, s[36:37] offset:64
	v_add_u32_e32 v178, 0x31000, v176
	v_add_u32_e32 v179, 0x18800, v177
	v_add_f32_e32 v89, v89, v186
	global_store_dword v178, v89, s[28:29]
	v_cvt_pk_bf16_f32 v186, v89, v89
	global_store_short v179, v186, s[36:37]
	v_add_f32_e32 v73, v73, v187
	global_store_dword v178, v73, s[28:29] offset:128
	v_cvt_pk_bf16_f32 v187, v73, v73
	global_store_short v179, v187, s[36:37] offset:64
	v_add_u32_e32 v178, 0x32000, v176
	v_add_u32_e32 v179, 0x19000, v177
	v_add_f32_e32 v90, v90, v190
	global_store_dword v178, v90, s[28:29]
	v_cvt_pk_bf16_f32 v190, v90, v90
	global_store_short v179, v190, s[36:37]
	v_add_f32_e32 v74, v74, v191
	global_store_dword v178, v74, s[28:29] offset:128
	v_cvt_pk_bf16_f32 v191, v74, v74
	global_store_short v179, v191, s[36:37] offset:64
	v_add_u32_e32 v178, 0x33000, v176
	v_add_u32_e32 v179, 0x19800, v177
	v_add_f32_e32 v91, v91, v192
	global_store_dword v178, v91, s[28:29]
	v_cvt_pk_bf16_f32 v192, v91, v91
	global_store_short v179, v192, s[36:37]
	v_add_f32_e32 v75, v75, v193
	global_store_dword v178, v75, s[28:29] offset:128
	v_cvt_pk_bf16_f32 v193, v75, v75
	global_store_short v179, v193, s[36:37] offset:64
	v_add_u32_e32 v178, 0x38000, v176
	v_add_u32_e32 v179, 0x1c000, v177
	v_add_f32_e32 v92, v92, v194
	global_store_dword v178, v92, s[28:29]
	v_cvt_pk_bf16_f32 v194, v92, v92
	global_store_short v179, v194, s[36:37]
	v_add_f32_e32 v76, v76, v195
	global_store_dword v178, v76, s[28:29] offset:128
	v_cvt_pk_bf16_f32 v195, v76, v76
	global_store_short v179, v195, s[36:37] offset:64
	v_add_u32_e32 v178, 0x39000, v176
	v_add_u32_e32 v179, 0x1c800, v177
	v_add_f32_e32 v93, v93, v196
	global_store_dword v178, v93, s[28:29]
	v_cvt_pk_bf16_f32 v196, v93, v93
	global_store_short v179, v196, s[36:37]
	v_add_f32_e32 v77, v77, v197
	global_store_dword v178, v77, s[28:29] offset:128
	v_cvt_pk_bf16_f32 v197, v77, v77
	global_store_short v179, v197, s[36:37] offset:64
	v_add_u32_e32 v178, 0x3a000, v176
	v_add_u32_e32 v179, 0x1d000, v177
	v_add_f32_e32 v94, v94, v198
	global_store_dword v178, v94, s[28:29]
	v_cvt_pk_bf16_f32 v198, v94, v94
	global_store_short v179, v198, s[36:37]
	v_add_f32_e32 v78, v78, v199
	global_store_dword v178, v78, s[28:29] offset:128
	v_cvt_pk_bf16_f32 v199, v78, v78
	global_store_short v179, v199, s[36:37] offset:64
	v_add_u32_e32 v178, 0x3b000, v176
	v_add_u32_e32 v179, 0x1d800, v177
	v_add_f32_e32 v95, v95, v200
	global_store_dword v178, v95, s[28:29]
	v_cvt_pk_bf16_f32 v200, v95, v95
	global_store_short v179, v200, s[36:37]
	v_add_f32_e32 v79, v79, v201
	global_store_dword v178, v79, s[28:29] offset:128
	v_cvt_pk_bf16_f32 v201, v79, v79
	global_store_short v179, v201, s[36:37] offset:64
	v_add_u32_e32 v178, 0x60000, v176
	global_load_dword v160, v178, s[28:29] nt
	global_load_dword v161, v178, s[28:29] offset:128 nt
	v_add_u32_e32 v178, 0x61000, v176
	global_load_dword v162, v178, s[28:29] nt
	global_load_dword v163, v178, s[28:29] offset:128 nt
	v_add_u32_e32 v178, 0x62000, v176
	global_load_dword v164, v178, s[28:29] nt
	global_load_dword v165, v178, s[28:29] offset:128 nt
	v_add_u32_e32 v178, 0x63000, v176
	global_load_dword v166, v178, s[28:29] nt
	global_load_dword v167, v178, s[28:29] offset:128 nt
	v_add_u32_e32 v178, 0x68000, v176
	global_load_dword v168, v178, s[28:29] nt
	global_load_dword v169, v178, s[28:29] offset:128 nt
	v_add_u32_e32 v178, 0x69000, v176
	global_load_dword v170, v178, s[28:29] nt
	global_load_dword v171, v178, s[28:29] offset:128 nt
	v_add_u32_e32 v178, 0x6a000, v176
	global_load_dword v172, v178, s[28:29] nt
	global_load_dword v173, v178, s[28:29] offset:128 nt
	v_add_u32_e32 v178, 0x6b000, v176
	global_load_dword v174, v178, s[28:29] nt
	global_load_dword v175, v178, s[28:29] offset:128 nt
	v_add_u32_e32 v178, 0x70000, v176
	global_load_dword v184, v178, s[28:29] nt
	global_load_dword v185, v178, s[28:29] offset:128 nt
	v_add_u32_e32 v178, 0x71000, v176
	global_load_dword v186, v178, s[28:29] nt
	global_load_dword v187, v178, s[28:29] offset:128 nt
	v_add_u32_e32 v178, 0x72000, v176
	global_load_dword v190, v178, s[28:29] nt
	global_load_dword v191, v178, s[28:29] offset:128 nt
	v_add_u32_e32 v178, 0x73000, v176
	global_load_dword v192, v178, s[28:29] nt
	global_load_dword v193, v178, s[28:29] offset:128 nt
	v_add_u32_e32 v178, 0x78000, v176
	global_load_dword v194, v178, s[28:29] nt
	global_load_dword v195, v178, s[28:29] offset:128 nt
	v_add_u32_e32 v178, 0x79000, v176
	global_load_dword v196, v178, s[28:29] nt
	global_load_dword v197, v178, s[28:29] offset:128 nt
	v_add_u32_e32 v178, 0x7a000, v176
	global_load_dword v198, v178, s[28:29] nt
	global_load_dword v199, v178, s[28:29] offset:128 nt
	v_add_u32_e32 v178, 0x7b000, v176
	global_load_dword v200, v178, s[28:29] nt
	global_load_dword v201, v178, s[28:29] offset:128 nt
	s_waitcnt vmcnt(63)
; DI void phase_resid(const Params& p, const bfu* A, int lda, const bfu* Bt, int K, char* smem) {
;     ...
;     EPI_BEGINM(acc, 4)
;       float* xp = p.out + (size_t)row * 1024 + col;
;       float nv = *xp + v; *xp = nv; p.xb[(size_t)row * 1024 + col] = f2bf(nv);
;     EPI_END
	v_add_u32_e32 v178, 0x40000, v176
	v_add_u32_e32 v179, 0x20000, v177
	v_add_f32_e32 v48, v48, v128
	global_store_dword v178, v48, s[28:29]
	v_cvt_pk_bf16_f32 v128, v48, v48
	global_store_short v179, v128, s[36:37]
	v_add_f32_e32 v32, v32, v129
	global_store_dword v178, v32, s[28:29] offset:128
	v_cvt_pk_bf16_f32 v129, v32, v32
	global_store_short v179, v129, s[36:37] offset:64
	v_add_u32_e32 v178, 0x41000, v176
	v_add_u32_e32 v179, 0x20800, v177
	v_add_f32_e32 v49, v49, v130
	global_store_dword v178, v49, s[28:29]
	v_cvt_pk_bf16_f32 v130, v49, v49
	global_store_short v179, v130, s[36:37]
	v_add_f32_e32 v33, v33, v131
	global_store_dword v178, v33, s[28:29] offset:128
	v_cvt_pk_bf16_f32 v131, v33, v33
	global_store_short v179, v131, s[36:37] offset:64
	v_add_u32_e32 v178, 0x42000, v176
	v_add_u32_e32 v179, 0x21000, v177
	v_add_f32_e32 v50, v50, v132
	global_store_dword v178, v50, s[28:29]
	v_cvt_pk_bf16_f32 v132, v50, v50
	global_store_short v179, v132, s[36:37]
	v_add_f32_e32 v34, v34, v133
	global_store_dword v178, v34, s[28:29] offset:128
	v_cvt_pk_bf16_f32 v133, v34, v34
	global_store_short v179, v133, s[36:37] offset:64
	v_add_u32_e32 v178, 0x43000, v176
	v_add_u32_e32 v179, 0x21800, v177
	v_add_f32_e32 v51, v51, v134
	global_store_dword v178, v51, s[28:29]
	v_cvt_pk_bf16_f32 v134, v51, v51
	global_store_short v179, v134, s[36:37]
	v_add_f32_e32 v35, v35, v135
	global_store_dword v178, v35, s[28:29] offset:128
	v_cvt_pk_bf16_f32 v135, v35, v35
	global_store_short v179, v135, s[36:37] offset:64
	v_add_u32_e32 v178, 0x48000, v176
	v_add_u32_e32 v179, 0x24000, v177
	v_add_f32_e32 v52, v52, v136
	global_store_dword v178, v52, s[28:29]
	v_cvt_pk_bf16_f32 v136, v52, v52
	global_store_short v179, v136, s[36:37]
	v_add_f32_e32 v36, v36, v137
	global_store_dword v178, v36, s[28:29] offset:128
	v_cvt_pk_bf16_f32 v137, v36, v36
	global_store_short v179, v137, s[36:37] offset:64
	v_add_u32_e32 v178, 0x49000, v176
	v_add_u32_e32 v179, 0x24800, v177
	v_add_f32_e32 v53, v53, v138
	global_store_dword v178, v53, s[28:29]
	v_cvt_pk_bf16_f32 v138, v53, v53
	global_store_short v179, v138, s[36:37]
	v_add_f32_e32 v37, v37, v139
	global_store_dword v178, v37, s[28:29] offset:128
	v_cvt_pk_bf16_f32 v139, v37, v37
	global_store_short v179, v139, s[36:37] offset:64
	v_add_u32_e32 v178, 0x4a000, v176
	v_add_u32_e32 v179, 0x25000, v177
	v_add_f32_e32 v54, v54, v140
	global_store_dword v178, v54, s[28:29]
	v_cvt_pk_bf16_f32 v140, v54, v54
	global_store_short v179, v140, s[36:37]
	v_add_f32_e32 v38, v38, v141
	global_store_dword v178, v38, s[28:29] offset:128
	v_cvt_pk_bf16_f32 v141, v38, v38
	global_store_short v179, v141, s[36:37] offset:64
	v_add_u32_e32 v178, 0x4b000, v176
	v_add_u32_e32 v179, 0x25800, v177
	v_add_f32_e32 v55, v55, v142
	global_store_dword v178, v55, s[28:29]
	v_cvt_pk_bf16_f32 v142, v55, v55
	global_store_short v179, v142, s[36:37]
	v_add_f32_e32 v39, v39, v143
	global_store_dword v178, v39, s[28:29] offset:128
	v_cvt_pk_bf16_f32 v143, v39, v39
	global_store_short v179, v143, s[36:37] offset:64
	v_add_u32_e32 v178, 0x50000, v176
	v_add_u32_e32 v179, 0x28000, v177
	v_add_f32_e32 v56, v56, v144
	global_store_dword v178, v56, s[28:29]
	v_cvt_pk_bf16_f32 v144, v56, v56
	global_store_short v179, v144, s[36:37]
	v_add_f32_e32 v40, v40, v145
	global_store_dword v178, v40, s[28:29] offset:128
	v_cvt_pk_bf16_f32 v145, v40, v40
	global_store_short v179, v145, s[36:37] offset:64
	v_add_u32_e32 v178, 0x51000, v176
	v_add_u32_e32 v179, 0x28800, v177
	v_add_f32_e32 v57, v57, v146
	global_store_dword v178, v57, s[28:29]
	v_cvt_pk_bf16_f32 v146, v57, v57
	global_store_short v179, v146, s[36:37]
	v_add_f32_e32 v41, v41, v147
	global_store_dword v178, v41, s[28:29] offset:128
	v_cvt_pk_bf16_f32 v147, v41, v41
	global_store_short v179, v147, s[36:37] offset:64
	v_add_u32_e32 v178, 0x52000, v176
	v_add_u32_e32 v179, 0x29000, v177
	v_add_f32_e32 v58, v58, v148
	global_store_dword v178, v58, s[28:29]
	v_cvt_pk_bf16_f32 v148, v58, v58
	global_store_short v179, v148, s[36:37]
	v_add_f32_e32 v42, v42, v149
	global_store_dword v178, v42, s[28:29] offset:128
	v_cvt_pk_bf16_f32 v149, v42, v42
	global_store_short v179, v149, s[36:37] offset:64
	v_add_u32_e32 v178, 0x53000, v176
	v_add_u32_e32 v179, 0x29800, v177
	v_add_f32_e32 v59, v59, v150
	global_store_dword v178, v59, s[28:29]
	v_cvt_pk_bf16_f32 v150, v59, v59
	global_store_short v179, v150, s[36:37]
	v_add_f32_e32 v43, v43, v151
	global_store_dword v178, v43, s[28:29] offset:128
	v_cvt_pk_bf16_f32 v151, v43, v43
	global_store_short v179, v151, s[36:37] offset:64
	v_add_u32_e32 v178, 0x58000, v176
	v_add_u32_e32 v179, 0x2c000, v177
	v_add_f32_e32 v60, v60, v152
	global_store_dword v178, v60, s[28:29]
	v_cvt_pk_bf16_f32 v152, v60, v60
	global_store_short v179, v152, s[36:37]
	v_add_f32_e32 v44, v44, v153
	global_store_dword v178, v44, s[28:29] offset:128
	v_cvt_pk_bf16_f32 v153, v44, v44
	global_store_short v179, v153, s[36:37] offset:64
	v_add_u32_e32 v178, 0x59000, v176
	v_add_u32_e32 v179, 0x2c800, v177
	v_add_f32_e32 v61, v61, v154
	global_store_dword v178, v61, s[28:29]
	v_cvt_pk_bf16_f32 v154, v61, v61
	global_store_short v179, v154, s[36:37]
	v_add_f32_e32 v45, v45, v155
	global_store_dword v178, v45, s[28:29] offset:128
	v_cvt_pk_bf16_f32 v155, v45, v45
	global_store_short v179, v155, s[36:37] offset:64
	v_add_u32_e32 v178, 0x5a000, v176
	v_add_u32_e32 v179, 0x2d000, v177
	v_add_f32_e32 v62, v62, v156
	global_store_dword v178, v62, s[28:29]
	v_cvt_pk_bf16_f32 v156, v62, v62
	global_store_short v179, v156, s[36:37]
	v_add_f32_e32 v46, v46, v157
	global_store_dword v178, v46, s[28:29] offset:128
	v_cvt_pk_bf16_f32 v157, v46, v46
	global_store_short v179, v157, s[36:37] offset:64
	v_add_u32_e32 v178, 0x5b000, v176
	v_add_u32_e32 v179, 0x2d800, v177
	v_add_f32_e32 v63, v63, v158
	global_store_dword v178, v63, s[28:29]
	v_cvt_pk_bf16_f32 v158, v63, v63
	global_store_short v179, v158, s[36:37]
	v_add_f32_e32 v47, v47, v159
	global_store_dword v178, v47, s[28:29] offset:128
	v_cvt_pk_bf16_f32 v159, v47, v47
	global_store_short v179, v159, s[36:37] offset:64
	s_waitcnt vmcnt(63)
; #define ZERO_ACCM(a, MT) _Pragma("unroll") for (int _m = 0; _m < MT; ++_m) _Pragma("unroll") for (int _n = 0; _n < 2; ++_n) _Pragma("unroll") for (int _i = 0; _i < 16; ++_i) a[_m][_n][_i] = 0.f;
; DI void phase_resid(const Params& p, const bfu* A, int lda, const bfu* Bt, int K, char* smem) {
;     ...
;   for (int id = blockIdx.x; id < 64 * 8; id += gridDim.x) {
;     int tm, tn; map_tile(id, 8, tm, tn);
;     const int m0 = tm * 256, n0 = tn * 128;
;     f32x16 acc[4][2]; ZERO_ACCM(acc, 4)
;     gemm_core<false, false, 4>(A, lda, Bt, K, K, m0, n0, acc, smem);
;     EPI_BEGINM(acc, 4)
;       float* xp = p.out + (size_t)row * 1024 + col;
;       float nv = *xp + v; *xp = nv; p.xb[(size_t)row * 1024 + col] = f2bf(nv);
;     EPI_END
;   }
	v_add_u32_e32 v178, 0x60000, v176
	v_add_u32_e32 v179, 0x30000, v177
	v_add_f32_e32 v16, v16, v160
	global_store_dword v178, v16, s[28:29]
	v_cvt_pk_bf16_f32 v160, v16, v16
	global_store_short v179, v160, s[36:37]
	v_add_f32_e32 v0, v0, v161
	global_store_dword v178, v0, s[28:29] offset:128
	v_cvt_pk_bf16_f32 v161, v0, v0
	global_store_short v179, v161, s[36:37] offset:64
	v_add_u32_e32 v178, 0x61000, v176
	v_add_u32_e32 v179, 0x30800, v177
	v_add_f32_e32 v17, v17, v162
	global_store_dword v178, v17, s[28:29]
	v_cvt_pk_bf16_f32 v162, v17, v17
	global_store_short v179, v162, s[36:37]
	v_add_f32_e32 v1, v1, v163
	global_store_dword v178, v1, s[28:29] offset:128
	v_cvt_pk_bf16_f32 v163, v1, v1
	global_store_short v179, v163, s[36:37] offset:64
	v_add_u32_e32 v178, 0x62000, v176
	v_add_u32_e32 v179, 0x31000, v177
	v_add_f32_e32 v18, v18, v164
	global_store_dword v178, v18, s[28:29]
	v_cvt_pk_bf16_f32 v164, v18, v18
	global_store_short v179, v164, s[36:37]
	v_add_f32_e32 v2, v2, v165
	global_store_dword v178, v2, s[28:29] offset:128
	v_cvt_pk_bf16_f32 v165, v2, v2
	global_store_short v179, v165, s[36:37] offset:64
	v_add_u32_e32 v178, 0x63000, v176
	v_add_u32_e32 v179, 0x31800, v177
	v_add_f32_e32 v19, v19, v166
	global_store_dword v178, v19, s[28:29]
	v_cvt_pk_bf16_f32 v166, v19, v19
	global_store_short v179, v166, s[36:37]
	v_add_f32_e32 v3, v3, v167
	global_store_dword v178, v3, s[28:29] offset:128
	v_cvt_pk_bf16_f32 v167, v3, v3
	global_store_short v179, v167, s[36:37] offset:64
	v_add_u32_e32 v178, 0x68000, v176
	v_add_u32_e32 v179, 0x34000, v177
	v_add_f32_e32 v20, v20, v168
	global_store_dword v178, v20, s[28:29]
	v_cvt_pk_bf16_f32 v168, v20, v20
	global_store_short v179, v168, s[36:37]
	v_add_f32_e32 v4, v4, v169
	global_store_dword v178, v4, s[28:29] offset:128
	v_cvt_pk_bf16_f32 v169, v4, v4
	global_store_short v179, v169, s[36:37] offset:64
	v_add_u32_e32 v178, 0x69000, v176
	v_add_u32_e32 v179, 0x34800, v177
	v_add_f32_e32 v21, v21, v170
	global_store_dword v178, v21, s[28:29]
	v_cvt_pk_bf16_f32 v170, v21, v21
	global_store_short v179, v170, s[36:37]
	v_add_f32_e32 v5, v5, v171
	global_store_dword v178, v5, s[28:29] offset:128
	v_cvt_pk_bf16_f32 v171, v5, v5
	global_store_short v179, v171, s[36:37] offset:64
	v_add_u32_e32 v178, 0x6a000, v176
	v_add_u32_e32 v179, 0x35000, v177
	v_add_f32_e32 v22, v22, v172
	global_store_dword v178, v22, s[28:29]
	v_cvt_pk_bf16_f32 v172, v22, v22
	global_store_short v179, v172, s[36:37]
	v_add_f32_e32 v6, v6, v173
	global_store_dword v178, v6, s[28:29] offset:128
	v_cvt_pk_bf16_f32 v173, v6, v6
	global_store_short v179, v173, s[36:37] offset:64
	v_add_u32_e32 v178, 0x6b000, v176
	v_add_u32_e32 v179, 0x35800, v177
	v_add_f32_e32 v23, v23, v174
	global_store_dword v178, v23, s[28:29]
	v_cvt_pk_bf16_f32 v174, v23, v23
	global_store_short v179, v174, s[36:37]
	v_add_f32_e32 v7, v7, v175
	global_store_dword v178, v7, s[28:29] offset:128
	v_cvt_pk_bf16_f32 v175, v7, v7
	global_store_short v179, v175, s[36:37] offset:64
	v_add_u32_e32 v178, 0x70000, v176
	v_add_u32_e32 v179, 0x38000, v177
	v_add_f32_e32 v24, v24, v184
	global_store_dword v178, v24, s[28:29]
	v_cvt_pk_bf16_f32 v184, v24, v24
	global_store_short v179, v184, s[36:37]
	v_add_f32_e32 v8, v8, v185
	global_store_dword v178, v8, s[28:29] offset:128
	v_cvt_pk_bf16_f32 v185, v8, v8
	global_store_short v179, v185, s[36:37] offset:64
	v_add_u32_e32 v178, 0x71000, v176
	v_add_u32_e32 v179, 0x38800, v177
	v_add_f32_e32 v25, v25, v186
	global_store_dword v178, v25, s[28:29]
	v_cvt_pk_bf16_f32 v186, v25, v25
	global_store_short v179, v186, s[36:37]
	v_add_f32_e32 v9, v9, v187
	global_store_dword v178, v9, s[28:29] offset:128
	v_cvt_pk_bf16_f32 v187, v9, v9
	global_store_short v179, v187, s[36:37] offset:64
	v_add_u32_e32 v178, 0x72000, v176
	v_add_u32_e32 v179, 0x39000, v177
	v_add_f32_e32 v26, v26, v190
	global_store_dword v178, v26, s[28:29]
	v_cvt_pk_bf16_f32 v190, v26, v26
	global_store_short v179, v190, s[36:37]
	v_add_f32_e32 v10, v10, v191
	global_store_dword v178, v10, s[28:29] offset:128
	v_cvt_pk_bf16_f32 v191, v10, v10
	global_store_short v179, v191, s[36:37] offset:64
	v_add_u32_e32 v178, 0x73000, v176
	v_add_u32_e32 v179, 0x39800, v177
	v_add_f32_e32 v27, v27, v192
	global_store_dword v178, v27, s[28:29]
	v_cvt_pk_bf16_f32 v192, v27, v27
	global_store_short v179, v192, s[36:37]
	v_add_f32_e32 v11, v11, v193
	global_store_dword v178, v11, s[28:29] offset:128
	v_cvt_pk_bf16_f32 v193, v11, v11
	global_store_short v179, v193, s[36:37] offset:64
	v_add_u32_e32 v178, 0x78000, v176
	v_add_u32_e32 v179, 0x3c000, v177
	v_add_f32_e32 v28, v28, v194
	global_store_dword v178, v28, s[28:29]
	v_cvt_pk_bf16_f32 v194, v28, v28
	global_store_short v179, v194, s[36:37]
	v_add_f32_e32 v12, v12, v195
	global_store_dword v178, v12, s[28:29] offset:128
	v_cvt_pk_bf16_f32 v195, v12, v12
	global_store_short v179, v195, s[36:37] offset:64
	v_add_u32_e32 v178, 0x79000, v176
	v_add_u32_e32 v179, 0x3c800, v177
	v_add_f32_e32 v29, v29, v196
	global_store_dword v178, v29, s[28:29]
	v_cvt_pk_bf16_f32 v196, v29, v29
	global_store_short v179, v196, s[36:37]
	v_add_f32_e32 v13, v13, v197
	global_store_dword v178, v13, s[28:29] offset:128
	v_cvt_pk_bf16_f32 v197, v13, v13
	global_store_short v179, v197, s[36:37] offset:64
	v_add_u32_e32 v178, 0x7a000, v176
	v_add_u32_e32 v179, 0x3d000, v177
	v_add_f32_e32 v30, v30, v198
	global_store_dword v178, v30, s[28:29]
	v_cvt_pk_bf16_f32 v198, v30, v30
	global_store_short v179, v198, s[36:37]
	v_add_f32_e32 v14, v14, v199
	global_store_dword v178, v14, s[28:29] offset:128
	v_cvt_pk_bf16_f32 v199, v14, v14
	global_store_short v179, v199, s[36:37] offset:64
	v_add_u32_e32 v178, 0x7b000, v176
	v_add_u32_e32 v179, 0x3d800, v177
	v_add_f32_e32 v31, v31, v200
	global_store_dword v178, v31, s[28:29]
	v_cvt_pk_bf16_f32 v200, v31, v31
	global_store_short v179, v200, s[36:37]
	v_add_f32_e32 v15, v15, v201
	global_store_dword v178, v15, s[28:29] offset:128
	v_cvt_pk_bf16_f32 v201, v15, v15
	global_store_short v179, v201, s[36:37] offset:64
	s_load_dword s3, s[4:5], 0x0
	s_waitcnt lgkmcnt(0)
	s_add_i32 s2, s3, s2
	s_cmpk_gt_i32 s2, 0x1ff
	s_cbranch_scc0 .LBB0_95

; template <bool NORM, bool DEEP, int MTW, int KSEG, class HOOK>
; DI void gemm_core_h(const bfu* __restrict__ A, int lda, const bfu* __restrict__ Bt, int ldb, int K, int m0, int n0,
;                     f32x16 (&acc)[MTW][2], char* smem, HOOK hook) {
;     ...
;   if (DEEP) {
;     for (int kt = 0; kt < nk; kt += 2) {
;       GEMM_STEP(ra0, rb0, kt, 2)
;       GEMM_STEP(ra1, rb1, kt + 1, 2)
;     }
;   } else {
;     for (int kt = 0; kt < nk; ++kt) {
;       GEMM_STEP(ra0, rb0, kt, 1)
.LBB0_128:
	s_waitcnt lgkmcnt(0)
	s_barrier
	s_waitcnt vmcnt(11)
	ds_write_b128 v183, v[140:143] offset:36864
	v_add_u32_e32 v188, s5, v178
	v_add_u32_e32 v188, 0x40, v188
	v_lshl_add_u64 v[140:141], v[188:189], 1, s[22:23]
	global_load_dwordx4 v[140:143], v[140:141], off
	s_waitcnt vmcnt(11)
	ds_write_b128 v183, v[136:139] offset:41472
	v_add_u32_e32 v188, s5, v178
	v_add_u32_e32 v188, 0x8040, v188
	v_lshl_add_u64 v[136:137], v[188:189], 1, s[22:23]
	global_load_dwordx4 v[136:139], v[136:137], off
	s_waitcnt vmcnt(11)
	ds_write_b128 v183, v[128:131] offset:46080
	v_add_u32_e32 v188, s5, v178
	v_add_u32_e32 v188, 0x10040, v188
	v_lshl_add_u64 v[128:129], v[188:189], 1, s[22:23]
	global_load_dwordx4 v[128:131], v[128:129], off
	s_waitcnt vmcnt(11)
	ds_write_b128 v183, v[132:135] offset:50688
	v_add_u32_e32 v188, s5, v178
	v_add_u32_e32 v188, 0x18040, v188
	v_lshl_add_u64 v[132:133], v[188:189], 1, s[22:23]
	global_load_dwordx4 v[132:135], v[132:133], off
	s_waitcnt vmcnt(11)
	ds_write_b128 v183, v[148:151]
	v_add_u32_e32 v188, s5, v176
	v_add_u32_e32 v188, 0x40, v188
	v_lshl_add_u64 v[148:149], v[188:189], 1, s[76:77]
	global_load_dwordx4 v[148:151], v[148:149], off
	s_waitcnt vmcnt(11)
	ds_write_b128 v183, v[144:147] offset:4608
	v_add_u32_e32 v188, s5, v176
	v_add_u32_e32 v188, 0x8040, v188
	v_lshl_add_u64 v[144:145], v[188:189], 1, s[76:77]
	global_load_dwordx4 v[144:147], v[144:145], off
	s_waitcnt vmcnt(11)
	ds_write_b128 v183, v[156:159] offset:9216
	v_add_u32_e32 v188, s5, v176
	v_add_u32_e32 v188, 0x10040, v188
	v_lshl_add_u64 v[156:157], v[188:189], 1, s[76:77]
	global_load_dwordx4 v[156:159], v[156:157], off
	s_waitcnt vmcnt(11)
	ds_write_b128 v183, v[152:155] offset:13824
	v_add_u32_e32 v188, s5, v176
	v_add_u32_e32 v188, 0x18040, v188
	v_lshl_add_u64 v[152:153], v[188:189], 1, s[76:77]
	global_load_dwordx4 v[152:155], v[152:153], off
	s_waitcnt vmcnt(11)
	ds_write_b128 v183, v[164:167] offset:18432
	v_add_u32_e32 v188, s5, v176
	v_add_u32_e32 v188, 0x20040, v188
	v_lshl_add_u64 v[164:165], v[188:189], 1, s[76:77]
	global_load_dwordx4 v[164:167], v[164:165], off
	s_waitcnt vmcnt(11)
	ds_write_b128 v183, v[160:163] offset:23040
	v_add_u32_e32 v188, s5, v176
	v_add_u32_e32 v188, 0x28040, v188
	v_lshl_add_u64 v[160:161], v[188:189], 1, s[76:77]
	global_load_dwordx4 v[160:163], v[160:161], off
	s_waitcnt vmcnt(11)
	ds_write_b128 v183, v[168:171] offset:27648
	v_add_u32_e32 v188, s5, v176
	v_add_u32_e32 v188, 0x30040, v188
	v_lshl_add_u64 v[168:169], v[188:189], 1, s[76:77]
	global_load_dwordx4 v[168:171], v[168:169], off
	s_waitcnt vmcnt(11)
	ds_write_b128 v183, v[172:175] offset:32256
	v_add_u32_e32 v188, s5, v176
	v_add_u32_e32 v188, 0x38040, v188
	v_lshl_add_u64 v[172:173], v[188:189], 1, s[76:77]
	global_load_dwordx4 v[172:175], v[172:173], off
	s_waitcnt lgkmcnt(0)
	s_barrier
	ds_read_b128 v[202:205], v182 offset:36864
	ds_read_b128 v[206:209], v182 offset:41472
	ds_read_b128 v[218:221], v179
	ds_read_b128 v[232:235], v179 offset:4608
	s_waitcnt lgkmcnt(1)
	v_mfma_f32_32x32x16_bf16 v[112:127], v[218:221], v[202:205], v[112:127]
	v_mfma_f32_32x32x16_bf16 v[96:111], v[218:221], v[206:209], v[96:111]
	ds_read_b128 v[218:221], v179 offset:9216
	s_waitcnt lgkmcnt(1)
	v_mfma_f32_32x32x16_bf16 v[80:95], v[232:235], v[202:205], v[80:95]
	v_mfma_f32_32x32x16_bf16 v[64:79], v[232:235], v[206:209], v[64:79]
	ds_read_b128 v[232:235], v177
	ds_read_b128 v[210:213], v182 offset:36896
	ds_read_b128 v[214:217], v182 offset:41504
	s_waitcnt lgkmcnt(3)
	v_mfma_f32_32x32x16_bf16 v[48:63], v[218:221], v[202:205], v[48:63]
	v_mfma_f32_32x32x16_bf16 v[32:47], v[218:221], v[206:209], v[32:47]
	ds_read_b128 v[218:221], v179 offset:32
	s_waitcnt lgkmcnt(3)
	v_mfma_f32_32x32x16_bf16 v[16:31], v[232:235], v[202:205], v[16:31]
	v_mfma_f32_32x32x16_bf16 v[0:15], v[232:235], v[206:209], v[0:15]
	ds_read_b128 v[232:235], v179 offset:4640
	s_waitcnt lgkmcnt(1)
	v_mfma_f32_32x32x16_bf16 v[112:127], v[218:221], v[210:213], v[112:127]
	v_mfma_f32_32x32x16_bf16 v[96:111], v[218:221], v[214:217], v[96:111]
	ds_read_b128 v[218:221], v179 offset:9248
	s_waitcnt lgkmcnt(1)
	v_mfma_f32_32x32x16_bf16 v[80:95], v[232:235], v[210:213], v[80:95]
	v_mfma_f32_32x32x16_bf16 v[64:79], v[232:235], v[214:217], v[64:79]
	ds_read_b128 v[232:235], v177 offset:32
	ds_read_b128 v[202:205], v182 offset:36928
	ds_read_b128 v[206:209], v182 offset:41536
	s_waitcnt lgkmcnt(3)
	v_mfma_f32_32x32x16_bf16 v[48:63], v[218:221], v[210:213], v[48:63]
	v_mfma_f32_32x32x16_bf16 v[32:47], v[218:221], v[214:217], v[32:47]
	ds_read_b128 v[218:221], v179 offset:64
	s_waitcnt lgkmcnt(3)
	v_mfma_f32_32x32x16_bf16 v[16:31], v[232:235], v[210:213], v[16:31]
	v_mfma_f32_32x32x16_bf16 v[0:15], v[232:235], v[214:217], v[0:15]
	ds_read_b128 v[232:235], v179 offset:4672
	s_waitcnt lgkmcnt(1)
	v_mfma_f32_32x32x16_bf16 v[112:127], v[218:221], v[202:205], v[112:127]
	v_mfma_f32_32x32x16_bf16 v[96:111], v[218:221], v[206:209], v[96:111]
	ds_read_b128 v[218:221], v179 offset:9280
	s_waitcnt lgkmcnt(1)
	v_mfma_f32_32x32x16_bf16 v[80:95], v[232:235], v[202:205], v[80:95]
	v_mfma_f32_32x32x16_bf16 v[64:79], v[232:235], v[206:209], v[64:79]
	ds_read_b128 v[232:235], v177 offset:64
	ds_read_b128 v[210:213], v182 offset:36960
	ds_read_b128 v[214:217], v182 offset:41568
	s_waitcnt lgkmcnt(3)
	v_mfma_f32_32x32x16_bf16 v[48:63], v[218:221], v[202:205], v[48:63]
	v_mfma_f32_32x32x16_bf16 v[32:47], v[218:221], v[206:209], v[32:47]
	ds_read_b128 v[218:221], v179 offset:96
	s_waitcnt lgkmcnt(3)
	v_mfma_f32_32x32x16_bf16 v[16:31], v[232:235], v[202:205], v[16:31]
	v_mfma_f32_32x32x16_bf16 v[0:15], v[232:235], v[206:209], v[0:15]
	ds_read_b128 v[232:235], v179 offset:4704
	s_waitcnt lgkmcnt(1)
	v_mfma_f32_32x32x16_bf16 v[112:127], v[218:221], v[210:213], v[112:127]
	v_mfma_f32_32x32x16_bf16 v[96:111], v[218:221], v[214:217], v[96:111]
	ds_read_b128 v[218:221], v179 offset:9312
	s_waitcnt lgkmcnt(1)
	v_mfma_f32_32x32x16_bf16 v[80:95], v[232:235], v[210:213], v[80:95]
	v_mfma_f32_32x32x16_bf16 v[64:79], v[232:235], v[214:217], v[64:79]
	ds_read_b128 v[232:235], v177 offset:96
	s_waitcnt lgkmcnt(1)
	v_mfma_f32_32x32x16_bf16 v[48:63], v[218:221], v[210:213], v[48:63]
	v_mfma_f32_32x32x16_bf16 v[32:47], v[218:221], v[214:217], v[32:47]
	s_waitcnt lgkmcnt(0)
	v_mfma_f32_32x32x16_bf16 v[16:31], v[232:235], v[210:213], v[16:31]
	v_mfma_f32_32x32x16_bf16 v[0:15], v[232:235], v[214:217], v[0:15]
	s_add_i32 s5, s5, 64
	s_cmpk_lg_i32 s5, 0x3c0
	s_cbranch_scc1 .LBB0_128
; template <bool NORM, bool DEEP, int MTW, int KSEG, class HOOK>
; DI void gemm_core_h(const bfu* __restrict__ A, int lda, const bfu* __restrict__ Bt, int ldb, int K, int m0, int n0,
;                     f32x16 (&acc)[MTW][2], char* smem, HOOK hook) {
;     ...
;   if (DEEP) {
;     for (int kt = 0; kt < nk; kt += 2) {
;       GEMM_STEP(ra0, rb0, kt, 2)
;       GEMM_STEP(ra1, rb1, kt + 1, 2)
;     }
;   } else {
;     for (int kt = 0; kt < nk; ++kt) {
;       GEMM_STEP(ra0, rb0, kt, 1)
;       if (KSEG > 0) { if (((kt + 1) % (KSEG > 0 ? KSEG : 1)) == 0) hook((kt + 1) / (KSEG > 0 ? KSEG : 1) - 1); }
;     }
;   }
;     ...
;   if (NORM) {
; #pragma unroll
;     for (int j = 0; j < NA; ++j) {
;       float v = ssq[j];
;       v += __shfl_xor(v, 1); v += __shfl_xor(v, 2); v += __shfl_xor(v, 4);
;       if (lkc == 0) rstd_s[lrow + 32 * j] = rsqrtf(v / (float)K + EPS);
;     }
;   }
;   __syncthreads();
	s_waitcnt vmcnt(0)
	s_waitcnt lgkmcnt(0)
	s_barrier
	s_waitcnt vmcnt(11)
	ds_write_b128 v183, v[148:151]
	s_waitcnt vmcnt(10)
	ds_write_b128 v183, v[144:147] offset:4608
	s_waitcnt vmcnt(9)
	ds_write_b128 v183, v[156:159] offset:9216
	s_waitcnt vmcnt(8)
	ds_write_b128 v183, v[152:155] offset:13824
	s_waitcnt vmcnt(7)
	ds_write_b128 v183, v[164:167] offset:18432
	s_waitcnt vmcnt(6)
	ds_write_b128 v183, v[160:163] offset:23040
	s_waitcnt vmcnt(5)
	ds_write_b128 v183, v[168:171] offset:27648
	s_waitcnt vmcnt(4)
	ds_write_b128 v183, v[172:175] offset:32256
	s_waitcnt vmcnt(3)
	ds_write_b128 v183, v[140:143] offset:36864
	s_waitcnt vmcnt(2)
	ds_write_b128 v183, v[136:139] offset:41472
	s_waitcnt vmcnt(1)
	ds_write_b128 v183, v[128:131] offset:46080
	s_waitcnt vmcnt(0)
	ds_write_b128 v183, v[132:135] offset:50688
	s_waitcnt lgkmcnt(0)
	s_barrier
	ds_read_b128 v[128:131], v182 offset:41472
	ds_read_b128 v[132:135], v182 offset:36864
	ds_read_b128 v[136:139], v182 offset:36896
	ds_read_b128 v[140:143], v179
	ds_read_b128 v[144:147], v179 offset:32
	s_waitcnt lgkmcnt(1)
	v_mfma_f32_32x32x16_bf16 v[112:127], v[140:143], v[132:135], v[112:127]
	v_readlane_b32 s16, v253, 32
	v_readlane_b32 s28, v253, 44
	v_readlane_b32 s29, v253, 45
	v_readlane_b32 s17, v253, 33
	v_readlane_b32 s18, v253, 34
	v_readlane_b32 s19, v253, 35
	v_readlane_b32 s20, v253, 36
	v_mfma_f32_32x32x16_bf16 v[96:111], v[140:143], v[128:131], v[96:111]
	ds_read_b128 v[140:143], v179 offset:4608
	v_readlane_b32 s21, v253, 37
	v_readlane_b32 s22, v253, 38
	v_readlane_b32 s23, v253, 39
	v_readlane_b32 s24, v253, 40
	v_readlane_b32 s25, v253, 41
	v_readlane_b32 s26, v253, 42
	s_waitcnt lgkmcnt(0)
	v_mfma_f32_32x32x16_bf16 v[80:95], v[140:143], v[132:135], v[80:95]
	v_readlane_b32 s27, v253, 43
	v_readlane_b32 s30, v253, 46
	v_readlane_b32 s31, v253, 47
	v_mfma_f32_32x32x16_bf16 v[64:79], v[140:143], v[128:131], v[64:79]
	ds_read_b128 v[140:143], v179 offset:9216
	s_waitcnt lgkmcnt(0)
	v_mfma_f32_32x32x16_bf16 v[48:63], v[140:143], v[132:135], v[48:63]
	v_mfma_f32_32x32x16_bf16 v[32:47], v[140:143], v[128:131], v[32:47]
	ds_read_b128 v[140:143], v177
	ds_read_b128 v[148:151], v177 offset:32
	s_waitcnt lgkmcnt(1)
	v_mfma_f32_32x32x16_bf16 v[16:31], v[140:143], v[132:135], v[16:31]
	ds_read_b128 v[132:135], v179 offset:4640
	v_mfma_f32_32x32x16_bf16 v[0:15], v[140:143], v[128:131], v[0:15]
	ds_read_b128 v[128:131], v182 offset:41504
	s_waitcnt lgkmcnt(1)
	v_mfma_f32_32x32x16_bf16 v[80:95], v[132:135], v[136:139], v[80:95]
	s_waitcnt lgkmcnt(0)
	v_mfma_f32_32x32x16_bf16 v[64:79], v[132:135], v[128:131], v[64:79]
	ds_read_b128 v[132:135], v179 offset:9248
	v_mfma_f32_32x32x16_bf16 v[112:127], v[144:147], v[136:139], v[112:127]
	v_mfma_f32_32x32x16_bf16 v[96:111], v[144:147], v[128:131], v[96:111]
	s_waitcnt lgkmcnt(0)
	v_mfma_f32_32x32x16_bf16 v[48:63], v[132:135], v[136:139], v[48:63]
	v_mfma_f32_32x32x16_bf16 v[32:47], v[132:135], v[128:131], v[32:47]
	v_mfma_f32_32x32x16_bf16 v[16:31], v[148:151], v[136:139], v[16:31]
	v_mfma_f32_32x32x16_bf16 v[0:15], v[148:151], v[128:131], v[0:15]
	ds_read_b128 v[128:131], v182 offset:36928
	ds_read_b128 v[132:135], v182 offset:41536
	ds_read_b128 v[136:139], v179 offset:64
	s_waitcnt lgkmcnt(0)
	v_mfma_f32_32x32x16_bf16 v[112:127], v[136:139], v[128:131], v[112:127]
	v_mfma_f32_32x32x16_bf16 v[96:111], v[136:139], v[132:135], v[96:111]
	ds_read_b128 v[136:139], v179 offset:4672
	s_waitcnt lgkmcnt(0)
	v_mfma_f32_32x32x16_bf16 v[80:95], v[136:139], v[128:131], v[80:95]
	v_mfma_f32_32x32x16_bf16 v[64:79], v[136:139], v[132:135], v[64:79]
	ds_read_b128 v[136:139], v179 offset:9280
	s_waitcnt lgkmcnt(0)
	v_mfma_f32_32x32x16_bf16 v[48:63], v[136:139], v[128:131], v[48:63]
	v_mfma_f32_32x32x16_bf16 v[32:47], v[136:139], v[132:135], v[32:47]
	ds_read_b128 v[136:139], v177 offset:64
	s_waitcnt lgkmcnt(0)
	v_mfma_f32_32x32x16_bf16 v[16:31], v[136:139], v[128:131], v[16:31]
	v_mfma_f32_32x32x16_bf16 v[0:15], v[136:139], v[132:135], v[0:15]
	ds_read_b128 v[128:131], v182 offset:36960
	ds_read_b128 v[132:135], v182 offset:41568
	ds_read_b128 v[136:139], v179 offset:96
	s_waitcnt lgkmcnt(0)
	v_mfma_f32_32x32x16_bf16 v[112:127], v[136:139], v[128:131], v[112:127]
	v_mfma_f32_32x32x16_bf16 v[96:111], v[136:139], v[132:135], v[96:111]
	ds_read_b128 v[136:139], v179 offset:4704
	s_waitcnt lgkmcnt(0)
	v_mfma_f32_32x32x16_bf16 v[80:95], v[136:139], v[128:131], v[80:95]
	v_mfma_f32_32x32x16_bf16 v[64:79], v[136:139], v[132:135], v[64:79]
	ds_read_b128 v[136:139], v179 offset:9312
	s_waitcnt lgkmcnt(0)
	v_mfma_f32_32x32x16_bf16 v[48:63], v[136:139], v[128:131], v[48:63]
	v_mfma_f32_32x32x16_bf16 v[32:47], v[136:139], v[132:135], v[32:47]
	ds_read_b128 v[136:139], v177 offset:96
	s_waitcnt lgkmcnt(0)
	s_barrier
; DI void phase_resid(const Params& p, const bfu* A, int lda, const bfu* Bt, int K, char* smem) {
;     ...
;     EPI_BEGINM(acc, 4)
;       float* xp = p.out + (size_t)row * 1024 + col;
;       float nv = *xp + v; *xp = nv; p.xb[(size_t)row * 1024 + col] = f2bf(nv);
;     EPI_END
	v_mfma_f32_32x32x16_bf16 v[16:31], v[136:139], v[128:131], v[16:31]
	v_mfma_f32_32x32x16_bf16 v[0:15], v[136:139], v[132:135], v[0:15]
	v_add_u32_e32 v176, s3, v180
	v_or_b32_e32 v177, s4, v181
	v_lshlrev_b32_e32 v176, 12, v176
	v_lshl_add_u32 v176, v177, 2, v176
	v_lshrrev_b32_e32 v177, 1, v176
	v_readlane_b32 s4, v254, 38
	v_readlane_b32 s5, v254, 39
	global_load_dword v128, v176, s[28:29] nt
	global_load_dword v129, v176, s[28:29] offset:128 nt
	v_add_u32_e32 v178, 0x1000, v176
	global_load_dword v130, v178, s[28:29] nt
	global_load_dword v131, v178, s[28:29] offset:128 nt
	v_add_u32_e32 v178, 0x2000, v176
	global_load_dword v132, v178, s[28:29] nt
	global_load_dword v133, v178, s[28:29] offset:128 nt
	v_add_u32_e32 v178, 0x3000, v176
	global_load_dword v134, v178, s[28:29] nt
	global_load_dword v135, v178, s[28:29] offset:128 nt
	v_add_u32_e32 v178, 0x8000, v176
	global_load_dword v136, v178, s[28:29] nt
	global_load_dword v137, v178, s[28:29] offset:128 nt
	v_add_u32_e32 v178, 0x9000, v176
	global_load_dword v138, v178, s[28:29] nt
	global_load_dword v139, v178, s[28:29] offset:128 nt
	v_add_u32_e32 v178, 0xa000, v176
	global_load_dword v140, v178, s[28:29] nt
	global_load_dword v141, v178, s[28:29] offset:128 nt
	v_add_u32_e32 v178, 0xb000, v176
	global_load_dword v142, v178, s[28:29] nt
	global_load_dword v143, v178, s[28:29] offset:128 nt
	v_add_u32_e32 v178, 0x10000, v176
	global_load_dword v144, v178, s[28:29] nt
	global_load_dword v145, v178, s[28:29] offset:128 nt
	v_add_u32_e32 v178, 0x11000, v176
	global_load_dword v146, v178, s[28:29] nt
	global_load_dword v147, v178, s[28:29] offset:128 nt
	v_add_u32_e32 v178, 0x12000, v176
	global_load_dword v148, v178, s[28:29] nt
	global_load_dword v149, v178, s[28:29] offset:128 nt
	v_add_u32_e32 v178, 0x13000, v176
	global_load_dword v150, v178, s[28:29] nt
	global_load_dword v151, v178, s[28:29] offset:128 nt
	v_add_u32_e32 v178, 0x18000, v176
	global_load_dword v152, v178, s[28:29] nt
	global_load_dword v153, v178, s[28:29] offset:128 nt
	v_add_u32_e32 v178, 0x19000, v176
	global_load_dword v154, v178, s[28:29] nt
	global_load_dword v155, v178, s[28:29] offset:128 nt
	v_add_u32_e32 v178, 0x1a000, v176
	global_load_dword v156, v178, s[28:29] nt
	global_load_dword v157, v178, s[28:29] offset:128 nt
	v_add_u32_e32 v178, 0x1b000, v176
	global_load_dword v158, v178, s[28:29] nt
	global_load_dword v159, v178, s[28:29] offset:128 nt
	v_add_u32_e32 v178, 0x20000, v176
	global_load_dword v160, v178, s[28:29] nt
	global_load_dword v161, v178, s[28:29] offset:128 nt
	v_add_u32_e32 v178, 0x21000, v176
	global_load_dword v162, v178, s[28:29] nt
	global_load_dword v163, v178, s[28:29] offset:128 nt
	v_add_u32_e32 v178, 0x22000, v176
	global_load_dword v164, v178, s[28:29] nt
	global_load_dword v165, v178, s[28:29] offset:128 nt
	v_add_u32_e32 v178, 0x23000, v176
	global_load_dword v166, v178, s[28:29] nt
	global_load_dword v167, v178, s[28:29] offset:128 nt
	v_add_u32_e32 v178, 0x28000, v176
	global_load_dword v168, v178, s[28:29] nt
	global_load_dword v169, v178, s[28:29] offset:128 nt
	v_add_u32_e32 v178, 0x29000, v176
	global_load_dword v170, v178, s[28:29] nt
	global_load_dword v171, v178, s[28:29] offset:128 nt
	v_add_u32_e32 v178, 0x2a000, v176
	global_load_dword v172, v178, s[28:29] nt
	global_load_dword v173, v178, s[28:29] offset:128 nt
	v_add_u32_e32 v178, 0x2b000, v176
	global_load_dword v174, v178, s[28:29] nt
	global_load_dword v175, v178, s[28:29] offset:128 nt
	v_add_u32_e32 v178, 0x30000, v176
	global_load_dword v184, v178, s[28:29] nt
	global_load_dword v185, v178, s[28:29] offset:128 nt
	v_add_u32_e32 v178, 0x31000, v176
	global_load_dword v186, v178, s[28:29] nt
	global_load_dword v187, v178, s[28:29] offset:128 nt
	v_add_u32_e32 v178, 0x32000, v176
	global_load_dword v190, v178, s[28:29] nt
	global_load_dword v191, v178, s[28:29] offset:128 nt
	v_add_u32_e32 v178, 0x33000, v176
	global_load_dword v192, v178, s[28:29] nt
	global_load_dword v193, v178, s[28:29] offset:128 nt
	v_add_u32_e32 v178, 0x38000, v176
	global_load_dword v194, v178, s[28:29] nt
	global_load_dword v195, v178, s[28:29] offset:128 nt
	v_add_u32_e32 v178, 0x39000, v176
	global_load_dword v196, v178, s[28:29] nt
	global_load_dword v197, v178, s[28:29] offset:128 nt
	v_add_u32_e32 v178, 0x3a000, v176
	global_load_dword v198, v178, s[28:29] nt
	global_load_dword v199, v178, s[28:29] offset:128 nt
	v_add_u32_e32 v178, 0x3b000, v176
	global_load_dword v200, v178, s[28:29] nt
	global_load_dword v201, v178, s[28:29] offset:128 nt
	s_waitcnt vmcnt(32)
; DI void phase_resid(const Params& p, const bfu* A, int lda, const bfu* Bt, int K, char* smem) {
;     ...
;     EPI_BEGINM(acc, 4)
;       float* xp = p.out + (size_t)row * 1024 + col;
;       float nv = *xp + v; *xp = nv; p.xb[(size_t)row * 1024 + col] = f2bf(nv);
;     EPI_END
	v_add_f32_e32 v112, v112, v128
	global_store_dword v176, v112, s[28:29]
	v_cvt_pk_bf16_f32 v128, v112, v112
	global_store_short v177, v128, s[36:37]
	v_add_f32_e32 v96, v96, v129
	global_store_dword v176, v96, s[28:29] offset:128
	v_cvt_pk_bf16_f32 v129, v96, v96
	global_store_short v177, v129, s[36:37] offset:64
	v_add_u32_e32 v178, 0x1000, v176
	v_add_u32_e32 v179, 0x800, v177
	v_add_f32_e32 v113, v113, v130
	global_store_dword v178, v113, s[28:29]
	v_cvt_pk_bf16_f32 v130, v113, v113
	global_store_short v179, v130, s[36:37]
	v_add_f32_e32 v97, v97, v131
	global_store_dword v178, v97, s[28:29] offset:128
	v_cvt_pk_bf16_f32 v131, v97, v97
	global_store_short v179, v131, s[36:37] offset:64
	v_add_u32_e32 v178, 0x2000, v176
	v_add_u32_e32 v179, 0x1000, v177
	v_add_f32_e32 v114, v114, v132
	global_store_dword v178, v114, s[28:29]
	v_cvt_pk_bf16_f32 v132, v114, v114
	global_store_short v179, v132, s[36:37]
	v_add_f32_e32 v98, v98, v133
	global_store_dword v178, v98, s[28:29] offset:128
	v_cvt_pk_bf16_f32 v133, v98, v98
	global_store_short v179, v133, s[36:37] offset:64
	v_add_u32_e32 v178, 0x3000, v176
	v_add_u32_e32 v179, 0x1800, v177
	v_add_f32_e32 v115, v115, v134
	global_store_dword v178, v115, s[28:29]
	v_cvt_pk_bf16_f32 v134, v115, v115
	global_store_short v179, v134, s[36:37]
	v_add_f32_e32 v99, v99, v135
	global_store_dword v178, v99, s[28:29] offset:128
	v_cvt_pk_bf16_f32 v135, v99, v99
	global_store_short v179, v135, s[36:37] offset:64
	v_add_u32_e32 v178, 0x8000, v176
	v_add_u32_e32 v179, 0x4000, v177
	v_add_f32_e32 v116, v116, v136
	global_store_dword v178, v116, s[28:29]
	v_cvt_pk_bf16_f32 v136, v116, v116
	global_store_short v179, v136, s[36:37]
	v_add_f32_e32 v100, v100, v137
	global_store_dword v178, v100, s[28:29] offset:128
	v_cvt_pk_bf16_f32 v137, v100, v100
	global_store_short v179, v137, s[36:37] offset:64
	v_add_u32_e32 v178, 0x9000, v176
	v_add_u32_e32 v179, 0x4800, v177
	v_add_f32_e32 v117, v117, v138
	global_store_dword v178, v117, s[28:29]
	v_cvt_pk_bf16_f32 v138, v117, v117
	global_store_short v179, v138, s[36:37]
	v_add_f32_e32 v101, v101, v139
	global_store_dword v178, v101, s[28:29] offset:128
	v_cvt_pk_bf16_f32 v139, v101, v101
	global_store_short v179, v139, s[36:37] offset:64
	v_add_u32_e32 v178, 0xa000, v176
	v_add_u32_e32 v179, 0x5000, v177
	v_add_f32_e32 v118, v118, v140
	global_store_dword v178, v118, s[28:29]
	v_cvt_pk_bf16_f32 v140, v118, v118
	global_store_short v179, v140, s[36:37]
	v_add_f32_e32 v102, v102, v141
	global_store_dword v178, v102, s[28:29] offset:128
	v_cvt_pk_bf16_f32 v141, v102, v102
	global_store_short v179, v141, s[36:37] offset:64
	v_add_u32_e32 v178, 0xb000, v176
	v_add_u32_e32 v179, 0x5800, v177
	v_add_f32_e32 v119, v119, v142
	global_store_dword v178, v119, s[28:29]
	v_cvt_pk_bf16_f32 v142, v119, v119
	global_store_short v179, v142, s[36:37]
	v_add_f32_e32 v103, v103, v143
	global_store_dword v178, v103, s[28:29] offset:128
	v_cvt_pk_bf16_f32 v143, v103, v103
	global_store_short v179, v143, s[36:37] offset:64
	v_add_u32_e32 v178, 0x10000, v176
	v_add_u32_e32 v179, 0x8000, v177
	v_add_f32_e32 v120, v120, v144
	global_store_dword v178, v120, s[28:29]
	v_cvt_pk_bf16_f32 v144, v120, v120
	global_store_short v179, v144, s[36:37]
	v_add_f32_e32 v104, v104, v145
	global_store_dword v178, v104, s[28:29] offset:128
	v_cvt_pk_bf16_f32 v145, v104, v104
	global_store_short v179, v145, s[36:37] offset:64
	v_add_u32_e32 v178, 0x11000, v176
	v_add_u32_e32 v179, 0x8800, v177
	v_add_f32_e32 v121, v121, v146
	global_store_dword v178, v121, s[28:29]
	v_cvt_pk_bf16_f32 v146, v121, v121
	global_store_short v179, v146, s[36:37]
	v_add_f32_e32 v105, v105, v147
	global_store_dword v178, v105, s[28:29] offset:128
	v_cvt_pk_bf16_f32 v147, v105, v105
	global_store_short v179, v147, s[36:37] offset:64
	v_add_u32_e32 v178, 0x12000, v176
	v_add_u32_e32 v179, 0x9000, v177
	v_add_f32_e32 v122, v122, v148
	global_store_dword v178, v122, s[28:29]
	v_cvt_pk_bf16_f32 v148, v122, v122
	global_store_short v179, v148, s[36:37]
	v_add_f32_e32 v106, v106, v149
	global_store_dword v178, v106, s[28:29] offset:128
	v_cvt_pk_bf16_f32 v149, v106, v106
	global_store_short v179, v149, s[36:37] offset:64
	v_add_u32_e32 v178, 0x13000, v176
	v_add_u32_e32 v179, 0x9800, v177
	v_add_f32_e32 v123, v123, v150
	global_store_dword v178, v123, s[28:29]
	v_cvt_pk_bf16_f32 v150, v123, v123
	global_store_short v179, v150, s[36:37]
	v_add_f32_e32 v107, v107, v151
	global_store_dword v178, v107, s[28:29] offset:128
	v_cvt_pk_bf16_f32 v151, v107, v107
	global_store_short v179, v151, s[36:37] offset:64
	v_add_u32_e32 v178, 0x18000, v176
	v_add_u32_e32 v179, 0xc000, v177
	v_add_f32_e32 v124, v124, v152
	global_store_dword v178, v124, s[28:29]
	v_cvt_pk_bf16_f32 v152, v124, v124
	global_store_short v179, v152, s[36:37]
	v_add_f32_e32 v108, v108, v153
	global_store_dword v178, v108, s[28:29] offset:128
	v_cvt_pk_bf16_f32 v153, v108, v108
	global_store_short v179, v153, s[36:37] offset:64
	v_add_u32_e32 v178, 0x19000, v176
	v_add_u32_e32 v179, 0xc800, v177
	v_add_f32_e32 v125, v125, v154
	global_store_dword v178, v125, s[28:29]
	v_cvt_pk_bf16_f32 v154, v125, v125
	global_store_short v179, v154, s[36:37]
	v_add_f32_e32 v109, v109, v155
	global_store_dword v178, v109, s[28:29] offset:128
	v_cvt_pk_bf16_f32 v155, v109, v109
	global_store_short v179, v155, s[36:37] offset:64
	v_add_u32_e32 v178, 0x1a000, v176
	v_add_u32_e32 v179, 0xd000, v177
	v_add_f32_e32 v126, v126, v156
	global_store_dword v178, v126, s[28:29]
	v_cvt_pk_bf16_f32 v156, v126, v126
	global_store_short v179, v156, s[36:37]
	v_add_f32_e32 v110, v110, v157
; DI void phase_resid(const Params& p, const bfu* A, int lda, const bfu* Bt, int K, char* smem) {
;     ...
;     EPI_BEGINM(acc, 4)
;       float* xp = p.out + (size_t)row * 1024 + col;
;       float nv = *xp + v; *xp = nv; p.xb[(size_t)row * 1024 + col] = f2bf(nv);
;     EPI_END
	global_store_dword v178, v110, s[28:29] offset:128
	v_cvt_pk_bf16_f32 v157, v110, v110
	global_store_short v179, v157, s[36:37] offset:64
	v_add_u32_e32 v178, 0x1b000, v176
	v_add_u32_e32 v179, 0xd800, v177
	v_add_f32_e32 v127, v127, v158
	global_store_dword v178, v127, s[28:29]
	v_cvt_pk_bf16_f32 v158, v127, v127
	global_store_short v179, v158, s[36:37]
	v_add_f32_e32 v111, v111, v159
	global_store_dword v178, v111, s[28:29] offset:128
	v_cvt_pk_bf16_f32 v159, v111, v111
	global_store_short v179, v159, s[36:37] offset:64
	v_add_u32_e32 v178, 0x40000, v176
	global_load_dword v128, v178, s[28:29] nt
	global_load_dword v129, v178, s[28:29] offset:128 nt
	v_add_u32_e32 v178, 0x41000, v176
	global_load_dword v130, v178, s[28:29] nt
	global_load_dword v131, v178, s[28:29] offset:128 nt
	v_add_u32_e32 v178, 0x42000, v176
	global_load_dword v132, v178, s[28:29] nt
	global_load_dword v133, v178, s[28:29] offset:128 nt
	v_add_u32_e32 v178, 0x43000, v176
	global_load_dword v134, v178, s[28:29] nt
	global_load_dword v135, v178, s[28:29] offset:128 nt
	v_add_u32_e32 v178, 0x48000, v176
	global_load_dword v136, v178, s[28:29] nt
	global_load_dword v137, v178, s[28:29] offset:128 nt
	v_add_u32_e32 v178, 0x49000, v176
	global_load_dword v138, v178, s[28:29] nt
	global_load_dword v139, v178, s[28:29] offset:128 nt
	v_add_u32_e32 v178, 0x4a000, v176
	global_load_dword v140, v178, s[28:29] nt
	global_load_dword v141, v178, s[28:29] offset:128 nt
	v_add_u32_e32 v178, 0x4b000, v176
	global_load_dword v142, v178, s[28:29] nt
	global_load_dword v143, v178, s[28:29] offset:128 nt
	v_add_u32_e32 v178, 0x50000, v176
	global_load_dword v144, v178, s[28:29] nt
	global_load_dword v145, v178, s[28:29] offset:128 nt
	v_add_u32_e32 v178, 0x51000, v176
	global_load_dword v146, v178, s[28:29] nt
	global_load_dword v147, v178, s[28:29] offset:128 nt
	v_add_u32_e32 v178, 0x52000, v176
	global_load_dword v148, v178, s[28:29] nt
	global_load_dword v149, v178, s[28:29] offset:128 nt
	v_add_u32_e32 v178, 0x53000, v176
	global_load_dword v150, v178, s[28:29] nt
	global_load_dword v151, v178, s[28:29] offset:128 nt
	v_add_u32_e32 v178, 0x58000, v176
	global_load_dword v152, v178, s[28:29] nt
	global_load_dword v153, v178, s[28:29] offset:128 nt
	v_add_u32_e32 v178, 0x59000, v176
	global_load_dword v154, v178, s[28:29] nt
	global_load_dword v155, v178, s[28:29] offset:128 nt
	v_add_u32_e32 v178, 0x5a000, v176
	global_load_dword v156, v178, s[28:29] nt
	global_load_dword v157, v178, s[28:29] offset:128 nt
	v_add_u32_e32 v178, 0x5b000, v176
	global_load_dword v158, v178, s[28:29] nt
	global_load_dword v159, v178, s[28:29] offset:128 nt
	s_waitcnt vmcnt(63)
	v_add_u32_e32 v178, 0x20000, v176
	v_add_u32_e32 v179, 0x10000, v177
	v_add_f32_e32 v80, v80, v160
	global_store_dword v178, v80, s[28:29]
	v_cvt_pk_bf16_f32 v160, v80, v80
	global_store_short v179, v160, s[36:37]
	v_add_f32_e32 v64, v64, v161
	global_store_dword v178, v64, s[28:29] offset:128
	v_cvt_pk_bf16_f32 v161, v64, v64
	global_store_short v179, v161, s[36:37] offset:64
	v_add_u32_e32 v178, 0x21000, v176
	v_add_u32_e32 v179, 0x10800, v177
	v_add_f32_e32 v81, v81, v162
	global_store_dword v178, v81, s[28:29]
	v_cvt_pk_bf16_f32 v162, v81, v81
	global_store_short v179, v162, s[36:37]
	v_add_f32_e32 v65, v65, v163
	global_store_dword v178, v65, s[28:29] offset:128
	v_cvt_pk_bf16_f32 v163, v65, v65
	global_store_short v179, v163, s[36:37] offset:64
	v_add_u32_e32 v178, 0x22000, v176
	v_add_u32_e32 v179, 0x11000, v177
	v_add_f32_e32 v82, v82, v164
	global_store_dword v178, v82, s[28:29]
	v_cvt_pk_bf16_f32 v164, v82, v82
	global_store_short v179, v164, s[36:37]
	v_add_f32_e32 v66, v66, v165
	global_store_dword v178, v66, s[28:29] offset:128
	v_cvt_pk_bf16_f32 v165, v66, v66
	global_store_short v179, v165, s[36:37] offset:64
	v_add_u32_e32 v178, 0x23000, v176
	v_add_u32_e32 v179, 0x11800, v177
	v_add_f32_e32 v83, v83, v166
	global_store_dword v178, v83, s[28:29]
	v_cvt_pk_bf16_f32 v166, v83, v83
	global_store_short v179, v166, s[36:37]
	v_add_f32_e32 v67, v67, v167
	global_store_dword v178, v67, s[28:29] offset:128
	v_cvt_pk_bf16_f32 v167, v67, v67
	global_store_short v179, v167, s[36:37] offset:64
	v_add_u32_e32 v178, 0x28000, v176
	v_add_u32_e32 v179, 0x14000, v177
	v_add_f32_e32 v84, v84, v168
	global_store_dword v178, v84, s[28:29]
	v_cvt_pk_bf16_f32 v168, v84, v84
	global_store_short v179, v168, s[36:37]
	v_add_f32_e32 v68, v68, v169
	global_store_dword v178, v68, s[28:29] offset:128
	v_cvt_pk_bf16_f32 v169, v68, v68
	global_store_short v179, v169, s[36:37] offset:64
	v_add_u32_e32 v178, 0x29000, v176
	v_add_u32_e32 v179, 0x14800, v177
	v_add_f32_e32 v85, v85, v170
	global_store_dword v178, v85, s[28:29]
	v_cvt_pk_bf16_f32 v170, v85, v85
	global_store_short v179, v170, s[36:37]
	v_add_f32_e32 v69, v69, v171
	global_store_dword v178, v69, s[28:29] offset:128
	v_cvt_pk_bf16_f32 v171, v69, v69
	global_store_short v179, v171, s[36:37] offset:64
	v_add_u32_e32 v178, 0x2a000, v176
	v_add_u32_e32 v179, 0x15000, v177
	v_add_f32_e32 v86, v86, v172
	global_store_dword v178, v86, s[28:29]
	v_cvt_pk_bf16_f32 v172, v86, v86
	global_store_short v179, v172, s[36:37]
	v_add_f32_e32 v70, v70, v173
	global_store_dword v178, v70, s[28:29] offset:128
	v_cvt_pk_bf16_f32 v173, v70, v70
	global_store_short v179, v173, s[36:37] offset:64
	v_add_u32_e32 v178, 0x2b000, v176
	v_add_u32_e32 v179, 0x15800, v177
	v_add_f32_e32 v87, v87, v174
	global_store_dword v178, v87, s[28:29]
	v_cvt_pk_bf16_f32 v174, v87, v87
	global_store_short v179, v174, s[36:37]
	v_add_f32_e32 v71, v71, v175
	global_store_dword v178, v71, s[28:29] offset:128
; DI void phase_resid(const Params& p, const bfu* A, int lda, const bfu* Bt, int K, char* smem) {
;     ...
;     EPI_BEGINM(acc, 4)
;       float* xp = p.out + (size_t)row * 1024 + col;
;       float nv = *xp + v; *xp = nv; p.xb[(size_t)row * 1024 + col] = f2bf(nv);
;     EPI_END
	v_cvt_pk_bf16_f32 v175, v71, v71
	global_store_short v179, v175, s[36:37] offset:64
	v_add_u32_e32 v178, 0x30000, v176
	v_add_u32_e32 v179, 0x18000, v177
	v_add_f32_e32 v88, v88, v184
	global_store_dword v178, v88, s[28:29]
	v_cvt_pk_bf16_f32 v184, v88, v88
	global_store_short v179, v184, s[36:37]
	v_add_f32_e32 v72, v72, v185
	global_store_dword v178, v72, s[28:29] offset:128
	v_cvt_pk_bf16_f32 v185, v72, v72
	global_store_short v179, v185, s[36:37] offset:64
	v_add_u32_e32 v178, 0x31000, v176
	v_add_u32_e32 v179, 0x18800, v177
	v_add_f32_e32 v89, v89, v186
	global_store_dword v178, v89, s[28:29]
	v_cvt_pk_bf16_f32 v186, v89, v89
	global_store_short v179, v186, s[36:37]
	v_add_f32_e32 v73, v73, v187
	global_store_dword v178, v73, s[28:29] offset:128
	v_cvt_pk_bf16_f32 v187, v73, v73
	global_store_short v179, v187, s[36:37] offset:64
	v_add_u32_e32 v178, 0x32000, v176
	v_add_u32_e32 v179, 0x19000, v177
	v_add_f32_e32 v90, v90, v190
	global_store_dword v178, v90, s[28:29]
	v_cvt_pk_bf16_f32 v190, v90, v90
	global_store_short v179, v190, s[36:37]
	v_add_f32_e32 v74, v74, v191
	global_store_dword v178, v74, s[28:29] offset:128
	v_cvt_pk_bf16_f32 v191, v74, v74
	global_store_short v179, v191, s[36:37] offset:64
	v_add_u32_e32 v178, 0x33000, v176
	v_add_u32_e32 v179, 0x19800, v177
	v_add_f32_e32 v91, v91, v192
	global_store_dword v178, v91, s[28:29]
	v_cvt_pk_bf16_f32 v192, v91, v91
	global_store_short v179, v192, s[36:37]
	v_add_f32_e32 v75, v75, v193
	global_store_dword v178, v75, s[28:29] offset:128
	v_cvt_pk_bf16_f32 v193, v75, v75
	global_store_short v179, v193, s[36:37] offset:64
	v_add_u32_e32 v178, 0x38000, v176
	v_add_u32_e32 v179, 0x1c000, v177
	v_add_f32_e32 v92, v92, v194
	global_store_dword v178, v92, s[28:29]
	v_cvt_pk_bf16_f32 v194, v92, v92
	global_store_short v179, v194, s[36:37]
	v_add_f32_e32 v76, v76, v195
	global_store_dword v178, v76, s[28:29] offset:128
	v_cvt_pk_bf16_f32 v195, v76, v76
	global_store_short v179, v195, s[36:37] offset:64
	v_add_u32_e32 v178, 0x39000, v176
	v_add_u32_e32 v179, 0x1c800, v177
	v_add_f32_e32 v93, v93, v196
	global_store_dword v178, v93, s[28:29]
	v_cvt_pk_bf16_f32 v196, v93, v93
	global_store_short v179, v196, s[36:37]
	v_add_f32_e32 v77, v77, v197
	global_store_dword v178, v77, s[28:29] offset:128
	v_cvt_pk_bf16_f32 v197, v77, v77
	global_store_short v179, v197, s[36:37] offset:64
	v_add_u32_e32 v178, 0x3a000, v176
	v_add_u32_e32 v179, 0x1d000, v177
	v_add_f32_e32 v94, v94, v198
	global_store_dword v178, v94, s[28:29]
	v_cvt_pk_bf16_f32 v198, v94, v94
	global_store_short v179, v198, s[36:37]
	v_add_f32_e32 v78, v78, v199
	global_store_dword v178, v78, s[28:29] offset:128
	v_cvt_pk_bf16_f32 v199, v78, v78
	global_store_short v179, v199, s[36:37] offset:64
	v_add_u32_e32 v178, 0x3b000, v176
	v_add_u32_e32 v179, 0x1d800, v177
	v_add_f32_e32 v95, v95, v200
	global_store_dword v178, v95, s[28:29]
	v_cvt_pk_bf16_f32 v200, v95, v95
	global_store_short v179, v200, s[36:37]
	v_add_f32_e32 v79, v79, v201
	global_store_dword v178, v79, s[28:29] offset:128
	v_cvt_pk_bf16_f32 v201, v79, v79
	global_store_short v179, v201, s[36:37] offset:64
	v_add_u32_e32 v178, 0x60000, v176
	global_load_dword v160, v178, s[28:29] nt
	global_load_dword v161, v178, s[28:29] offset:128 nt
	v_add_u32_e32 v178, 0x61000, v176
	global_load_dword v162, v178, s[28:29] nt
	global_load_dword v163, v178, s[28:29] offset:128 nt
	v_add_u32_e32 v178, 0x62000, v176
	global_load_dword v164, v178, s[28:29] nt
	global_load_dword v165, v178, s[28:29] offset:128 nt
	v_add_u32_e32 v178, 0x63000, v176
	global_load_dword v166, v178, s[28:29] nt
	global_load_dword v167, v178, s[28:29] offset:128 nt
	v_add_u32_e32 v178, 0x68000, v176
	global_load_dword v168, v178, s[28:29] nt
	global_load_dword v169, v178, s[28:29] offset:128 nt
	v_add_u32_e32 v178, 0x69000, v176
	global_load_dword v170, v178, s[28:29] nt
	global_load_dword v171, v178, s[28:29] offset:128 nt
	v_add_u32_e32 v178, 0x6a000, v176
	global_load_dword v172, v178, s[28:29] nt
	global_load_dword v173, v178, s[28:29] offset:128 nt
	v_add_u32_e32 v178, 0x6b000, v176
	global_load_dword v174, v178, s[28:29] nt
	global_load_dword v175, v178, s[28:29] offset:128 nt
	v_add_u32_e32 v178, 0x70000, v176
	global_load_dword v184, v178, s[28:29] nt
	global_load_dword v185, v178, s[28:29] offset:128 nt
	v_add_u32_e32 v178, 0x71000, v176
	global_load_dword v186, v178, s[28:29] nt
	global_load_dword v187, v178, s[28:29] offset:128 nt
	v_add_u32_e32 v178, 0x72000, v176
	global_load_dword v190, v178, s[28:29] nt
	global_load_dword v191, v178, s[28:29] offset:128 nt
	v_add_u32_e32 v178, 0x73000, v176
	global_load_dword v192, v178, s[28:29] nt
	global_load_dword v193, v178, s[28:29] offset:128 nt
	v_add_u32_e32 v178, 0x78000, v176
	global_load_dword v194, v178, s[28:29] nt
	global_load_dword v195, v178, s[28:29] offset:128 nt
	v_add_u32_e32 v178, 0x79000, v176
	global_load_dword v196, v178, s[28:29] nt
	global_load_dword v197, v178, s[28:29] offset:128 nt
	v_add_u32_e32 v178, 0x7a000, v176
	global_load_dword v198, v178, s[28:29] nt
	global_load_dword v199, v178, s[28:29] offset:128 nt
	v_add_u32_e32 v178, 0x7b000, v176
	global_load_dword v200, v178, s[28:29] nt
	global_load_dword v201, v178, s[28:29] offset:128 nt
	s_waitcnt vmcnt(63)
; DI void phase_resid(const Params& p, const bfu* A, int lda, const bfu* Bt, int K, char* smem) {
;     ...
;     EPI_BEGINM(acc, 4)
;       float* xp = p.out + (size_t)row * 1024 + col;
;       float nv = *xp + v; *xp = nv; p.xb[(size_t)row * 1024 + col] = f2bf(nv);
;     EPI_END
	v_add_u32_e32 v178, 0x40000, v176
	v_add_u32_e32 v179, 0x20000, v177
	v_add_f32_e32 v48, v48, v128
	global_store_dword v178, v48, s[28:29]
	v_cvt_pk_bf16_f32 v128, v48, v48
	global_store_short v179, v128, s[36:37]
	v_add_f32_e32 v32, v32, v129
	global_store_dword v178, v32, s[28:29] offset:128
	v_cvt_pk_bf16_f32 v129, v32, v32
	global_store_short v179, v129, s[36:37] offset:64
	v_add_u32_e32 v178, 0x41000, v176
	v_add_u32_e32 v179, 0x20800, v177
	v_add_f32_e32 v49, v49, v130
	global_store_dword v178, v49, s[28:29]
	v_cvt_pk_bf16_f32 v130, v49, v49
	global_store_short v179, v130, s[36:37]
	v_add_f32_e32 v33, v33, v131
	global_store_dword v178, v33, s[28:29] offset:128
	v_cvt_pk_bf16_f32 v131, v33, v33
	global_store_short v179, v131, s[36:37] offset:64
	v_add_u32_e32 v178, 0x42000, v176
	v_add_u32_e32 v179, 0x21000, v177
	v_add_f32_e32 v50, v50, v132
	global_store_dword v178, v50, s[28:29]
	v_cvt_pk_bf16_f32 v132, v50, v50
	global_store_short v179, v132, s[36:37]
	v_add_f32_e32 v34, v34, v133
	global_store_dword v178, v34, s[28:29] offset:128
	v_cvt_pk_bf16_f32 v133, v34, v34
	global_store_short v179, v133, s[36:37] offset:64
	v_add_u32_e32 v178, 0x43000, v176
	v_add_u32_e32 v179, 0x21800, v177
	v_add_f32_e32 v51, v51, v134
	global_store_dword v178, v51, s[28:29]
	v_cvt_pk_bf16_f32 v134, v51, v51
	global_store_short v179, v134, s[36:37]
	v_add_f32_e32 v35, v35, v135
	global_store_dword v178, v35, s[28:29] offset:128
	v_cvt_pk_bf16_f32 v135, v35, v35
	global_store_short v179, v135, s[36:37] offset:64
	v_add_u32_e32 v178, 0x48000, v176
	v_add_u32_e32 v179, 0x24000, v177
	v_add_f32_e32 v52, v52, v136
	global_store_dword v178, v52, s[28:29]
	v_cvt_pk_bf16_f32 v136, v52, v52
	global_store_short v179, v136, s[36:37]
	v_add_f32_e32 v36, v36, v137
	global_store_dword v178, v36, s[28:29] offset:128
	v_cvt_pk_bf16_f32 v137, v36, v36
	global_store_short v179, v137, s[36:37] offset:64
	v_add_u32_e32 v178, 0x49000, v176
	v_add_u32_e32 v179, 0x24800, v177
	v_add_f32_e32 v53, v53, v138
	global_store_dword v178, v53, s[28:29]
	v_cvt_pk_bf16_f32 v138, v53, v53
	global_store_short v179, v138, s[36:37]
	v_add_f32_e32 v37, v37, v139
	global_store_dword v178, v37, s[28:29] offset:128
	v_cvt_pk_bf16_f32 v139, v37, v37
	global_store_short v179, v139, s[36:37] offset:64
	v_add_u32_e32 v178, 0x4a000, v176
	v_add_u32_e32 v179, 0x25000, v177
	v_add_f32_e32 v54, v54, v140
	global_store_dword v178, v54, s[28:29]
	v_cvt_pk_bf16_f32 v140, v54, v54
	global_store_short v179, v140, s[36:37]
	v_add_f32_e32 v38, v38, v141
	global_store_dword v178, v38, s[28:29] offset:128
	v_cvt_pk_bf16_f32 v141, v38, v38
	global_store_short v179, v141, s[36:37] offset:64
	v_add_u32_e32 v178, 0x4b000, v176
	v_add_u32_e32 v179, 0x25800, v177
	v_add_f32_e32 v55, v55, v142
	global_store_dword v178, v55, s[28:29]
	v_cvt_pk_bf16_f32 v142, v55, v55
	global_store_short v179, v142, s[36:37]
	v_add_f32_e32 v39, v39, v143
	global_store_dword v178, v39, s[28:29] offset:128
	v_cvt_pk_bf16_f32 v143, v39, v39
	global_store_short v179, v143, s[36:37] offset:64
	v_add_u32_e32 v178, 0x50000, v176
	v_add_u32_e32 v179, 0x28000, v177
	v_add_f32_e32 v56, v56, v144
	global_store_dword v178, v56, s[28:29]
	v_cvt_pk_bf16_f32 v144, v56, v56
	global_store_short v179, v144, s[36:37]
	v_add_f32_e32 v40, v40, v145
	global_store_dword v178, v40, s[28:29] offset:128
	v_cvt_pk_bf16_f32 v145, v40, v40
	global_store_short v179, v145, s[36:37] offset:64
	v_add_u32_e32 v178, 0x51000, v176
	v_add_u32_e32 v179, 0x28800, v177
	v_add_f32_e32 v57, v57, v146
	global_store_dword v178, v57, s[28:29]
	v_cvt_pk_bf16_f32 v146, v57, v57
	global_store_short v179, v146, s[36:37]
	v_add_f32_e32 v41, v41, v147
	global_store_dword v178, v41, s[28:29] offset:128
	v_cvt_pk_bf16_f32 v147, v41, v41
	global_store_short v179, v147, s[36:37] offset:64
	v_add_u32_e32 v178, 0x52000, v176
	v_add_u32_e32 v179, 0x29000, v177
	v_add_f32_e32 v58, v58, v148
	global_store_dword v178, v58, s[28:29]
	v_cvt_pk_bf16_f32 v148, v58, v58
	global_store_short v179, v148, s[36:37]
	v_add_f32_e32 v42, v42, v149
	global_store_dword v178, v42, s[28:29] offset:128
	v_cvt_pk_bf16_f32 v149, v42, v42
	global_store_short v179, v149, s[36:37] offset:64
	v_add_u32_e32 v178, 0x53000, v176
	v_add_u32_e32 v179, 0x29800, v177
	v_add_f32_e32 v59, v59, v150
	global_store_dword v178, v59, s[28:29]
	v_cvt_pk_bf16_f32 v150, v59, v59
	global_store_short v179, v150, s[36:37]
	v_add_f32_e32 v43, v43, v151
	global_store_dword v178, v43, s[28:29] offset:128
	v_cvt_pk_bf16_f32 v151, v43, v43
	global_store_short v179, v151, s[36:37] offset:64
	v_add_u32_e32 v178, 0x58000, v176
	v_add_u32_e32 v179, 0x2c000, v177
	v_add_f32_e32 v60, v60, v152
	global_store_dword v178, v60, s[28:29]
	v_cvt_pk_bf16_f32 v152, v60, v60
	global_store_short v179, v152, s[36:37]
	v_add_f32_e32 v44, v44, v153
	global_store_dword v178, v44, s[28:29] offset:128
	v_cvt_pk_bf16_f32 v153, v44, v44
	global_store_short v179, v153, s[36:37] offset:64
	v_add_u32_e32 v178, 0x59000, v176
	v_add_u32_e32 v179, 0x2c800, v177
	v_add_f32_e32 v61, v61, v154
	global_store_dword v178, v61, s[28:29]
	v_cvt_pk_bf16_f32 v154, v61, v61
	global_store_short v179, v154, s[36:37]
	v_add_f32_e32 v45, v45, v155
	global_store_dword v178, v45, s[28:29] offset:128
	v_cvt_pk_bf16_f32 v155, v45, v45
	global_store_short v179, v155, s[36:37] offset:64
	v_add_u32_e32 v178, 0x5a000, v176
	v_add_u32_e32 v179, 0x2d000, v177
	v_add_f32_e32 v62, v62, v156
	global_store_dword v178, v62, s[28:29]
	v_cvt_pk_bf16_f32 v156, v62, v62
	global_store_short v179, v156, s[36:37]
	v_add_f32_e32 v46, v46, v157
	global_store_dword v178, v46, s[28:29] offset:128
	v_cvt_pk_bf16_f32 v157, v46, v46
	global_store_short v179, v157, s[36:37] offset:64
	v_add_u32_e32 v178, 0x5b000, v176
	v_add_u32_e32 v179, 0x2d800, v177
	v_add_f32_e32 v63, v63, v158
	global_store_dword v178, v63, s[28:29]
	v_cvt_pk_bf16_f32 v158, v63, v63
	global_store_short v179, v158, s[36:37]
	v_add_f32_e32 v47, v47, v159
	global_store_dword v178, v47, s[28:29] offset:128
	v_cvt_pk_bf16_f32 v159, v47, v47
	global_store_short v179, v159, s[36:37] offset:64
	s_waitcnt vmcnt(63)
; #define ZERO_ACCM(a, MT) _Pragma("unroll") for (int _m = 0; _m < MT; ++_m) _Pragma("unroll") for (int _n = 0; _n < 2; ++_n) _Pragma("unroll") for (int _i = 0; _i < 16; ++_i) a[_m][_n][_i] = 0.f;
; DI void phase_resid(const Params& p, const bfu* A, int lda, const bfu* Bt, int K, char* smem) {
;     ...
;   for (int id = blockIdx.x; id < 64 * 8; id += gridDim.x) {
;     int tm, tn; map_tile(id, 8, tm, tn);
;     const int m0 = tm * 256, n0 = tn * 128;
;     f32x16 acc[4][2]; ZERO_ACCM(acc, 4)
;     gemm_core<false, false, 4>(A, lda, Bt, K, K, m0, n0, acc, smem);
;     EPI_BEGINM(acc, 4)
;       float* xp = p.out + (size_t)row * 1024 + col;
;       float nv = *xp + v; *xp = nv; p.xb[(size_t)row * 1024 + col] = f2bf(nv);
;     EPI_END
;   }
	v_add_u32_e32 v178, 0x60000, v176
	v_add_u32_e32 v179, 0x30000, v177
	v_add_f32_e32 v16, v16, v160
	global_store_dword v178, v16, s[28:29]
	v_cvt_pk_bf16_f32 v160, v16, v16
	global_store_short v179, v160, s[36:37]
	v_add_f32_e32 v0, v0, v161
	global_store_dword v178, v0, s[28:29] offset:128
	v_cvt_pk_bf16_f32 v161, v0, v0
	global_store_short v179, v161, s[36:37] offset:64
	v_add_u32_e32 v178, 0x61000, v176
	v_add_u32_e32 v179, 0x30800, v177
	v_add_f32_e32 v17, v17, v162
	global_store_dword v178, v17, s[28:29]
	v_cvt_pk_bf16_f32 v162, v17, v17
	global_store_short v179, v162, s[36:37]
	v_add_f32_e32 v1, v1, v163
	global_store_dword v178, v1, s[28:29] offset:128
	v_cvt_pk_bf16_f32 v163, v1, v1
	global_store_short v179, v163, s[36:37] offset:64
	v_add_u32_e32 v178, 0x62000, v176
	v_add_u32_e32 v179, 0x31000, v177
	v_add_f32_e32 v18, v18, v164
	global_store_dword v178, v18, s[28:29]
	v_cvt_pk_bf16_f32 v164, v18, v18
	global_store_short v179, v164, s[36:37]
	v_add_f32_e32 v2, v2, v165
	global_store_dword v178, v2, s[28:29] offset:128
	v_cvt_pk_bf16_f32 v165, v2, v2
	global_store_short v179, v165, s[36:37] offset:64
	v_add_u32_e32 v178, 0x63000, v176
	v_add_u32_e32 v179, 0x31800, v177
	v_add_f32_e32 v19, v19, v166
	global_store_dword v178, v19, s[28:29]
	v_cvt_pk_bf16_f32 v166, v19, v19
	global_store_short v179, v166, s[36:37]
	v_add_f32_e32 v3, v3, v167
	global_store_dword v178, v3, s[28:29] offset:128
	v_cvt_pk_bf16_f32 v167, v3, v3
	global_store_short v179, v167, s[36:37] offset:64
	v_add_u32_e32 v178, 0x68000, v176
	v_add_u32_e32 v179, 0x34000, v177
	v_add_f32_e32 v20, v20, v168
	global_store_dword v178, v20, s[28:29]
	v_cvt_pk_bf16_f32 v168, v20, v20
	global_store_short v179, v168, s[36:37]
	v_add_f32_e32 v4, v4, v169
	global_store_dword v178, v4, s[28:29] offset:128
	v_cvt_pk_bf16_f32 v169, v4, v4
	global_store_short v179, v169, s[36:37] offset:64
	v_add_u32_e32 v178, 0x69000, v176
	v_add_u32_e32 v179, 0x34800, v177
	v_add_f32_e32 v21, v21, v170
	global_store_dword v178, v21, s[28:29]
	v_cvt_pk_bf16_f32 v170, v21, v21
	global_store_short v179, v170, s[36:37]
	v_add_f32_e32 v5, v5, v171
	global_store_dword v178, v5, s[28:29] offset:128
	v_cvt_pk_bf16_f32 v171, v5, v5
	global_store_short v179, v171, s[36:37] offset:64
	v_add_u32_e32 v178, 0x6a000, v176
	v_add_u32_e32 v179, 0x35000, v177
	v_add_f32_e32 v22, v22, v172
	global_store_dword v178, v22, s[28:29]
	v_cvt_pk_bf16_f32 v172, v22, v22
	global_store_short v179, v172, s[36:37]
	v_add_f32_e32 v6, v6, v173
	global_store_dword v178, v6, s[28:29] offset:128
	v_cvt_pk_bf16_f32 v173, v6, v6
	global_store_short v179, v173, s[36:37] offset:64
	v_add_u32_e32 v178, 0x6b000, v176
	v_add_u32_e32 v179, 0x35800, v177
	v_add_f32_e32 v23, v23, v174
	global_store_dword v178, v23, s[28:29]
	v_cvt_pk_bf16_f32 v174, v23, v23
	global_store_short v179, v174, s[36:37]
	v_add_f32_e32 v7, v7, v175
	global_store_dword v178, v7, s[28:29] offset:128
	v_cvt_pk_bf16_f32 v175, v7, v7
	global_store_short v179, v175, s[36:37] offset:64
	v_add_u32_e32 v178, 0x70000, v176
	v_add_u32_e32 v179, 0x38000, v177
	v_add_f32_e32 v24, v24, v184
	global_store_dword v178, v24, s[28:29]
	v_cvt_pk_bf16_f32 v184, v24, v24
	global_store_short v179, v184, s[36:37]
	v_add_f32_e32 v8, v8, v185
	global_store_dword v178, v8, s[28:29] offset:128
	v_cvt_pk_bf16_f32 v185, v8, v8
	global_store_short v179, v185, s[36:37] offset:64
	v_add_u32_e32 v178, 0x71000, v176
	v_add_u32_e32 v179, 0x38800, v177
	v_add_f32_e32 v25, v25, v186
	global_store_dword v178, v25, s[28:29]
	v_cvt_pk_bf16_f32 v186, v25, v25
	global_store_short v179, v186, s[36:37]
	v_add_f32_e32 v9, v9, v187
	global_store_dword v178, v9, s[28:29] offset:128
	v_cvt_pk_bf16_f32 v187, v9, v9
	global_store_short v179, v187, s[36:37] offset:64
	v_add_u32_e32 v178, 0x72000, v176
	v_add_u32_e32 v179, 0x39000, v177
	v_add_f32_e32 v26, v26, v190
	global_store_dword v178, v26, s[28:29]
	v_cvt_pk_bf16_f32 v190, v26, v26
	global_store_short v179, v190, s[36:37]
	v_add_f32_e32 v10, v10, v191
	global_store_dword v178, v10, s[28:29] offset:128
	v_cvt_pk_bf16_f32 v191, v10, v10
	global_store_short v179, v191, s[36:37] offset:64
	v_add_u32_e32 v178, 0x73000, v176
	v_add_u32_e32 v179, 0x39800, v177
	v_add_f32_e32 v27, v27, v192
	global_store_dword v178, v27, s[28:29]
	v_cvt_pk_bf16_f32 v192, v27, v27
	global_store_short v179, v192, s[36:37]
	v_add_f32_e32 v11, v11, v193
	global_store_dword v178, v11, s[28:29] offset:128
	v_cvt_pk_bf16_f32 v193, v11, v11
	global_store_short v179, v193, s[36:37] offset:64
	v_add_u32_e32 v178, 0x78000, v176
	v_add_u32_e32 v179, 0x3c000, v177
	v_add_f32_e32 v28, v28, v194
	global_store_dword v178, v28, s[28:29]
	v_cvt_pk_bf16_f32 v194, v28, v28
	global_store_short v179, v194, s[36:37]
	v_add_f32_e32 v12, v12, v195
	global_store_dword v178, v12, s[28:29] offset:128
	v_cvt_pk_bf16_f32 v195, v12, v12
	global_store_short v179, v195, s[36:37] offset:64
	v_add_u32_e32 v178, 0x79000, v176
	v_add_u32_e32 v179, 0x3c800, v177
	v_add_f32_e32 v29, v29, v196
	global_store_dword v178, v29, s[28:29]
	v_cvt_pk_bf16_f32 v196, v29, v29
	global_store_short v179, v196, s[36:37]
	v_add_f32_e32 v13, v13, v197
	global_store_dword v178, v13, s[28:29] offset:128
	v_cvt_pk_bf16_f32 v197, v13, v13
	global_store_short v179, v197, s[36:37] offset:64
	v_add_u32_e32 v178, 0x7a000, v176
	v_add_u32_e32 v179, 0x3d000, v177
	v_add_f32_e32 v30, v30, v198
	global_store_dword v178, v30, s[28:29]
	v_cvt_pk_bf16_f32 v198, v30, v30
	global_store_short v179, v198, s[36:37]
	v_add_f32_e32 v14, v14, v199
	global_store_dword v178, v14, s[28:29] offset:128
	v_cvt_pk_bf16_f32 v199, v14, v14
	global_store_short v179, v199, s[36:37] offset:64
	v_add_u32_e32 v178, 0x7b000, v176
	v_add_u32_e32 v179, 0x3d800, v177
	v_add_f32_e32 v31, v31, v200
	global_store_dword v178, v31, s[28:29]
	v_cvt_pk_bf16_f32 v200, v31, v31
	global_store_short v179, v200, s[36:37]
	v_add_f32_e32 v15, v15, v201
	global_store_dword v178, v15, s[28:29] offset:128
	v_cvt_pk_bf16_f32 v201, v15, v15
	global_store_short v179, v201, s[36:37] offset:64
	s_load_dword s3, s[4:5], 0x0
	s_waitcnt lgkmcnt(0)
	s_add_i32 s2, s3, s2
	s_cmpk_gt_i32 s2, 0x1ff
	s_cbranch_scc0 .LBB0_127

; DI float bf2f(bfu b) { return __uint_as_float(((unsigned)b) << 16); }
; #define EPI_BEGIN(accv) EPI_BEGINM(accv, 2)
; template <bool NORM, bool DEEP, int MTW, int KSEG, class HOOK>
; DI void gemm_core_h(const bfu* __restrict__ A, int lda, const bfu* __restrict__ Bt, int ldb, int K, int m0, int n0,
;                     f32x16 (&acc)[MTW][2], char* smem, HOOK hook) {
;     ...
;   if (DEEP) {
;     for (int kt = 0; kt < nk; kt += 2) {
;       GEMM_STEP(ra0, rb0, kt, 2)
;       GEMM_STEP(ra1, rb1, kt + 1, 2)
;     }
;   } else {
;     for (int kt = 0; kt < nk; ++kt) {
;       GEMM_STEP(ra0, rb0, kt, 1)
;       if (KSEG > 0) { if (((kt + 1) % (KSEG > 0 ? KSEG : 1)) == 0) hook((kt + 1) / (KSEG > 0 ? KSEG : 1) - 1); }
; DI void phase_widen(const Params& p, char* smem) {
;     ...
;     auto flush = [&](int n) {
;       EPI_BEGIN(acc) tot[mt][nt][i] += v * bf2f(p.gates[(size_t)row * 4096 + n * 1024 + col]); acc[mt][nt][i] = 0.f; EPI_END
;     };
.LBB0_137:
	s_waitcnt lgkmcnt(0)
	s_barrier
	s_waitcnt vmcnt(7)
	ds_write_b128 v133, v[68:71]
	s_waitcnt vmcnt(6)
	ds_write_b128 v133, v[64:67] offset:4608
	s_waitcnt vmcnt(5)
	ds_write_b128 v133, v[72:75] offset:9216
	s_waitcnt vmcnt(4)
	ds_write_b128 v133, v[76:79] offset:13824
	s_waitcnt vmcnt(3)
	ds_write_b128 v133, v[84:87] offset:18432
	s_waitcnt vmcnt(2)
	ds_write_b128 v133, v[80:83] offset:23040
	s_waitcnt vmcnt(1)
	ds_write_b128 v133, v[88:91] offset:27648
	s_waitcnt vmcnt(0)
	ds_write_b128 v133, v[92:95] offset:32256
	s_waitcnt lgkmcnt(0)
	s_barrier
	ds_read_b128 v[64:67], v213
	ds_read_b128 v[68:71], v129 offset:18432
	ds_read_b128 v[72:75], v129 offset:18464
	ds_read_b128 v[76:79], v213 offset:32
	ds_read_b128 v[80:83], v129 offset:23040
	ds_read_b128 v[84:87], v129 offset:23072
	s_waitcnt lgkmcnt(4)
	v_mfma_f32_32x32x16_bf16 v[48:63], v[64:67], v[68:71], v[48:63]
	s_cmpk_lg_i32 s2, 0x1e00
	s_cselect_b32 s7, s6, 0x3c0
	v_add_u32_e32 v188, s7, v128
	v_readlane_b32 s16, v253, 48
	v_readlane_b32 s20, v253, 52
	v_readlane_b32 s21, v253, 53
	v_readlane_b32 s17, v253, 49
	s_waitcnt lgkmcnt(1)
	v_mfma_f32_32x32x16_bf16 v[32:47], v[64:67], v[80:83], v[32:47]
	ds_read_b128 v[64:67], v213 offset:4608
	ds_read_b128 v[88:91], v213 offset:4640
	v_readlane_b32 s18, v253, 50
	v_readlane_b32 s19, v253, 51
	v_readlane_b32 s22, v253, 54
	v_readlane_b32 s23, v253, 55
	v_readlane_b32 s24, v253, 56
	v_readlane_b32 s25, v253, 57
	s_waitcnt lgkmcnt(1)
	v_mfma_f32_32x32x16_bf16 v[16:31], v[64:67], v[68:71], v[16:31]
	v_readlane_b32 s26, v253, 58
	v_readlane_b32 s27, v253, 59
	v_readlane_b32 s28, v253, 60
	v_readlane_b32 s29, v253, 61
	v_readlane_b32 s30, v253, 62
	v_readlane_b32 s31, v253, 63
	v_mfma_f32_32x32x16_bf16 v[0:15], v[64:67], v[80:83], v[0:15]
	v_mfma_f32_32x32x16_bf16 v[48:63], v[76:79], v[72:75], v[48:63]
	v_mfma_f32_32x32x16_bf16 v[32:47], v[76:79], v[84:87], v[32:47]
	s_waitcnt lgkmcnt(0)
	v_mfma_f32_32x32x16_bf16 v[16:31], v[88:91], v[72:75], v[16:31]
	v_mfma_f32_32x32x16_bf16 v[0:15], v[88:91], v[84:87], v[0:15]
	ds_read_b128 v[64:67], v213 offset:64
	ds_read_b128 v[68:71], v129 offset:18496
	ds_read_b128 v[88:91], v129 offset:18528
	ds_read_b128 v[80:83], v213 offset:96
	ds_read_b128 v[72:75], v129 offset:23104
	ds_read_b128 v[184:187], v129 offset:23136
	v_mov_b32_e32 v87, v189
	s_waitcnt lgkmcnt(4)
	v_mfma_f32_32x32x16_bf16 v[48:63], v[64:67], v[68:71], v[48:63]
	s_waitcnt lgkmcnt(1)
	v_mfma_f32_32x32x16_bf16 v[32:47], v[64:67], v[72:75], v[32:47]
	ds_read_b128 v[64:67], v213 offset:4672
	ds_read_b128 v[190:193], v213 offset:4704
	s_waitcnt lgkmcnt(1)
	v_mfma_f32_32x32x16_bf16 v[16:31], v[64:67], v[68:71], v[16:31]
	v_add_u32_e32 v70, 0x8000, v188
	v_mov_b32_e32 v71, v189
	v_lshl_add_u64 v[68:69], v[188:189], 1, s[74:75]
	v_lshl_add_u64 v[76:77], v[70:71], 1, s[74:75]
	v_mfma_f32_32x32x16_bf16 v[0:15], v[64:67], v[72:75], v[0:15]
	v_add_u32_e32 v72, 0x10000, v188
	v_add_u32_e32 v188, 0x18000, v188
	global_load_dwordx4 v[68:71], v[68:69], off
	s_nop 0
	global_load_dwordx4 v[64:67], v[76:77], off
	v_lshl_add_u64 v[76:77], v[188:189], 1, s[74:75]
	v_add_u32_e32 v188, s7, v132
	v_mov_b32_e32 v73, v189
	v_add_u32_e32 v86, 0x8000, v188
	v_lshl_add_u64 v[72:73], v[72:73], 1, s[74:75]
	v_lshl_add_u64 v[84:85], v[188:189], 1, s[20:21]
	v_lshl_add_u64 v[92:93], v[86:87], 1, s[20:21]
	v_mfma_f32_32x32x16_bf16 v[48:63], v[80:83], v[88:91], v[48:63]
	global_load_dwordx4 v[72:75], v[72:73], off
	s_nop 0
	global_load_dwordx4 v[76:79], v[76:77], off
	s_and_b32 s7, s5, 3
	s_cmp_lg_u32 s7, 0
	v_mfma_f32_32x32x16_bf16 v[32:47], v[80:83], v[184:187], v[32:47]
	global_load_dwordx4 v[84:87], v[84:85], off
	s_nop 0
	global_load_dwordx4 v[80:83], v[92:93], off
	v_add_u32_e32 v92, 0x10000, v188
	v_mov_b32_e32 v93, v189
	v_add_u32_e32 v188, 0x18000, v188
	v_lshl_add_u64 v[92:93], v[92:93], 1, s[20:21]
	v_lshl_add_u64 v[94:95], v[188:189], 1, s[20:21]
	s_waitcnt lgkmcnt(0)
	v_mfma_f32_32x32x16_bf16 v[16:31], v[190:193], v[88:91], v[16:31]
	global_load_dwordx4 v[88:91], v[92:93], off
	s_nop 0
	global_load_dwordx4 v[92:95], v[94:95], off
	v_mfma_f32_32x32x16_bf16 v[0:15], v[190:193], v[184:187], v[0:15]
	s_cbranch_scc1 .LBB0_136
	v_lshlrev_b32_e32 v200, 13, v96
	v_lshl_add_u32 v200, v150, 1, v200
	s_add_u32 s8, s2, 0xfffffa00
	s_add_u32 s8, s70, s8
	s_addc_u32 s9, s71, 0
	global_load_ushort v216, v200, s[8:9] nt
	global_load_ushort v217, v200, s[8:9] offset:64 nt
	v_add_u32_e32 v199, 0x2000, v200
	global_load_ushort v218, v199, s[8:9] nt
	global_load_ushort v219, v199, s[8:9] offset:64 nt
	v_add_u32_e32 v199, 0x4000, v200
	global_load_ushort v220, v199, s[8:9] nt
	global_load_ushort v221, v199, s[8:9] offset:64 nt
	v_add_u32_e32 v199, 0x6000, v200
	global_load_ushort v223, v199, s[8:9] nt
	global_load_ushort v232, v199, s[8:9] offset:64 nt
	v_add_u32_e32 v199, 0x10000, v200
	global_load_ushort v233, v199, s[8:9] nt
	global_load_ushort v234, v199, s[8:9] offset:64 nt
	v_add_u32_e32 v199, 0x12000, v200
	global_load_ushort v235, v199, s[8:9] nt
	global_load_ushort v237, v199, s[8:9] offset:64 nt
	v_add_u32_e32 v199, 0x14000, v200
	global_load_ushort v238, v199, s[8:9] nt
	global_load_ushort v239, v199, s[8:9] offset:64 nt
	v_add_u32_e32 v199, 0x16000, v200
	global_load_ushort v240, v199, s[8:9] nt
	global_load_ushort v241, v199, s[8:9] offset:64 nt
	v_add_u32_e32 v199, 0x20000, v200
	global_load_ushort v242, v199, s[8:9] nt
	global_load_ushort v243, v199, s[8:9] offset:64 nt
	v_add_u32_e32 v199, 0x22000, v200
	global_load_ushort v244, v199, s[8:9] nt
	global_load_ushort v245, v199, s[8:9] offset:64 nt
	v_add_u32_e32 v199, 0x24000, v200
	global_load_ushort v246, v199, s[8:9] nt
; DI float bf2f(bfu b) { return __uint_as_float(((unsigned)b) << 16); }
; #define EPI_BEGIN(accv) EPI_BEGINM(accv, 2)
; DI void phase_widen(const Params& p, char* smem) {
;     ...
;     auto flush = [&](int n) {
;       EPI_BEGIN(acc) tot[mt][nt][i] += v * bf2f(p.gates[(size_t)row * 4096 + n * 1024 + col]); acc[mt][nt][i] = 0.f; EPI_END
;     };
	global_load_ushort v247, v199, s[8:9] offset:64 nt
	v_add_u32_e32 v199, 0x26000, v200
	global_load_ushort v248, v199, s[8:9] nt
	global_load_ushort v249, v199, s[8:9] offset:64 nt
	v_add_u32_e32 v199, 0x30000, v200
	global_load_ushort v250, v199, s[8:9] nt
	global_load_ushort v251, v199, s[8:9] offset:64 nt
	v_add_u32_e32 v199, 0x32000, v200
	global_load_ushort v252, v199, s[8:9] nt
	global_load_ushort v194, v199, s[8:9] offset:64 nt
	v_add_u32_e32 v199, 0x34000, v200
	global_load_ushort v195, v199, s[8:9] nt
	global_load_ushort v196, v199, s[8:9] offset:64 nt
	v_add_u32_e32 v199, 0x36000, v200
	global_load_ushort v197, v199, s[8:9] nt
	global_load_ushort v198, v199, s[8:9] offset:64 nt
	v_add_u32_e32 v199, 0x40000, v200
	global_load_ushort v201, v199, s[8:9] nt
	global_load_ushort v202, v199, s[8:9] offset:64 nt
	v_add_u32_e32 v199, 0x42000, v200
	global_load_ushort v203, v199, s[8:9] nt
	global_load_ushort v214, v199, s[8:9] offset:64 nt
	v_add_u32_e32 v199, 0x44000, v200
	global_load_ushort v215, v199, s[8:9] nt
	global_load_ushort v184, v199, s[8:9] offset:64 nt
	v_add_u32_e32 v199, 0x46000, v200
	global_load_ushort v185, v199, s[8:9] nt
	global_load_ushort v186, v199, s[8:9] offset:64 nt
	v_add_u32_e32 v199, 0x50000, v200
	global_load_ushort v187, v199, s[8:9] nt
	global_load_ushort v190, v199, s[8:9] offset:64 nt
	v_add_u32_e32 v199, 0x52000, v200
	global_load_ushort v191, v199, s[8:9] nt
	global_load_ushort v192, v199, s[8:9] offset:64 nt
	v_add_u32_e32 v199, 0x54000, v200
	global_load_ushort v193, v199, s[8:9] nt
	s_waitcnt vmcnt(13)
	v_lshlrev_b32_e32 v216, 16, v216
	v_fmac_f32_e32 v182, v48, v216
	v_lshlrev_b32_e32 v217, 16, v217
	v_fmac_f32_e32 v148, v32, v217
	v_lshlrev_b32_e32 v218, 16, v218
	v_fmac_f32_e32 v183, v49, v218
	v_lshlrev_b32_e32 v219, 16, v219
	v_fmac_f32_e32 v149, v33, v219
	v_lshlrev_b32_e32 v220, 16, v220
	v_fmac_f32_e32 v180, v50, v220
	v_lshlrev_b32_e32 v221, 16, v221
	v_fmac_f32_e32 v146, v34, v221
	v_lshlrev_b32_e32 v223, 16, v223
	v_fmac_f32_e32 v181, v51, v223
	v_lshlrev_b32_e32 v232, 16, v232
	v_fmac_f32_e32 v147, v35, v232
	v_lshlrev_b32_e32 v233, 16, v233
	v_fmac_f32_e32 v178, v52, v233
	v_lshlrev_b32_e32 v234, 16, v234
	v_fmac_f32_e32 v144, v36, v234
	v_lshlrev_b32_e32 v235, 16, v235
	v_fmac_f32_e32 v179, v53, v235
	v_lshlrev_b32_e32 v237, 16, v237
	v_fmac_f32_e32 v145, v37, v237
	v_lshlrev_b32_e32 v238, 16, v238
	v_fmac_f32_e32 v176, v54, v238
	v_lshlrev_b32_e32 v239, 16, v239
	v_fmac_f32_e32 v142, v38, v239
	v_lshlrev_b32_e32 v240, 16, v240
	v_fmac_f32_e32 v177, v55, v240
	v_lshlrev_b32_e32 v241, 16, v241
	v_fmac_f32_e32 v143, v39, v241
	v_lshlrev_b32_e32 v242, 16, v242
	v_fmac_f32_e32 v170, v56, v242
	v_lshlrev_b32_e32 v243, 16, v243
	v_fmac_f32_e32 v140, v40, v243
	v_lshlrev_b32_e32 v244, 16, v244
	v_fmac_f32_e32 v171, v57, v244
	v_lshlrev_b32_e32 v245, 16, v245
	v_fmac_f32_e32 v141, v41, v245
	v_lshlrev_b32_e32 v246, 16, v246
	v_fmac_f32_e32 v164, v58, v246
	v_lshlrev_b32_e32 v247, 16, v247
	v_fmac_f32_e32 v138, v42, v247
	v_lshlrev_b32_e32 v248, 16, v248
	v_fmac_f32_e32 v165, v59, v248
	v_lshlrev_b32_e32 v249, 16, v249
	v_fmac_f32_e32 v139, v43, v249
	v_lshlrev_b32_e32 v250, 16, v250
	v_fmac_f32_e32 v158, v60, v250
	v_lshlrev_b32_e32 v251, 16, v251
	v_fmac_f32_e32 v136, v44, v251
	v_lshlrev_b32_e32 v252, 16, v252
	v_fmac_f32_e32 v159, v61, v252
	v_lshlrev_b32_e32 v194, 16, v194
	v_fmac_f32_e32 v137, v45, v194
	v_lshlrev_b32_e32 v195, 16, v195
	v_fmac_f32_e32 v152, v62, v195
	v_lshlrev_b32_e32 v196, 16, v196
	v_fmac_f32_e32 v134, v46, v196
	v_lshlrev_b32_e32 v197, 16, v197
	v_fmac_f32_e32 v153, v63, v197
	v_lshlrev_b32_e32 v198, 16, v198
	v_fmac_f32_e32 v135, v47, v198
	v_add_u32_e32 v199, 0x54000, v200
	global_load_ushort v216, v199, s[8:9] offset:64 nt
	v_add_u32_e32 v199, 0x56000, v200
	global_load_ushort v217, v199, s[8:9] nt
	global_load_ushort v218, v199, s[8:9] offset:64 nt
	v_add_u32_e32 v199, 0x60000, v200
	global_load_ushort v219, v199, s[8:9] nt
	global_load_ushort v220, v199, s[8:9] offset:64 nt
	v_add_u32_e32 v199, 0x62000, v200
	global_load_ushort v221, v199, s[8:9] nt
	global_load_ushort v223, v199, s[8:9] offset:64 nt
	v_add_u32_e32 v199, 0x64000, v200
	global_load_ushort v232, v199, s[8:9] nt
	global_load_ushort v233, v199, s[8:9] offset:64 nt
	v_add_u32_e32 v199, 0x66000, v200
	global_load_ushort v234, v199, s[8:9] nt
	global_load_ushort v235, v199, s[8:9] offset:64 nt
	v_add_u32_e32 v199, 0x70000, v200
	global_load_ushort v237, v199, s[8:9] nt
	global_load_ushort v238, v199, s[8:9] offset:64 nt
	v_add_u32_e32 v199, 0x72000, v200
	global_load_ushort v239, v199, s[8:9] nt
	global_load_ushort v240, v199, s[8:9] offset:64 nt
	v_add_u32_e32 v199, 0x74000, v200
	global_load_ushort v241, v199, s[8:9] nt
	global_load_ushort v242, v199, s[8:9] offset:64 nt
	v_add_u32_e32 v199, 0x76000, v200
	global_load_ushort v243, v199, s[8:9] nt
	global_load_ushort v244, v199, s[8:9] offset:64 nt
	s_waitcnt vmcnt(19)
; DI float bf2f(bfu b) { return __uint_as_float(((unsigned)b) << 16); }
; #define EPI_BEGIN(accv) EPI_BEGINM(accv, 2)
; DI void phase_widen(const Params& p, char* smem) {
;     ...
;     auto flush = [&](int n) {
;       EPI_BEGIN(acc) tot[mt][nt][i] += v * bf2f(p.gates[(size_t)row * 4096 + n * 1024 + col]); acc[mt][nt][i] = 0.f; EPI_END
;     };
	v_lshlrev_b32_e32 v201, 16, v201
	v_fmac_f32_e32 v130, v16, v201
	v_lshlrev_b32_e32 v202, 16, v202
	v_fmac_f32_e32 v104, v0, v202
	v_lshlrev_b32_e32 v203, 16, v203
	v_fmac_f32_e32 v131, v17, v203
	v_lshlrev_b32_e32 v214, 16, v214
	v_fmac_f32_e32 v105, v1, v214
	v_lshlrev_b32_e32 v215, 16, v215
	v_fmac_f32_e32 v126, v18, v215
	v_lshlrev_b32_e32 v184, 16, v184
	v_fmac_f32_e32 v112, v2, v184
	v_lshlrev_b32_e32 v185, 16, v185
	v_fmac_f32_e32 v127, v19, v185
	v_lshlrev_b32_e32 v186, 16, v186
	v_fmac_f32_e32 v113, v3, v186
	v_lshlrev_b32_e32 v187, 16, v187
	v_fmac_f32_e32 v124, v20, v187
	v_lshlrev_b32_e32 v190, 16, v190
	v_fmac_f32_e32 v110, v4, v190
	v_lshlrev_b32_e32 v191, 16, v191
	v_fmac_f32_e32 v125, v21, v191
	v_lshlrev_b32_e32 v192, 16, v192
	v_fmac_f32_e32 v111, v5, v192
	v_lshlrev_b32_e32 v193, 16, v193
	v_fmac_f32_e32 v122, v22, v193
	s_waitcnt vmcnt(0)
	v_lshlrev_b32_e32 v216, 16, v216
	v_fmac_f32_e32 v108, v6, v216
	v_lshlrev_b32_e32 v217, 16, v217
	v_fmac_f32_e32 v123, v23, v217
	v_lshlrev_b32_e32 v218, 16, v218
	v_fmac_f32_e32 v109, v7, v218
	v_lshlrev_b32_e32 v219, 16, v219
	v_fmac_f32_e32 v120, v24, v219
	v_lshlrev_b32_e32 v220, 16, v220
	v_fmac_f32_e32 v106, v8, v220
	v_lshlrev_b32_e32 v221, 16, v221
	v_fmac_f32_e32 v121, v25, v221
	v_lshlrev_b32_e32 v223, 16, v223
	v_fmac_f32_e32 v107, v9, v223
	v_lshlrev_b32_e32 v232, 16, v232
	v_fmac_f32_e32 v118, v26, v232
	v_lshlrev_b32_e32 v233, 16, v233
	v_fmac_f32_e32 v102, v10, v233
	v_lshlrev_b32_e32 v234, 16, v234
	v_fmac_f32_e32 v119, v27, v234
	v_lshlrev_b32_e32 v235, 16, v235
	v_fmac_f32_e32 v103, v11, v235
	v_lshlrev_b32_e32 v237, 16, v237
	v_fmac_f32_e32 v116, v28, v237
	v_lshlrev_b32_e32 v238, 16, v238
	v_fmac_f32_e32 v100, v12, v238
	v_lshlrev_b32_e32 v239, 16, v239
	v_fmac_f32_e32 v117, v29, v239
	v_lshlrev_b32_e32 v240, 16, v240
	v_fmac_f32_e32 v101, v13, v240
	v_lshlrev_b32_e32 v241, 16, v241
	v_fmac_f32_e32 v114, v30, v241
	v_lshlrev_b32_e32 v242, 16, v242
	v_fmac_f32_e32 v98, v14, v242
	v_lshlrev_b32_e32 v243, 16, v243
	v_fmac_f32_e32 v115, v31, v243
	v_lshlrev_b32_e32 v244, 16, v244
	v_fmac_f32_e32 v99, v15, v244
	v_mov_b32_e32 v0, 0
	v_mov_b32_e32 v1, v0
	v_mov_b32_e32 v2, v0
	v_mov_b32_e32 v3, v0
	v_mov_b32_e32 v4, v0
	v_mov_b32_e32 v5, v0
	v_mov_b32_e32 v6, v0
	v_mov_b32_e32 v7, v0
	v_mov_b32_e32 v8, v0
	v_mov_b32_e32 v9, v0
	v_mov_b32_e32 v10, v0
	v_mov_b32_e32 v11, v0
	v_mov_b32_e32 v12, v0
	v_mov_b32_e32 v13, v0
	v_mov_b32_e32 v14, v0
	v_mov_b32_e32 v15, v0
	v_mov_b32_e32 v16, v0
	v_mov_b32_e32 v17, v0
	v_mov_b32_e32 v18, v0
	v_mov_b32_e32 v19, v0
	v_mov_b32_e32 v20, v0
	v_mov_b32_e32 v21, v0
	v_mov_b32_e32 v22, v0
	v_mov_b32_e32 v23, v0
	v_mov_b32_e32 v24, v0
	v_mov_b32_e32 v25, v0
	v_mov_b32_e32 v26, v0
	v_mov_b32_e32 v27, v0
	v_mov_b32_e32 v28, v0
	v_mov_b32_e32 v29, v0
	v_mov_b32_e32 v30, v0
	v_mov_b32_e32 v31, v0
	v_mov_b32_e32 v32, v0
	v_mov_b32_e32 v33, v0
	v_mov_b32_e32 v34, v0
	v_mov_b32_e32 v35, v0
	v_mov_b32_e32 v36, v0
	v_mov_b32_e32 v37, v0
	v_mov_b32_e32 v38, v0
	v_mov_b32_e32 v39, v0
	v_mov_b32_e32 v40, v0
	v_mov_b32_e32 v41, v0
	v_mov_b32_e32 v42, v0
	v_mov_b32_e32 v43, v0
	v_mov_b32_e32 v44, v0
	v_mov_b32_e32 v45, v0
	v_mov_b32_e32 v46, v0
	v_mov_b32_e32 v47, v0
	v_mov_b32_e32 v48, v0
	v_mov_b32_e32 v49, v0
	v_mov_b32_e32 v50, v0
	v_mov_b32_e32 v51, v0
	v_mov_b32_e32 v52, v0
	v_mov_b32_e32 v53, v0
	v_mov_b32_e32 v54, v0
	v_mov_b32_e32 v55, v0
	v_mov_b32_e32 v56, v0
	v_mov_b32_e32 v57, v0
	v_mov_b32_e32 v58, v0
	v_mov_b32_e32 v59, v0
	v_mov_b32_e32 v60, v0
	v_mov_b32_e32 v61, v0
	v_mov_b32_e32 v62, v0
	v_mov_b32_e32 v63, v0
	s_branch .LBB0_136

; DI int TID() { int t = threadIdx.x; asm volatile("" : "+v"(t)); return t; }
; DI unsigned pk2(float a, float b) { f32x2_t v = {a, b}; bf16x2_t r_ = __builtin_convertvector(v, bf16x2_t); return __builtin_bit_cast(unsigned, r_); }
; template <bool MAP = false>
; DI void conv_tile(const float* __restrict__ src, int N, int K, bfu* __restrict__ dst, const float* __restrict__ g,
;                   int tk, int tn, char* smem, int ldk = -1) {
;   const int LK = ldk < 0 ? K : ldk;
;   float* T = (float*)smem;
;   const int tid = TID();
;   __syncthreads();
; #pragma unroll
;   for (int j = 0; j < 4; ++j) {
;     int k = (tid >> 4) + 16 * j, n4 = (tid & 15) * 4;
;     int gn = tn * 64 + n4, gk = tk * 64 + k;
;     float4 v = make_float4(0.f, 0.f, 0.f, 0.f);
;     const int og = MAP ? in_colmap(gn) : (gn < N ? gn : -1);
;     if (og >= 0) v = *(const float4*)(src + (size_t)gk * N + og);
;     float gg = g ? g[gk] : 1.f;
;     T[k * 65 + n4 + 0] = v.x * gg; T[k * 65 + n4 + 1] = v.y * gg; T[k * 65 + n4 + 2] = v.z * gg; T[k * 65 + n4 + 3] = v.w * gg;
;   }
;   __syncthreads();
; #pragma unroll
;   for (int j = 0; j < 2; ++j) {
;     int n = (tid >> 3) + 32 * j, kc = tid & 7;
;     float e[8];
; #pragma unroll
;     for (int q = 0; q < 8; ++q) e[q] = T[(kc * 8 + q) * 65 + n];
;     u32x4 o = {pk2(e[0], e[1]), pk2(e[2], e[3]), pk2(e[4], e[5]), pk2(e[6], e[7])};
;     *(u32x4*)(dst + (size_t)(tn * 64 + n) * LK + tk * 64 + kc * 8) = o;
;   }
; DI void conv_item_C(const Params& p, int L, int it, char* smem) {
;     ...
;   else if (it < 2880) { int t = it - 2816; conv_tile(p.w_ple_proj + (size_t)L * 256 * D, D, 256, p.wt_pp, nullptr, t / 16, t % 16, smem); }
.LBB0_162:
	s_andn2_b64 vcc, exec, s[2:3]
	s_cbranch_vccnz .LBB0_164
	v_mov_b32_e32 v8, v224
	s_lshl_b32 s3, s6, 2
	s_lshl_b32 s2, s6, 6
	v_lshlrev_b32_e32 v0, 2, v8
	s_and_b32 s3, s3, 0x3fc0
	v_ashrrev_i32_e32 v2, 4, v8
	v_and_b32_e32 v3, 60, v0
	s_and_b32 s2, s2, 0x3c0
	s_add_i32 s96, s3, 0xffffd400
	v_or_b32_e32 v0, s2, v3
	v_add_u32_e32 v6, s96, v2
	v_lshlrev_b32_e32 v188, 2, v0
	v_ashrrev_i32_e32 v7, 31, v6
	v_lshl_add_u64 v[4:5], s[64:65], 0, v[188:189]
	v_lshlrev_b64 v[0:1], 12, v[6:7]
	s_movk_i32 s3, 0x104
	v_lshl_add_u64 v[0:1], v[4:5], 0, v[0:1]
	v_mul_lo_u32 v2, v2, s3
	s_waitcnt vmcnt(63) expcnt(7) lgkmcnt(15)
	s_barrier
	v_lshl_add_u32 v7, v3, 2, v2
	v_add_u32_e32 v210, 16, v6
	v_ashrrev_i32_e32 v211, 31, v210
	v_lshlrev_b64 v[210:211], 12, v[210:211]
	v_lshl_add_u64 v[210:211], v[4:5], 0, v[210:211]
	global_load_dwordx4 v[240:243], v[210:211], off nt
	v_add_u32_e32 v210, 32, v6
	v_ashrrev_i32_e32 v211, 31, v210
	v_lshlrev_b64 v[210:211], 12, v[210:211]
	v_lshl_add_u64 v[210:211], v[4:5], 0, v[210:211]
	global_load_dwordx4 v[244:247], v[210:211], off nt
	v_add_u32_e32 v210, 48, v6
	v_ashrrev_i32_e32 v211, 31, v210
	v_lshlrev_b64 v[210:211], 12, v[210:211]
	v_lshl_add_u64 v[210:211], v[4:5], 0, v[210:211]
	global_load_dwordx4 v[248:251], v[210:211], off nt
	global_load_dwordx4 v[0:3], v[0:1], off
	v_add_u32_e32 v9, 0x1040, v7
	v_ashrrev_i32_e32 v22, 3, v8
	v_readlane_b32 s16, v253, 48
	s_lshl_b64 s[4:5], s[96:97], 1
	v_readlane_b32 s30, v253, 62
	v_readlane_b32 s31, v253, 63
	s_add_u32 s4, s30, s4
	s_addc_u32 s5, s31, s5
	v_readlane_b32 s17, v253, 49
	v_readlane_b32 s18, v253, 50
	v_readlane_b32 s19, v253, 51
	v_readlane_b32 s20, v253, 52
	v_readlane_b32 s21, v253, 53
	v_readlane_b32 s22, v253, 54
	v_readlane_b32 s23, v253, 55
	v_readlane_b32 s24, v253, 56
	v_readlane_b32 s25, v253, 57
	v_readlane_b32 s26, v253, 58
	v_readlane_b32 s27, v253, 59
	v_readlane_b32 s28, v253, 60
	v_readlane_b32 s29, v253, 61
	s_waitcnt vmcnt(0)
	ds_write2_b32 v7, v0, v1 offset1:1
	ds_write2_b32 v7, v2, v3 offset0:2 offset1:3
	v_add_u32_e32 v0, 16, v6
	v_ashrrev_i32_e32 v1, 31, v0
	v_lshlrev_b64 v[0:1], 12, v[0:1]
	v_lshl_add_u64 v[0:1], v[4:5], 0, v[0:1]
	v_mov_b32_e32 v0, v240
	v_mov_b32_e32 v1, v241
	v_mov_b32_e32 v2, v242
	v_mov_b32_e32 v3, v243
	s_waitcnt vmcnt(0)
	ds_write2_b32 v9, v0, v1 offset1:1
	v_add_u32_e32 v0, 0x1048, v7
	ds_write2_b32 v0, v2, v3 offset1:1
	v_add_u32_e32 v0, 32, v6
	v_ashrrev_i32_e32 v1, 31, v0
	v_lshlrev_b64 v[0:1], 12, v[0:1]
	v_lshl_add_u64 v[0:1], v[4:5], 0, v[0:1]
	v_mov_b32_e32 v0, v244
	v_mov_b32_e32 v1, v245
	v_mov_b32_e32 v2, v246
	v_mov_b32_e32 v3, v247
	v_add_u32_e32 v9, 0x2080, v7
	s_waitcnt vmcnt(0)
	ds_write2_b32 v9, v0, v1 offset1:1
	v_add_u32_e32 v0, 0x2088, v7
	ds_write2_b32 v0, v2, v3 offset1:1
	v_add_u32_e32 v0, 48, v6
	v_ashrrev_i32_e32 v1, 31, v0
	v_lshlrev_b64 v[0:1], 12, v[0:1]
	v_lshl_add_u64 v[0:1], v[4:5], 0, v[0:1]
	v_mov_b32_e32 v0, v248
	v_mov_b32_e32 v1, v249
	v_mov_b32_e32 v2, v250
	v_mov_b32_e32 v3, v251
	v_add_u32_e32 v4, 0x30c0, v7
	s_waitcnt vmcnt(0)
	ds_write2_b32 v4, v0, v1 offset1:1
	v_add_u32_e32 v0, 0x30c8, v7
	ds_write2_b32 v0, v2, v3 offset1:1
	v_lshlrev_b32_e32 v0, 3, v8
	v_and_b32_e32 v2, 56, v0
	v_lshlrev_b32_e32 v188, 1, v2
	v_mul_u32_u24_e32 v2, 0x104, v2
	v_lshl_add_u32 v2, v22, 2, v2
	s_waitcnt lgkmcnt(0)
	s_barrier
	ds_read2_b32 v[6:7], v2 offset1:32
	ds_read2_b32 v[8:9], v2 offset0:65 offset1:97
	ds_read2_b32 v[10:11], v2 offset0:130 offset1:162
	ds_read2_b32 v[12:13], v2 offset0:195 offset1:227
	v_add_u32_e32 v2, 0x400, v2
	ds_read2_b32 v[14:15], v2 offset0:4 offset1:36
	ds_read2_b32 v[16:17], v2 offset0:69 offset1:101
	ds_read2_b32 v[18:19], v2 offset0:134 offset1:166
	ds_read2_b32 v[20:21], v2 offset0:199 offset1:231
	v_add_u32_e32 v22, s2, v22
	v_ashrrev_i32_e32 v23, 31, v22
	v_lshl_add_u64 v[0:1], s[4:5], 0, v[188:189]
	v_lshlrev_b64 v[24:25], 9, v[22:23]
	s_waitcnt lgkmcnt(6)
	v_cvt_pk_bf16_f32 v2, v6, v8
	s_waitcnt lgkmcnt(4)
	v_cvt_pk_bf16_f32 v3, v10, v12
	s_waitcnt lgkmcnt(2)
	v_cvt_pk_bf16_f32 v4, v14, v16
	s_waitcnt lgkmcnt(0)
	v_cvt_pk_bf16_f32 v5, v18, v20
	v_lshl_add_u64 v[24:25], v[0:1], 0, v[24:25]
	v_add_u32_e32 v6, 32, v22
	global_store_dwordx4 v[24:25], v[2:5], off
	s_nop 1
	v_cvt_pk_bf16_f32 v2, v7, v9
	v_ashrrev_i32_e32 v7, 31, v6
	v_lshlrev_b64 v[6:7], 9, v[6:7]
	v_cvt_pk_bf16_f32 v3, v11, v13
	v_cvt_pk_bf16_f32 v4, v15, v17
	v_cvt_pk_bf16_f32 v5, v19, v21
	v_lshl_add_u64 v[0:1], v[0:1], 0, v[6:7]
	global_store_dwordx4 v[0:1], v[2:5], off

; template <bool MAP = false>
; DI void conv_tile(const float* __restrict__ src, int N, int K, bfu* __restrict__ dst, const float* __restrict__ g,
;                   int tk, int tn, char* smem, int ldk = -1) {
;     ...
;   for (int j = 0; j < 4; ++j) {
;     int k = (tid >> 4) + 16 * j, n4 = (tid & 15) * 4;
;     int gn = tn * 64 + n4, gk = tk * 64 + k;
;     float4 v = make_float4(0.f, 0.f, 0.f, 0.f);
;     const int og = MAP ? in_colmap(gn) : (gn < N ? gn : -1);
;     if (og >= 0) v = *(const float4*)(src + (size_t)gk * N + og);
;     float gg = g ? g[gk] : 1.f;
;     T[k * 65 + n4 + 0] = v.x * gg; T[k * 65 + n4 + 1] = v.y * gg; T[k * 65 + n4 + 2] = v.z * gg; T[k * 65 + n4 + 3] = v.w * gg;
; DI void conv_item_C(const Params& p, int L, int it, char* smem) {
;     ...
;   else if (it < 2816) { int t = it - 2560; conv_tile(p.w_ple_gate + (size_t)L * D * D, D, D, p.wt_pg, p.norm_ple_g + L * D, t / 16, t % 16, smem); }
.LBB0_165:
	s_andn2_b64 vcc, exec, s[2:3]
	s_cbranch_vccnz .LBB0_175
	s_lshl_b32 s2, s6, 6
	v_mov_b32_e32 v11, v224
	s_and_b32 s4, s2, 0x3c0
	s_lshl_b32 s2, s6, 2
	s_and_b32 s2, s2, 0x3fc0
	v_lshlrev_b32_e32 v0, 2, v11
	v_ashrrev_i32_e32 v13, 4, v11
	v_and_b32_e32 v14, 60, v0
	s_add_i32 s96, s2, 0xffffd800
	v_or_b32_e32 v0, s4, v14
	v_add_u32_e32 v8, s96, v13
	v_lshlrev_b32_e32 v188, 2, v0
	v_ashrrev_i32_e32 v9, 31, v8
	v_lshl_add_u64 v[6:7], s[66:67], 0, v[188:189]
	v_lshlrev_b64 v[0:1], 12, v[8:9]
	v_lshl_add_u64 v[0:1], v[6:7], 0, v[0:1]
	s_waitcnt vmcnt(63) expcnt(7) lgkmcnt(15)
	s_barrier
	v_add_u32_e32 v210, 16, v8
	v_ashrrev_i32_e32 v211, 31, v210
	v_lshlrev_b64 v[210:211], 12, v[210:211]
	v_lshl_add_u64 v[210:211], v[6:7], 0, v[210:211]
	global_load_dwordx4 v[240:243], v[210:211], off nt
	v_add_u32_e32 v210, 32, v8
	v_ashrrev_i32_e32 v211, 31, v210
	v_lshlrev_b64 v[210:211], 12, v[210:211]
	v_lshl_add_u64 v[210:211], v[6:7], 0, v[210:211]
	global_load_dwordx4 v[244:247], v[210:211], off nt
	v_add_u32_e32 v210, 48, v8
	v_ashrrev_i32_e32 v211, 31, v210
	v_lshlrev_b64 v[210:211], 12, v[210:211]
	v_lshl_add_u64 v[210:211], v[6:7], 0, v[210:211]
	global_load_dwordx4 v[248:251], v[210:211], off nt
	global_load_dwordx4 v[0:3], v[0:1], off
	v_readlane_b32 s8, v255, 4
	v_readlane_b32 s9, v255, 5
	v_mov_b32_e32 v10, 1.0
	s_andn2_b64 vcc, exec, s[8:9]
	v_cndmask_b32_e64 v4, 0, 1, s[8:9]
	v_cmp_ne_u32_e64 s[2:3], 1, v4
	v_lshl_add_u64 v[4:5], v[8:9], 2, s[86:87]
	v_mov_b32_e32 v12, 1.0
	s_cbranch_vccnz .LBB0_168
	global_load_dword v12, v[4:5], off

; DI int TID() { int t = threadIdx.x; asm volatile("" : "+v"(t)); return t; }
; DI unsigned pk2(float a, float b) { f32x2_t v = {a, b}; bf16x2_t r_ = __builtin_convertvector(v, bf16x2_t); return __builtin_bit_cast(unsigned, r_); }
; template <bool MAP = false>
; DI void conv_tile(const float* __restrict__ src, int N, int K, bfu* __restrict__ dst, const float* __restrict__ g,
;                   int tk, int tn, char* smem, int ldk = -1) {
;   const int LK = ldk < 0 ? K : ldk;
;   float* T = (float*)smem;
;   const int tid = TID();
;   __syncthreads();
; #pragma unroll
;   for (int j = 0; j < 4; ++j) {
;     int k = (tid >> 4) + 16 * j, n4 = (tid & 15) * 4;
;     int gn = tn * 64 + n4, gk = tk * 64 + k;
;     float4 v = make_float4(0.f, 0.f, 0.f, 0.f);
;     const int og = MAP ? in_colmap(gn) : (gn < N ? gn : -1);
;     if (og >= 0) v = *(const float4*)(src + (size_t)gk * N + og);
;     float gg = g ? g[gk] : 1.f;
;     T[k * 65 + n4 + 0] = v.x * gg; T[k * 65 + n4 + 1] = v.y * gg; T[k * 65 + n4 + 2] = v.z * gg; T[k * 65 + n4 + 3] = v.w * gg;
;   }
;   __syncthreads();
; #pragma unroll
;   for (int j = 0; j < 2; ++j) {
;     int n = (tid >> 3) + 32 * j, kc = tid & 7;
;     float e[8];
; #pragma unroll
;     for (int q = 0; q < 8; ++q) e[q] = T[(kc * 8 + q) * 65 + n];
;     u32x4 o = {pk2(e[0], e[1]), pk2(e[2], e[3]), pk2(e[4], e[5]), pk2(e[6], e[7])};
;     *(u32x4*)(dst + (size_t)(tn * 64 + n) * LK + tk * 64 + kc * 8) = o;
;   }
; DI void conv_item_C(const Params& p, int L, int it, char* smem) {
;     ...
;   else if (it < 2560) { int t = it - 1536; conv_tile(p.w_down + (size_t)L * DFF * D, D, DFF, p.wt_down, nullptr, t / 16, t % 16, smem); }
.LBB0_176:
	s_andn2_b64 vcc, exec, s[2:3]
	s_cbranch_vccnz .LBB0_178
	v_mov_b32_e32 v8, v224
	s_lshl_b32 s3, s6, 2
	s_lshl_b32 s2, s6, 6
	v_lshlrev_b32_e32 v0, 2, v8
	s_and_b32 s3, s3, 0x3fc0
	v_ashrrev_i32_e32 v2, 4, v8
	v_and_b32_e32 v3, 60, v0
	s_and_b32 s2, s2, 0x3c0
	s_add_i32 s96, s3, 0xffffe800
	v_or_b32_e32 v0, s2, v3
	v_add_u32_e32 v6, s96, v2
	v_lshlrev_b32_e32 v188, 2, v0
	v_ashrrev_i32_e32 v7, 31, v6
	v_lshl_add_u64 v[4:5], s[90:91], 0, v[188:189]
	v_lshlrev_b64 v[0:1], 12, v[6:7]
	s_movk_i32 s3, 0x104
	v_lshl_add_u64 v[0:1], v[4:5], 0, v[0:1]
	v_mul_lo_u32 v2, v2, s3
	s_waitcnt vmcnt(63) expcnt(7) lgkmcnt(15)
	s_barrier
	v_lshl_add_u32 v7, v3, 2, v2
	v_add_u32_e32 v210, 16, v6
	v_ashrrev_i32_e32 v211, 31, v210
	v_lshlrev_b64 v[210:211], 12, v[210:211]
	v_lshl_add_u64 v[210:211], v[4:5], 0, v[210:211]
	global_load_dwordx4 v[240:243], v[210:211], off nt
	v_add_u32_e32 v210, 32, v6
	v_ashrrev_i32_e32 v211, 31, v210
	v_lshlrev_b64 v[210:211], 12, v[210:211]
	v_lshl_add_u64 v[210:211], v[4:5], 0, v[210:211]
	global_load_dwordx4 v[244:247], v[210:211], off nt
	v_add_u32_e32 v210, 48, v6
	v_ashrrev_i32_e32 v211, 31, v210
	v_lshlrev_b64 v[210:211], 12, v[210:211]
	v_lshl_add_u64 v[210:211], v[4:5], 0, v[210:211]
	global_load_dwordx4 v[248:251], v[210:211], off nt
	global_load_dwordx4 v[0:3], v[0:1], off
	v_add_u32_e32 v9, 0x1040, v7
	v_ashrrev_i32_e32 v22, 3, v8
	v_readlane_b32 s16, v253, 48
	s_lshl_b64 s[4:5], s[96:97], 1
	v_readlane_b32 s26, v253, 58
	v_readlane_b32 s27, v253, 59
	s_add_u32 s4, s26, s4
	s_addc_u32 s5, s27, s5
	v_readlane_b32 s17, v253, 49
	v_readlane_b32 s18, v253, 50
	v_readlane_b32 s19, v253, 51
	v_readlane_b32 s20, v253, 52
	v_readlane_b32 s21, v253, 53
	v_readlane_b32 s22, v253, 54
	v_readlane_b32 s23, v253, 55
	v_readlane_b32 s24, v253, 56
	v_readlane_b32 s25, v253, 57
	v_readlane_b32 s28, v253, 60
	v_readlane_b32 s29, v253, 61
	v_readlane_b32 s30, v253, 62
	v_readlane_b32 s31, v253, 63
	s_waitcnt vmcnt(0)
	ds_write2_b32 v7, v0, v1 offset1:1
	ds_write2_b32 v7, v2, v3 offset0:2 offset1:3
	v_add_u32_e32 v0, 16, v6
	v_ashrrev_i32_e32 v1, 31, v0
	v_lshlrev_b64 v[0:1], 12, v[0:1]
	v_lshl_add_u64 v[0:1], v[4:5], 0, v[0:1]
	v_mov_b32_e32 v0, v240
	v_mov_b32_e32 v1, v241
	v_mov_b32_e32 v2, v242
	v_mov_b32_e32 v3, v243
	s_waitcnt vmcnt(0)
	ds_write2_b32 v9, v0, v1 offset1:1
	v_add_u32_e32 v0, 0x1048, v7
	ds_write2_b32 v0, v2, v3 offset1:1
	v_add_u32_e32 v0, 32, v6
	v_ashrrev_i32_e32 v1, 31, v0
	v_lshlrev_b64 v[0:1], 12, v[0:1]
	v_lshl_add_u64 v[0:1], v[4:5], 0, v[0:1]
	v_mov_b32_e32 v0, v244
	v_mov_b32_e32 v1, v245
	v_mov_b32_e32 v2, v246
	v_mov_b32_e32 v3, v247
	v_add_u32_e32 v9, 0x2080, v7
	s_waitcnt vmcnt(0)
	ds_write2_b32 v9, v0, v1 offset1:1
	v_add_u32_e32 v0, 0x2088, v7
	ds_write2_b32 v0, v2, v3 offset1:1
	v_add_u32_e32 v0, 48, v6
	v_ashrrev_i32_e32 v1, 31, v0
	v_lshlrev_b64 v[0:1], 12, v[0:1]
	v_lshl_add_u64 v[0:1], v[4:5], 0, v[0:1]
	v_mov_b32_e32 v0, v248
	v_mov_b32_e32 v1, v249
	v_mov_b32_e32 v2, v250
	v_mov_b32_e32 v3, v251
	v_add_u32_e32 v4, 0x30c0, v7
	s_waitcnt vmcnt(0)
	ds_write2_b32 v4, v0, v1 offset1:1
	v_add_u32_e32 v0, 0x30c8, v7
	ds_write2_b32 v0, v2, v3 offset1:1
	v_lshlrev_b32_e32 v0, 3, v8
	v_and_b32_e32 v2, 56, v0
	v_lshlrev_b32_e32 v188, 1, v2
	v_mul_u32_u24_e32 v2, 0x104, v2
	v_lshl_add_u32 v2, v22, 2, v2
	s_waitcnt lgkmcnt(0)
	s_barrier
	ds_read2_b32 v[6:7], v2 offset1:32
	ds_read2_b32 v[8:9], v2 offset0:65 offset1:97
	ds_read2_b32 v[10:11], v2 offset0:130 offset1:162
	ds_read2_b32 v[12:13], v2 offset0:195 offset1:227
	v_add_u32_e32 v2, 0x400, v2
	ds_read2_b32 v[14:15], v2 offset0:4 offset1:36
	ds_read2_b32 v[16:17], v2 offset0:69 offset1:101
	ds_read2_b32 v[18:19], v2 offset0:134 offset1:166
	ds_read2_b32 v[20:21], v2 offset0:199 offset1:231
	v_add_u32_e32 v22, s2, v22
	v_ashrrev_i32_e32 v23, 31, v22
	v_lshl_add_u64 v[0:1], s[4:5], 0, v[188:189]
	v_lshlrev_b64 v[24:25], 13, v[22:23]
	s_waitcnt lgkmcnt(6)
	v_cvt_pk_bf16_f32 v2, v6, v8
	s_waitcnt lgkmcnt(4)
	v_cvt_pk_bf16_f32 v3, v10, v12
	s_waitcnt lgkmcnt(2)
	v_cvt_pk_bf16_f32 v4, v14, v16
	s_waitcnt lgkmcnt(0)
	v_cvt_pk_bf16_f32 v5, v18, v20
	v_lshl_add_u64 v[24:25], v[0:1], 0, v[24:25]
	v_add_u32_e32 v6, 32, v22
	global_store_dwordx4 v[24:25], v[2:5], off
	s_nop 1
	v_cvt_pk_bf16_f32 v2, v7, v9
	v_ashrrev_i32_e32 v7, 31, v6
	v_lshlrev_b64 v[6:7], 13, v[6:7]
	v_cvt_pk_bf16_f32 v3, v11, v13
	v_cvt_pk_bf16_f32 v4, v15, v17
	v_cvt_pk_bf16_f32 v5, v19, v21
	v_lshl_add_u64 v[0:1], v[0:1], 0, v[6:7]
	global_store_dwordx4 v[0:1], v[2:5], off

; template <bool MAP = false>
; DI void conv_tile(const float* __restrict__ src, int N, int K, bfu* __restrict__ dst, const float* __restrict__ g,
;                   int tk, int tn, char* smem, int ldk = -1) {
;     ...
;   for (int j = 0; j < 4; ++j) {
;     int k = (tid >> 4) + 16 * j, n4 = (tid & 15) * 4;
;     int gn = tn * 64 + n4, gk = tk * 64 + k;
;     float4 v = make_float4(0.f, 0.f, 0.f, 0.f);
;     const int og = MAP ? in_colmap(gn) : (gn < N ? gn : -1);
;     if (og >= 0) v = *(const float4*)(src + (size_t)gk * N + og);
;     float gg = g ? g[gk] : 1.f;
;     T[k * 65 + n4 + 0] = v.x * gg; T[k * 65 + n4 + 1] = v.y * gg; T[k * 65 + n4 + 2] = v.z * gg; T[k * 65 + n4 + 3] = v.w * gg;
; DI void conv_item_C(const Params& p, int L, int it, char* smem) {
;     ...
;   else if (it < 1536) { int t = it - 512; conv_tile(p.w_up + (size_t)L * D * DFF, DFF, D, p.wt_up, p.norm_mlp_g + L * D, t / 64, t % 64, smem); }
.LBB0_179:
	s_andn2_b64 vcc, exec, s[2:3]
	s_cbranch_vccnz .LBB0_189
	v_mov_b32_e32 v11, v224
	s_and_b32 s4, s6, 0x7c0
	s_lshl_b32 s2, s6, 6
	v_lshlrev_b32_e32 v0, 2, v11
	s_add_i32 s96, s4, 0xfffffe00
	v_ashrrev_i32_e32 v8, 4, v11
	v_and_b32_e32 v13, 60, v0
	s_and_b32 s7, s2, 0xfc0
	v_or_b32_e32 v0, s7, v13
	v_add_u32_e32 v6, s96, v8
	v_lshlrev_b32_e32 v188, 2, v0
	v_ashrrev_i32_e32 v7, 31, v6
	v_lshl_add_u64 v[4:5], s[92:93], 0, v[188:189]
	v_lshlrev_b64 v[0:1], 14, v[6:7]
	v_lshl_add_u64 v[0:1], v[4:5], 0, v[0:1]
	s_waitcnt vmcnt(63) expcnt(7) lgkmcnt(15)
	s_barrier
	v_add_u32_e32 v210, 16, v6
	v_ashrrev_i32_e32 v211, 31, v210
	v_lshlrev_b64 v[210:211], 14, v[210:211]
	v_lshl_add_u64 v[210:211], v[4:5], 0, v[210:211]
	global_load_dwordx4 v[240:243], v[210:211], off nt
	v_add_u32_e32 v210, 32, v6
	v_ashrrev_i32_e32 v211, 31, v210
	v_lshlrev_b64 v[210:211], 14, v[210:211]
	v_lshl_add_u64 v[210:211], v[4:5], 0, v[210:211]
	global_load_dwordx4 v[244:247], v[210:211], off nt
	v_add_u32_e32 v210, 48, v6
	v_ashrrev_i32_e32 v211, 31, v210
	v_lshlrev_b64 v[210:211], 14, v[210:211]
	v_lshl_add_u64 v[210:211], v[4:5], 0, v[210:211]
	global_load_dwordx4 v[248:251], v[210:211], off nt
	global_load_dwordx4 v[0:3], v[0:1], off
	v_readlane_b32 s8, v255, 6
	v_readlane_b32 s9, v255, 7
	v_mov_b32_e32 v10, 1.0
	s_andn2_b64 vcc, exec, s[8:9]
	v_cndmask_b32_e64 v9, 0, 1, s[8:9]
	v_cmp_ne_u32_e64 s[2:3], 1, v9
	v_mov_b32_e32 v12, 1.0
	s_cbranch_vccnz .LBB0_182
	v_ashrrev_i32_e32 v9, 31, v8
	s_mov_b32 s5, s97
	v_lshl_add_u64 v[14:15], v[8:9], 0, s[4:5]
	v_lshl_add_u64 v[14:15], v[14:15], 2, s[52:53]
	global_load_dword v12, v[14:15], off offset:-2048

; DI int TID() { int t = threadIdx.x; asm volatile("" : "+v"(t)); return t; }
; DI unsigned pk2(float a, float b) { f32x2_t v = {a, b}; bf16x2_t r_ = __builtin_convertvector(v, bf16x2_t); return __builtin_bit_cast(unsigned, r_); }
; template <bool MAP = false>
; DI void conv_tile(const float* __restrict__ src, int N, int K, bfu* __restrict__ dst, const float* __restrict__ g,
;                   int tk, int tn, char* smem, int ldk = -1) {
;   const int LK = ldk < 0 ? K : ldk;
;   float* T = (float*)smem;
;   const int tid = TID();
;   __syncthreads();
; #pragma unroll
;   for (int j = 0; j < 4; ++j) {
;     int k = (tid >> 4) + 16 * j, n4 = (tid & 15) * 4;
;     int gn = tn * 64 + n4, gk = tk * 64 + k;
;     float4 v = make_float4(0.f, 0.f, 0.f, 0.f);
;     const int og = MAP ? in_colmap(gn) : (gn < N ? gn : -1);
;     if (og >= 0) v = *(const float4*)(src + (size_t)gk * N + og);
;     float gg = g ? g[gk] : 1.f;
;     T[k * 65 + n4 + 0] = v.x * gg; T[k * 65 + n4 + 1] = v.y * gg; T[k * 65 + n4 + 2] = v.z * gg; T[k * 65 + n4 + 3] = v.w * gg;
;   }
;   __syncthreads();
; #pragma unroll
;   for (int j = 0; j < 2; ++j) {
;     int n = (tid >> 3) + 32 * j, kc = tid & 7;
;     float e[8];
; #pragma unroll
;     for (int q = 0; q < 8; ++q) e[q] = T[(kc * 8 + q) * 65 + n];
;     u32x4 o = {pk2(e[0], e[1]), pk2(e[2], e[3]), pk2(e[4], e[5]), pk2(e[6], e[7])};
;     *(u32x4*)(dst + (size_t)(tn * 64 + n) * LK + tk * 64 + kc * 8) = o;
;   }
; DI void conv_item_C(const Params& p, int L, int it, char* smem) {
;     ...
;   else if (it < 512) { int t = it - 256; conv_tile(p.w_o + (size_t)L * D * D, D, D, p.wt_o, nullptr, t / 16, t % 16, smem); }
.LBB0_190:
	s_andn2_b64 vcc, exec, s[2:3]
	s_cbranch_vccnz .LBB0_192
	v_mov_b32_e32 v8, v224
	s_lshl_b32 s3, s6, 2
	s_lshl_b32 s2, s6, 6
	v_lshlrev_b32_e32 v0, 2, v8
	s_and_b32 s3, s3, 0x7c0
	v_ashrrev_i32_e32 v2, 4, v8
	v_and_b32_e32 v3, 60, v0
	s_and_b32 s2, s2, 0x3c0
	s_add_i32 s96, s3, 0xfffffc00
	v_or_b32_e32 v0, s2, v3
	v_readlane_b32 s4, v255, 28
	v_add_u32_e32 v6, s96, v2
	v_lshlrev_b32_e32 v188, 2, v0
	v_readlane_b32 s5, v255, 29
	v_ashrrev_i32_e32 v7, 31, v6
	v_lshlrev_b64 v[0:1], 12, v[6:7]
	v_lshl_add_u64 v[4:5], s[4:5], 0, v[188:189]
	s_movk_i32 s3, 0x104
	v_lshl_add_u64 v[0:1], v[4:5], 0, v[0:1]
	v_mul_lo_u32 v2, v2, s3
	s_waitcnt vmcnt(63) expcnt(7) lgkmcnt(15)
	s_barrier
	v_lshl_add_u32 v7, v3, 2, v2
	v_add_u32_e32 v210, 16, v6
	v_ashrrev_i32_e32 v211, 31, v210
	v_lshlrev_b64 v[210:211], 12, v[210:211]
	v_lshl_add_u64 v[210:211], v[4:5], 0, v[210:211]
	global_load_dwordx4 v[240:243], v[210:211], off nt
	v_add_u32_e32 v210, 32, v6
	v_ashrrev_i32_e32 v211, 31, v210
	v_lshlrev_b64 v[210:211], 12, v[210:211]
	v_lshl_add_u64 v[210:211], v[4:5], 0, v[210:211]
	global_load_dwordx4 v[244:247], v[210:211], off nt
	v_add_u32_e32 v210, 48, v6
	v_ashrrev_i32_e32 v211, 31, v210
	v_lshlrev_b64 v[210:211], 12, v[210:211]
	v_lshl_add_u64 v[210:211], v[4:5], 0, v[210:211]
	global_load_dwordx4 v[248:251], v[210:211], off nt
	global_load_dwordx4 v[0:3], v[0:1], off
	v_add_u32_e32 v9, 0x1040, v7
	v_ashrrev_i32_e32 v22, 3, v8
	v_readlane_b32 s16, v253, 48
	s_lshl_b64 s[4:5], s[96:97], 1
	v_readlane_b32 s22, v253, 54
	v_readlane_b32 s23, v253, 55
	s_add_u32 s4, s22, s4
	s_addc_u32 s5, s23, s5
	v_readlane_b32 s17, v253, 49
	v_readlane_b32 s18, v253, 50
	v_readlane_b32 s19, v253, 51
	v_readlane_b32 s20, v253, 52
	v_readlane_b32 s21, v253, 53
	v_readlane_b32 s24, v253, 56
	v_readlane_b32 s25, v253, 57
	v_readlane_b32 s26, v253, 58
	v_readlane_b32 s27, v253, 59
	v_readlane_b32 s28, v253, 60
	v_readlane_b32 s29, v253, 61
	v_readlane_b32 s30, v253, 62
	v_readlane_b32 s31, v253, 63
	s_waitcnt vmcnt(0)
	ds_write2_b32 v7, v0, v1 offset1:1
	ds_write2_b32 v7, v2, v3 offset0:2 offset1:3
	v_add_u32_e32 v0, 16, v6
	v_ashrrev_i32_e32 v1, 31, v0
	v_lshlrev_b64 v[0:1], 12, v[0:1]
	v_lshl_add_u64 v[0:1], v[4:5], 0, v[0:1]
	v_mov_b32_e32 v0, v240
	v_mov_b32_e32 v1, v241
	v_mov_b32_e32 v2, v242
	v_mov_b32_e32 v3, v243
	s_waitcnt vmcnt(0)
	ds_write2_b32 v9, v0, v1 offset1:1
	v_add_u32_e32 v0, 0x1048, v7
	ds_write2_b32 v0, v2, v3 offset1:1
	v_add_u32_e32 v0, 32, v6
	v_ashrrev_i32_e32 v1, 31, v0
	v_lshlrev_b64 v[0:1], 12, v[0:1]
	v_lshl_add_u64 v[0:1], v[4:5], 0, v[0:1]
	v_mov_b32_e32 v0, v244
	v_mov_b32_e32 v1, v245
	v_mov_b32_e32 v2, v246
	v_mov_b32_e32 v3, v247
	v_add_u32_e32 v9, 0x2080, v7
	s_waitcnt vmcnt(0)
	ds_write2_b32 v9, v0, v1 offset1:1
	v_add_u32_e32 v0, 0x2088, v7
	ds_write2_b32 v0, v2, v3 offset1:1
	v_add_u32_e32 v0, 48, v6
	v_ashrrev_i32_e32 v1, 31, v0
	v_lshlrev_b64 v[0:1], 12, v[0:1]
	v_lshl_add_u64 v[0:1], v[4:5], 0, v[0:1]
	v_mov_b32_e32 v0, v248
	v_mov_b32_e32 v1, v249
	v_mov_b32_e32 v2, v250
	v_mov_b32_e32 v3, v251
	v_add_u32_e32 v4, 0x30c0, v7
	s_waitcnt vmcnt(0)
	ds_write2_b32 v4, v0, v1 offset1:1
	v_add_u32_e32 v0, 0x30c8, v7
	ds_write2_b32 v0, v2, v3 offset1:1
	v_lshlrev_b32_e32 v0, 3, v8
	v_and_b32_e32 v2, 56, v0
	v_lshlrev_b32_e32 v188, 1, v2
	v_mul_u32_u24_e32 v2, 0x104, v2
	v_lshl_add_u32 v2, v22, 2, v2
	s_waitcnt lgkmcnt(0)
	s_barrier
	ds_read2_b32 v[6:7], v2 offset1:32
	ds_read2_b32 v[8:9], v2 offset0:65 offset1:97
	ds_read2_b32 v[10:11], v2 offset0:130 offset1:162
	ds_read2_b32 v[12:13], v2 offset0:195 offset1:227
	v_add_u32_e32 v2, 0x400, v2
	ds_read2_b32 v[14:15], v2 offset0:4 offset1:36
	ds_read2_b32 v[16:17], v2 offset0:69 offset1:101
	ds_read2_b32 v[18:19], v2 offset0:134 offset1:166
	ds_read2_b32 v[20:21], v2 offset0:199 offset1:231
	v_add_u32_e32 v22, s2, v22
	v_ashrrev_i32_e32 v23, 31, v22
	v_lshl_add_u64 v[0:1], s[4:5], 0, v[188:189]
	v_lshlrev_b64 v[24:25], 11, v[22:23]
	s_waitcnt lgkmcnt(6)
	v_cvt_pk_bf16_f32 v2, v6, v8
	s_waitcnt lgkmcnt(4)
	v_cvt_pk_bf16_f32 v3, v10, v12
	s_waitcnt lgkmcnt(2)
	v_cvt_pk_bf16_f32 v4, v14, v16
	s_waitcnt lgkmcnt(0)
	v_cvt_pk_bf16_f32 v5, v18, v20
	v_lshl_add_u64 v[24:25], v[0:1], 0, v[24:25]
	v_add_u32_e32 v6, 32, v22
	global_store_dwordx4 v[24:25], v[2:5], off
	s_nop 1
	v_cvt_pk_bf16_f32 v2, v7, v9
	v_ashrrev_i32_e32 v7, 31, v6
	v_lshlrev_b64 v[6:7], 11, v[6:7]
	v_cvt_pk_bf16_f32 v3, v11, v13
	v_cvt_pk_bf16_f32 v4, v15, v17
	v_cvt_pk_bf16_f32 v5, v19, v21
	v_lshl_add_u64 v[0:1], v[0:1], 0, v[6:7]
	global_store_dwordx4 v[0:1], v[2:5], off

; DI int TID() { int t = threadIdx.x; asm volatile("" : "+v"(t)); return t; }
; DI unsigned pk2(float a, float b) { f32x2_t v = {a, b}; bf16x2_t r_ = __builtin_convertvector(v, bf16x2_t); return __builtin_bit_cast(unsigned, r_); }
; template <bool MAP = false>
; DI void conv_tile(const float* __restrict__ src, int N, int K, bfu* __restrict__ dst, const float* __restrict__ g,
;                   int tk, int tn, char* smem, int ldk = -1) {
;   const int LK = ldk < 0 ? K : ldk;
;   float* T = (float*)smem;
;   const int tid = TID();
;   __syncthreads();
; #pragma unroll
;   for (int j = 0; j < 4; ++j) {
;     int k = (tid >> 4) + 16 * j, n4 = (tid & 15) * 4;
;     int gn = tn * 64 + n4, gk = tk * 64 + k;
;     float4 v = make_float4(0.f, 0.f, 0.f, 0.f);
;     const int og = MAP ? in_colmap(gn) : (gn < N ? gn : -1);
;     if (og >= 0) v = *(const float4*)(src + (size_t)gk * N + og);
;     float gg = g ? g[gk] : 1.f;
;     T[k * 65 + n4 + 0] = v.x * gg; T[k * 65 + n4 + 1] = v.y * gg; T[k * 65 + n4 + 2] = v.z * gg; T[k * 65 + n4 + 3] = v.w * gg;
;   }
;   __syncthreads();
; #pragma unroll
;   for (int j = 0; j < 2; ++j) {
;     int n = (tid >> 3) + 32 * j, kc = tid & 7;
;     float e[8];
; #pragma unroll
;     for (int q = 0; q < 8; ++q) e[q] = T[(kc * 8 + q) * 65 + n];
;     u32x4 o = {pk2(e[0], e[1]), pk2(e[2], e[3]), pk2(e[4], e[5]), pk2(e[6], e[7])};
;     *(u32x4*)(dst + (size_t)(tn * 64 + n) * LK + tk * 64 + kc * 8) = o;
;   }
; DI void conv_item_C(const Params& p, int L, int it, char* smem) {
;   if (it < 256) { int t = it; int n = t >> 6; t &= 63; conv_tile(p.w_branch + ((size_t)L * 4 + n) * 256 * D, D, 256, p.wt_br + (size_t)n * 256, nullptr, t / 16, t % 16, smem, 1024); }
.LBB0_193:
	s_andn2_b64 vcc, exec, s[2:3]
	s_cbranch_vccnz .LBB0_195
	s_lshr_b32 s96, s6, 6
	s_lshl_b64 s[2:3], s[96:97], 20
	s_add_u32 s4, s61, s2
	v_readlane_b32 s16, v253, 48
	s_addc_u32 s5, s89, s3
	s_lshl_b64 s[2:3], s[96:97], 9
	v_readlane_b32 s20, v253, 52
	v_readlane_b32 s21, v253, 53
	s_add_u32 s7, s20, s2
	v_mov_b32_e32 v8, v224
	s_addc_u32 s3, s21, s3
	s_lshl_b32 s2, s6, 6
	v_lshlrev_b32_e32 v0, 2, v8
	s_lshl_b32 s6, s6, 2
	v_ashrrev_i32_e32 v2, 4, v8
	v_and_b32_e32 v3, 60, v0
	s_and_b32 s2, s2, 0x3c0
	s_and_b32 s6, s6, 0xc0
	v_or_b32_e32 v0, s2, v3
	v_add_u32_e32 v6, s6, v2
	v_lshlrev_b32_e32 v188, 2, v0
	v_ashrrev_i32_e32 v7, 31, v6
	v_lshl_add_u64 v[4:5], s[4:5], 0, v[188:189]
	v_lshlrev_b64 v[0:1], 12, v[6:7]
	s_movk_i32 s4, 0x104
	v_lshl_add_u64 v[0:1], v[4:5], 0, v[0:1]
	v_mul_lo_u32 v2, v2, s4
	s_waitcnt vmcnt(63) expcnt(7) lgkmcnt(15)
	s_barrier
	v_lshl_add_u32 v7, v3, 2, v2
	v_add_u32_e32 v210, 16, v6
	v_ashrrev_i32_e32 v211, 31, v210
	v_lshlrev_b64 v[210:211], 12, v[210:211]
	v_lshl_add_u64 v[210:211], v[4:5], 0, v[210:211]
	global_load_dwordx4 v[240:243], v[210:211], off nt
	v_add_u32_e32 v210, 32, v6
	v_ashrrev_i32_e32 v211, 31, v210
	v_lshlrev_b64 v[210:211], 12, v[210:211]
	v_lshl_add_u64 v[210:211], v[4:5], 0, v[210:211]
	global_load_dwordx4 v[244:247], v[210:211], off nt
	v_add_u32_e32 v210, 48, v6
	v_ashrrev_i32_e32 v211, 31, v210
	v_lshlrev_b64 v[210:211], 12, v[210:211]
	v_lshl_add_u64 v[210:211], v[4:5], 0, v[210:211]
	global_load_dwordx4 v[248:251], v[210:211], off nt
	global_load_dwordx4 v[0:3], v[0:1], off
	v_add_u32_e32 v9, 0x1040, v7
	v_ashrrev_i32_e32 v22, 3, v8
	s_lshl_b32 s4, s6, 1
	s_add_u32 s4, s7, s4
	s_addc_u32 s5, s3, 0
	v_readlane_b32 s17, v253, 49
	v_readlane_b32 s18, v253, 50
	v_readlane_b32 s19, v253, 51
	v_readlane_b32 s22, v253, 54
	v_readlane_b32 s23, v253, 55
	v_readlane_b32 s24, v253, 56
	v_readlane_b32 s25, v253, 57
	v_readlane_b32 s26, v253, 58
	v_readlane_b32 s27, v253, 59
	v_readlane_b32 s28, v253, 60
	v_readlane_b32 s29, v253, 61
	v_readlane_b32 s30, v253, 62
	v_readlane_b32 s31, v253, 63
	s_waitcnt vmcnt(0)
	ds_write2_b32 v7, v0, v1 offset1:1
	ds_write2_b32 v7, v2, v3 offset0:2 offset1:3
	v_add_u32_e32 v0, 16, v6
	v_ashrrev_i32_e32 v1, 31, v0
	v_lshlrev_b64 v[0:1], 12, v[0:1]
	v_lshl_add_u64 v[0:1], v[4:5], 0, v[0:1]
	v_mov_b32_e32 v0, v240
	v_mov_b32_e32 v1, v241
	v_mov_b32_e32 v2, v242
	v_mov_b32_e32 v3, v243
	s_waitcnt vmcnt(0)
	ds_write2_b32 v9, v0, v1 offset1:1
	v_add_u32_e32 v0, 0x1048, v7
	ds_write2_b32 v0, v2, v3 offset1:1
	v_add_u32_e32 v0, 32, v6
	v_ashrrev_i32_e32 v1, 31, v0
	v_lshlrev_b64 v[0:1], 12, v[0:1]
	v_lshl_add_u64 v[0:1], v[4:5], 0, v[0:1]
	v_mov_b32_e32 v0, v244
	v_mov_b32_e32 v1, v245
	v_mov_b32_e32 v2, v246
	v_mov_b32_e32 v3, v247
	v_add_u32_e32 v9, 0x2080, v7
	s_waitcnt vmcnt(0)
	ds_write2_b32 v9, v0, v1 offset1:1
	v_add_u32_e32 v0, 0x2088, v7
	ds_write2_b32 v0, v2, v3 offset1:1
	v_add_u32_e32 v0, 48, v6
	v_ashrrev_i32_e32 v1, 31, v0
	v_lshlrev_b64 v[0:1], 12, v[0:1]
	v_lshl_add_u64 v[0:1], v[4:5], 0, v[0:1]
	v_mov_b32_e32 v0, v248
	v_mov_b32_e32 v1, v249
	v_mov_b32_e32 v2, v250
	v_mov_b32_e32 v3, v251
	v_add_u32_e32 v4, 0x30c0, v7
	s_waitcnt vmcnt(0)
	ds_write2_b32 v4, v0, v1 offset1:1
	v_add_u32_e32 v0, 0x30c8, v7
	ds_write2_b32 v0, v2, v3 offset1:1
	v_lshlrev_b32_e32 v0, 3, v8
	v_and_b32_e32 v2, 56, v0
	v_lshlrev_b32_e32 v188, 1, v2
	v_mul_u32_u24_e32 v2, 0x104, v2
	v_lshl_add_u32 v2, v22, 2, v2
	s_waitcnt lgkmcnt(0)
	s_barrier
	ds_read2_b32 v[6:7], v2 offset1:32
	ds_read2_b32 v[8:9], v2 offset0:65 offset1:97
	ds_read2_b32 v[10:11], v2 offset0:130 offset1:162
	ds_read2_b32 v[12:13], v2 offset0:195 offset1:227
	v_add_u32_e32 v2, 0x400, v2
	ds_read2_b32 v[14:15], v2 offset0:4 offset1:36
	ds_read2_b32 v[16:17], v2 offset0:69 offset1:101
	ds_read2_b32 v[18:19], v2 offset0:134 offset1:166
	ds_read2_b32 v[20:21], v2 offset0:199 offset1:231
	v_add_u32_e32 v22, s2, v22
	v_ashrrev_i32_e32 v23, 31, v22
	v_lshl_add_u64 v[0:1], s[4:5], 0, v[188:189]
	v_lshlrev_b64 v[24:25], 11, v[22:23]
	s_waitcnt lgkmcnt(6)
	v_cvt_pk_bf16_f32 v2, v6, v8
	s_waitcnt lgkmcnt(4)
	v_cvt_pk_bf16_f32 v3, v10, v12
	s_waitcnt lgkmcnt(2)
	v_cvt_pk_bf16_f32 v4, v14, v16
	s_waitcnt lgkmcnt(0)
	v_cvt_pk_bf16_f32 v5, v18, v20
	v_lshl_add_u64 v[24:25], v[0:1], 0, v[24:25]
	v_add_u32_e32 v6, 32, v22
	global_store_dwordx4 v[24:25], v[2:5], off
	s_nop 1
	v_cvt_pk_bf16_f32 v2, v7, v9
	v_ashrrev_i32_e32 v7, 31, v6
	v_lshlrev_b64 v[6:7], 11, v[6:7]
	v_cvt_pk_bf16_f32 v3, v11, v13
	v_cvt_pk_bf16_f32 v4, v15, v17
	v_cvt_pk_bf16_f32 v5, v19, v21
	v_lshl_add_u64 v[0:1], v[0:1], 0, v[6:7]
	global_store_dwordx4 v[0:1], v[2:5], off

; DI unsigned pk2(float a, float b) { f32x2_t v = {a, b}; bf16x2_t r_ = __builtin_convertvector(v, bf16x2_t); return __builtin_bit_cast(unsigned, r_); }
; DI float bflo(unsigned u) { return __uint_as_float(u << 16); }
; DI float bfhi(unsigned u) { return __uint_as_float(u & 0xffff0000u); }
; DI void mlaprep_item(const Params& p, int L, int item, char* smem) {
;     ...
;     const bfu* srcA = which ? (p.kvraw + t * 512 + h * 128) : (p.qraw + t * 384 + h * 96);
;     const bfu* srcB = which ? (p.krope + t * 32) : (p.qraw + t * 384 + h * 96 + 64);
;     const float* g = (which ? p.mla_kn_g : p.mla_qn_g) + L * 96;
;     float ss = 0.f;
; #pragma unroll
;     for (int c = 0; c < 12; ++c) {
;       u32x4 v = *(const u32x4*)((c < 8) ? (srcA + c * 8) : (srcB + (c - 8) * 8));
; #pragma unroll
;       for (int q = 0; q < 4; ++q) { float lo = bflo(v[q]), hi = bfhi(v[q]); ss += lo * lo + hi * hi; }
;     }
;     const float sc = which ? 1.f : 0.10206207261596577f;
;     const float rs = rsqrtf(ss * (1.f / 96.f) + EPS) * sc;
;     bfu* dst = (which ? p.k_mla : p.q_mla) + (((size_t)(b * 4 + h)) * S + spos) * 96;
; #pragma unroll
;     for (int c = 0; c < 8; ++c) {
;       u32x4 v = *(const u32x4*)(srcA + c * 8);
;       const float* gc = g + c * 8;
;       *(u32x4*)(dst + c * 8) = (u32x4){pk2(bflo(v[0]) * rs * gc[0], bfhi(v[0]) * rs * gc[1]), pk2(bflo(v[1]) * rs * gc[2], bfhi(v[1]) * rs * gc[3]),
;                                        pk2(bflo(v[2]) * rs * gc[4], bfhi(v[2]) * rs * gc[5]), pk2(bflo(v[3]) * rs * gc[6], bfhi(v[3]) * rs * gc[7])};
;     }
.LBB0_198:
	s_nop 0
	v_cndmask_b32_e64 v0, 0, 1, s[6:7]
	v_cmp_ne_u32_e32 vcc, 1, v0
	v_cndmask_b32_e64 v61, v51, v53, s[6:7]
	v_cndmask_b32_e64 v60, v50, v52, s[6:7]
	v_mov_b32_e32 v0, 0x3dd105ec
	v_cndmask_b32_e64 v82, 1.0, v0, s[6:7]
	v_cndmask_b32_e64 v59, v55, v57, s[6:7]
	v_cndmask_b32_e64 v58, v54, v56, s[6:7]
	s_and_b64 s[2:3], s[6:7], exec
	s_cselect_b32 s4, s18, s20
	s_cselect_b32 s2, s58, s24
	s_cselect_b32 s3, s59, s25
	s_cselect_b32 s5, s19, s21
	s_add_u32 s4, s4, s34
	s_addc_u32 s5, s5, s35
	s_mov_b64 s[6:7], 0
	s_and_b64 vcc, exec, vcc
	global_load_dwordx4 v[118:121], v[60:61], off
	global_load_dwordx4 v[122:125], v[60:61], off offset:16
	global_load_dwordx4 v[126:129], v[60:61], off offset:32
	global_load_dwordx4 v[130:133], v[60:61], off offset:48
	global_load_dwordx4 v[134:137], v[60:61], off offset:64
	global_load_dwordx4 v[138:141], v[60:61], off offset:80
	global_load_dwordx4 v[142:145], v[60:61], off offset:96
	global_load_dwordx4 v[146:149], v[60:61], off offset:112
	global_load_dwordx4 v[150:153], v[58:59], off
	global_load_dwordx4 v[154:157], v[58:59], off offset:16
	global_load_dwordx4 v[158:161], v[58:59], off offset:32
	global_load_dwordx4 v[162:165], v[58:59], off offset:48
	global_load_dwordx4 v[62:65], v189, s[4:5]
	global_load_dwordx4 v[66:69], v189, s[4:5] offset:16
	global_load_dwordx4 v[70:73], v189, s[4:5] offset:32
	global_load_dwordx4 v[74:77], v189, s[4:5] offset:48
	global_load_dwordx4 v[78:81], v189, s[4:5] offset:64
	global_load_dwordx4 v[84:87], v189, s[4:5] offset:80
	global_load_dwordx4 v[88:91], v189, s[4:5] offset:96
	global_load_dwordx4 v[92:95], v189, s[4:5] offset:112
	global_load_dwordx4 v[96:99], v189, s[4:5] offset:128
	global_load_dwordx4 v[100:103], v189, s[4:5] offset:144
	global_load_dwordx4 v[104:107], v189, s[4:5] offset:160
	global_load_dwordx4 v[108:111], v189, s[4:5] offset:176
	global_load_dwordx4 v[112:115], v189, s[4:5] offset:192
	global_load_dwordx4 v[166:169], v189, s[4:5] offset:208
	global_load_dwordx4 v[170:173], v189, s[4:5] offset:224
	global_load_dwordx4 v[174:177], v189, s[4:5] offset:240
	global_load_dwordx4 v[178:181], v189, s[4:5] offset:256
	global_load_dwordx4 v[190:193], v189, s[4:5] offset:272
	global_load_dwordx4 v[194:197], v189, s[4:5] offset:288
	global_load_dwordx4 v[198:201], v189, s[4:5] offset:304
	global_load_dwordx4 v[202:205], v189, s[4:5] offset:320
	global_load_dwordx4 v[206:209], v189, s[4:5] offset:336
	global_load_dwordx4 v[240:243], v189, s[4:5] offset:352 nt
	global_load_dwordx4 v[244:247], v189, s[4:5] offset:368 nt
	v_lshl_add_u64 v[10:11], s[2:3], 0, v[16:17]
	s_waitcnt vmcnt(24)
	v_lshlrev_b32_e32 v4, 16, v118
	v_and_b32_e32 v5, 0xffff0000, v118
	v_mul_f32_e32 v0, v4, v4
	v_fmac_f32_e32 v0, v5, v5
	v_lshlrev_b32_e32 v6, 16, v119
	v_and_b32_e32 v7, 0xffff0000, v119
	v_mul_f32_e32 v1, v6, v6
	v_fmac_f32_e32 v1, v7, v7
	v_lshlrev_b32_e32 v4, 16, v120
	v_and_b32_e32 v5, 0xffff0000, v120
	v_mul_f32_e32 v2, v4, v4
	v_fmac_f32_e32 v2, v5, v5
	v_lshlrev_b32_e32 v6, 16, v121
	v_and_b32_e32 v7, 0xffff0000, v121
	v_mul_f32_e32 v3, v6, v6
	v_fmac_f32_e32 v3, v7, v7
	v_lshlrev_b32_e32 v4, 16, v122
	v_and_b32_e32 v5, 0xffff0000, v122
	v_fmac_f32_e32 v0, v4, v4
	v_fmac_f32_e32 v0, v5, v5
	v_lshlrev_b32_e32 v6, 16, v123
	v_and_b32_e32 v7, 0xffff0000, v123
	v_fmac_f32_e32 v1, v6, v6
	v_fmac_f32_e32 v1, v7, v7
	v_lshlrev_b32_e32 v4, 16, v124
	v_and_b32_e32 v5, 0xffff0000, v124
	v_fmac_f32_e32 v2, v4, v4
	v_fmac_f32_e32 v2, v5, v5
	v_lshlrev_b32_e32 v6, 16, v125
	v_and_b32_e32 v7, 0xffff0000, v125
	v_fmac_f32_e32 v3, v6, v6
	v_fmac_f32_e32 v3, v7, v7
	v_lshlrev_b32_e32 v4, 16, v126
	v_and_b32_e32 v5, 0xffff0000, v126
	v_fmac_f32_e32 v0, v4, v4
	v_fmac_f32_e32 v0, v5, v5
	v_lshlrev_b32_e32 v6, 16, v127
	v_and_b32_e32 v7, 0xffff0000, v127
	v_fmac_f32_e32 v1, v6, v6
	v_fmac_f32_e32 v1, v7, v7
	v_lshlrev_b32_e32 v4, 16, v128
	v_and_b32_e32 v5, 0xffff0000, v128
	v_fmac_f32_e32 v2, v4, v4
	v_fmac_f32_e32 v2, v5, v5
	v_lshlrev_b32_e32 v6, 16, v129
	v_and_b32_e32 v7, 0xffff0000, v129
	v_fmac_f32_e32 v3, v6, v6
	v_fmac_f32_e32 v3, v7, v7
	v_lshlrev_b32_e32 v4, 16, v130
	v_and_b32_e32 v5, 0xffff0000, v130
	v_fmac_f32_e32 v0, v4, v4
	v_fmac_f32_e32 v0, v5, v5
	v_lshlrev_b32_e32 v6, 16, v131
	v_and_b32_e32 v7, 0xffff0000, v131
	v_fmac_f32_e32 v1, v6, v6
	v_fmac_f32_e32 v1, v7, v7
	v_lshlrev_b32_e32 v4, 16, v132
	v_and_b32_e32 v5, 0xffff0000, v132
	v_fmac_f32_e32 v2, v4, v4
	v_fmac_f32_e32 v2, v5, v5
	v_lshlrev_b32_e32 v6, 16, v133
	v_and_b32_e32 v7, 0xffff0000, v133
	v_fmac_f32_e32 v3, v6, v6
	v_fmac_f32_e32 v3, v7, v7
	v_lshlrev_b32_e32 v4, 16, v134
	v_and_b32_e32 v5, 0xffff0000, v134
	v_fmac_f32_e32 v0, v4, v4
	v_fmac_f32_e32 v0, v5, v5
	v_lshlrev_b32_e32 v6, 16, v135
	v_and_b32_e32 v7, 0xffff0000, v135
	v_fmac_f32_e32 v1, v6, v6
	v_fmac_f32_e32 v1, v7, v7
	v_lshlrev_b32_e32 v4, 16, v136
	v_and_b32_e32 v5, 0xffff0000, v136
	v_fmac_f32_e32 v2, v4, v4
	v_fmac_f32_e32 v2, v5, v5
	v_lshlrev_b32_e32 v6, 16, v137
	v_and_b32_e32 v7, 0xffff0000, v137
	v_fmac_f32_e32 v3, v6, v6
	v_fmac_f32_e32 v3, v7, v7
	v_lshlrev_b32_e32 v4, 16, v138
	v_and_b32_e32 v5, 0xffff0000, v138
	v_fmac_f32_e32 v0, v4, v4
	v_fmac_f32_e32 v0, v5, v5
	v_lshlrev_b32_e32 v6, 16, v139
	v_and_b32_e32 v7, 0xffff0000, v139
	v_fmac_f32_e32 v1, v6, v6
	v_fmac_f32_e32 v1, v7, v7
	v_lshlrev_b32_e32 v4, 16, v140
	v_and_b32_e32 v5, 0xffff0000, v140
	v_fmac_f32_e32 v2, v4, v4
	v_fmac_f32_e32 v2, v5, v5
	v_lshlrev_b32_e32 v6, 16, v141
	v_and_b32_e32 v7, 0xffff0000, v141
	v_fmac_f32_e32 v3, v6, v6
	v_fmac_f32_e32 v3, v7, v7
	v_lshlrev_b32_e32 v4, 16, v142
	v_and_b32_e32 v5, 0xffff0000, v142
	v_fmac_f32_e32 v0, v4, v4
; DI unsigned pk2(float a, float b) { f32x2_t v = {a, b}; bf16x2_t r_ = __builtin_convertvector(v, bf16x2_t); return __builtin_bit_cast(unsigned, r_); }
; DI float bflo(unsigned u) { return __uint_as_float(u << 16); }
; DI float bfhi(unsigned u) { return __uint_as_float(u & 0xffff0000u); }
; DI void mlaprep_item(const Params& p, int L, int item, char* smem) {
;     ...
; #pragma unroll
;     for (int c = 0; c < 12; ++c) {
;       u32x4 v = *(const u32x4*)((c < 8) ? (srcA + c * 8) : (srcB + (c - 8) * 8));
; #pragma unroll
;       for (int q = 0; q < 4; ++q) { float lo = bflo(v[q]), hi = bfhi(v[q]); ss += lo * lo + hi * hi; }
;     }
;     const float sc = which ? 1.f : 0.10206207261596577f;
;     const float rs = rsqrtf(ss * (1.f / 96.f) + EPS) * sc;
;     bfu* dst = (which ? p.k_mla : p.q_mla) + (((size_t)(b * 4 + h)) * S + spos) * 96;
; #pragma unroll
;     for (int c = 0; c < 8; ++c) {
;       u32x4 v = *(const u32x4*)(srcA + c * 8);
;       const float* gc = g + c * 8;
;       *(u32x4*)(dst + c * 8) = (u32x4){pk2(bflo(v[0]) * rs * gc[0], bfhi(v[0]) * rs * gc[1]), pk2(bflo(v[1]) * rs * gc[2], bfhi(v[1]) * rs * gc[3]),
;                                        pk2(bflo(v[2]) * rs * gc[4], bfhi(v[2]) * rs * gc[5]), pk2(bflo(v[3]) * rs * gc[6], bfhi(v[3]) * rs * gc[7])};
	v_fmac_f32_e32 v0, v5, v5
	v_lshlrev_b32_e32 v6, 16, v143
	v_and_b32_e32 v7, 0xffff0000, v143
	v_fmac_f32_e32 v1, v6, v6
	v_fmac_f32_e32 v1, v7, v7
	v_lshlrev_b32_e32 v4, 16, v144
	v_and_b32_e32 v5, 0xffff0000, v144
	v_fmac_f32_e32 v2, v4, v4
	v_fmac_f32_e32 v2, v5, v5
	v_lshlrev_b32_e32 v6, 16, v145
	v_and_b32_e32 v7, 0xffff0000, v145
	v_fmac_f32_e32 v3, v6, v6
	v_fmac_f32_e32 v3, v7, v7
	v_lshlrev_b32_e32 v4, 16, v146
	v_and_b32_e32 v5, 0xffff0000, v146
	v_fmac_f32_e32 v0, v4, v4
	v_fmac_f32_e32 v0, v5, v5
	v_lshlrev_b32_e32 v6, 16, v147
	v_and_b32_e32 v7, 0xffff0000, v147
	v_fmac_f32_e32 v1, v6, v6
	v_fmac_f32_e32 v1, v7, v7
	v_lshlrev_b32_e32 v4, 16, v148
	v_and_b32_e32 v5, 0xffff0000, v148
	v_fmac_f32_e32 v2, v4, v4
	v_fmac_f32_e32 v2, v5, v5
	v_lshlrev_b32_e32 v6, 16, v149
	v_and_b32_e32 v7, 0xffff0000, v149
	v_fmac_f32_e32 v3, v6, v6
	v_fmac_f32_e32 v3, v7, v7
	v_lshlrev_b32_e32 v4, 16, v150
	v_and_b32_e32 v5, 0xffff0000, v150
	v_fmac_f32_e32 v0, v4, v4
	v_fmac_f32_e32 v0, v5, v5
	v_lshlrev_b32_e32 v6, 16, v151
	v_and_b32_e32 v7, 0xffff0000, v151
	v_fmac_f32_e32 v1, v6, v6
	v_fmac_f32_e32 v1, v7, v7
	v_lshlrev_b32_e32 v4, 16, v152
	v_and_b32_e32 v5, 0xffff0000, v152
	v_fmac_f32_e32 v2, v4, v4
	v_fmac_f32_e32 v2, v5, v5
	v_lshlrev_b32_e32 v6, 16, v153
	v_and_b32_e32 v7, 0xffff0000, v153
	v_fmac_f32_e32 v3, v6, v6
	v_fmac_f32_e32 v3, v7, v7
	v_lshlrev_b32_e32 v4, 16, v154
	v_and_b32_e32 v5, 0xffff0000, v154
	v_fmac_f32_e32 v0, v4, v4
	v_fmac_f32_e32 v0, v5, v5
	v_lshlrev_b32_e32 v6, 16, v155
	v_and_b32_e32 v7, 0xffff0000, v155
	v_fmac_f32_e32 v1, v6, v6
	v_fmac_f32_e32 v1, v7, v7
	v_lshlrev_b32_e32 v4, 16, v156
	v_and_b32_e32 v5, 0xffff0000, v156
	v_fmac_f32_e32 v2, v4, v4
	v_fmac_f32_e32 v2, v5, v5
	v_lshlrev_b32_e32 v6, 16, v157
	v_and_b32_e32 v7, 0xffff0000, v157
	v_fmac_f32_e32 v3, v6, v6
	v_fmac_f32_e32 v3, v7, v7
	v_lshlrev_b32_e32 v4, 16, v158
	v_and_b32_e32 v5, 0xffff0000, v158
	v_fmac_f32_e32 v0, v4, v4
	v_fmac_f32_e32 v0, v5, v5
	v_lshlrev_b32_e32 v6, 16, v159
	v_and_b32_e32 v7, 0xffff0000, v159
	v_fmac_f32_e32 v1, v6, v6
	v_fmac_f32_e32 v1, v7, v7
	v_lshlrev_b32_e32 v4, 16, v160
	v_and_b32_e32 v5, 0xffff0000, v160
	v_fmac_f32_e32 v2, v4, v4
	v_fmac_f32_e32 v2, v5, v5
	v_lshlrev_b32_e32 v6, 16, v161
	v_and_b32_e32 v7, 0xffff0000, v161
	v_fmac_f32_e32 v3, v6, v6
	v_fmac_f32_e32 v3, v7, v7
	v_lshlrev_b32_e32 v4, 16, v162
	v_and_b32_e32 v5, 0xffff0000, v162
	v_fmac_f32_e32 v0, v4, v4
	v_fmac_f32_e32 v0, v5, v5
	v_lshlrev_b32_e32 v6, 16, v163
	v_and_b32_e32 v7, 0xffff0000, v163
	v_fmac_f32_e32 v1, v6, v6
	v_fmac_f32_e32 v1, v7, v7
	v_lshlrev_b32_e32 v4, 16, v164
	v_and_b32_e32 v5, 0xffff0000, v164
	v_fmac_f32_e32 v2, v4, v4
	v_fmac_f32_e32 v2, v5, v5
	v_lshlrev_b32_e32 v6, 16, v165
	v_and_b32_e32 v7, 0xffff0000, v165
	v_fmac_f32_e32 v3, v6, v6
	v_fmac_f32_e32 v3, v7, v7
	v_add_f32_e32 v0, v0, v1
	v_add_f32_e32 v2, v2, v3
	v_add_f32_e32 v0, v0, v2
	v_fmamk_f32 v0, v0, 0x3c2aaaab, v225
	s_nop 0
	v_cmp_gt_f32_e64 s[2:3], s10, v0
	v_mul_f32_e32 v1, 0x4b800000, v0
	s_nop 0
	v_cndmask_b32_e64 v0, v0, v1, s[2:3]
	v_rsq_f32_e32 v0, v0
	s_nop 0
	v_mul_f32_e32 v1, 0x45800000, v0
	v_cndmask_b32_e64 v0, v0, v1, s[2:3]
	v_mul_f32_e32 v12, v82, v0
	s_waitcnt vmcnt(0)
	v_lshlrev_b32_e32 v0, 16, v118
	v_and_b32_e32 v1, 0xffff0000, v118
	v_lshlrev_b32_e32 v2, 16, v119
	v_and_b32_e32 v3, 0xffff0000, v119
	v_lshlrev_b32_e32 v4, 16, v120
	v_and_b32_e32 v5, 0xffff0000, v120
	v_lshlrev_b32_e32 v14, 16, v121
	v_and_b32_e32 v15, 0xffff0000, v121
	v_pk_mul_f32 v[0:1], v[12:13], v[0:1] op_sel_hi:[0,1]
	v_pk_mul_f32 v[2:3], v[12:13], v[2:3] op_sel_hi:[0,1]
	v_pk_mul_f32 v[4:5], v[12:13], v[4:5] op_sel_hi:[0,1]
	v_pk_mul_f32 v[14:15], v[12:13], v[14:15] op_sel_hi:[0,1]
	v_pk_mul_f32 v[0:1], v[62:63], v[0:1]
	v_pk_mul_f32 v[2:3], v[64:65], v[2:3]
	v_pk_mul_f32 v[4:5], v[66:67], v[4:5]
	v_pk_mul_f32 v[14:15], v[68:69], v[14:15]
	s_nop 0
	v_cvt_pk_bf16_f32 v6, v0, v1
	v_cvt_pk_bf16_f32 v7, v2, v3
	v_cvt_pk_bf16_f32 v8, v4, v5
	v_cvt_pk_bf16_f32 v9, v14, v15
	global_store_dwordx4 v[10:11], v[6:9], off
	v_lshlrev_b32_e32 v0, 16, v122
	v_and_b32_e32 v1, 0xffff0000, v122
	v_lshlrev_b32_e32 v2, 16, v123
	v_and_b32_e32 v3, 0xffff0000, v123
	v_lshlrev_b32_e32 v4, 16, v124
	v_and_b32_e32 v5, 0xffff0000, v124
	v_lshlrev_b32_e32 v14, 16, v125
	v_and_b32_e32 v15, 0xffff0000, v125
	v_pk_mul_f32 v[0:1], v[12:13], v[0:1] op_sel_hi:[0,1]
	v_pk_mul_f32 v[2:3], v[12:13], v[2:3] op_sel_hi:[0,1]
	v_pk_mul_f32 v[4:5], v[12:13], v[4:5] op_sel_hi:[0,1]
	v_pk_mul_f32 v[14:15], v[12:13], v[14:15] op_sel_hi:[0,1]
	v_pk_mul_f32 v[0:1], v[70:71], v[0:1]
	v_pk_mul_f32 v[2:3], v[72:73], v[2:3]
	v_pk_mul_f32 v[4:5], v[74:75], v[4:5]
	v_pk_mul_f32 v[14:15], v[76:77], v[14:15]
	s_nop 0
	v_cvt_pk_bf16_f32 v6, v0, v1
	v_cvt_pk_bf16_f32 v7, v2, v3
	v_cvt_pk_bf16_f32 v8, v4, v5
	v_cvt_pk_bf16_f32 v9, v14, v15
	global_store_dwordx4 v[10:11], v[6:9], off offset:16
	v_lshlrev_b32_e32 v0, 16, v126
	v_and_b32_e32 v1, 0xffff0000, v126
	v_lshlrev_b32_e32 v2, 16, v127
	v_and_b32_e32 v3, 0xffff0000, v127
	v_lshlrev_b32_e32 v4, 16, v128
	v_and_b32_e32 v5, 0xffff0000, v128
	v_lshlrev_b32_e32 v14, 16, v129
	v_and_b32_e32 v15, 0xffff0000, v129
	v_pk_mul_f32 v[0:1], v[12:13], v[0:1] op_sel_hi:[0,1]
	v_pk_mul_f32 v[2:3], v[12:13], v[2:3] op_sel_hi:[0,1]
	v_pk_mul_f32 v[4:5], v[12:13], v[4:5] op_sel_hi:[0,1]
	v_pk_mul_f32 v[14:15], v[12:13], v[14:15] op_sel_hi:[0,1]
	v_pk_mul_f32 v[0:1], v[78:79], v[0:1]
	v_pk_mul_f32 v[2:3], v[80:81], v[2:3]
	v_pk_mul_f32 v[4:5], v[84:85], v[4:5]
	v_pk_mul_f32 v[14:15], v[86:87], v[14:15]
	s_nop 0
	v_cvt_pk_bf16_f32 v6, v0, v1
	v_cvt_pk_bf16_f32 v7, v2, v3
; DI unsigned pk2(float a, float b) { f32x2_t v = {a, b}; bf16x2_t r_ = __builtin_convertvector(v, bf16x2_t); return __builtin_bit_cast(unsigned, r_); }
; DI float bflo(unsigned u) { return __uint_as_float(u << 16); }
; DI float bfhi(unsigned u) { return __uint_as_float(u & 0xffff0000u); }
; DI void mlaprep_item(const Params& p, int L, int item, char* smem) {
;     ...
; #pragma unroll
;     for (int c = 0; c < 8; ++c) {
;       u32x4 v = *(const u32x4*)(srcA + c * 8);
;       const float* gc = g + c * 8;
;       *(u32x4*)(dst + c * 8) = (u32x4){pk2(bflo(v[0]) * rs * gc[0], bfhi(v[0]) * rs * gc[1]), pk2(bflo(v[1]) * rs * gc[2], bfhi(v[1]) * rs * gc[3]),
;                                        pk2(bflo(v[2]) * rs * gc[4], bfhi(v[2]) * rs * gc[5]), pk2(bflo(v[3]) * rs * gc[6], bfhi(v[3]) * rs * gc[7])};
;     }
; #pragma unroll
;     for (int c = 0; c < 2; ++c) {
;       u32x4 va = *(const u32x4*)(srcB + c * 8);
;       u32x4 vb = *(const u32x4*)(srcB + 16 + c * 8);
;       float oa[8], ob[8];
; #pragma unroll
;       for (int q = 0; q < 8; ++q) {
;         const int i2 = c * 8 + q;
;         float a = ((q & 1) ? bfhi(va[q >> 1]) : bflo(va[q >> 1])) * rs * g[64 + i2];
;         float bb = ((q & 1) ? bfhi(vb[q >> 1]) : bflo(vb[q >> 1])) * rs * g[80 + i2];
;         float inv = expf(-9.210340371976184f * (float)i2 / 16.f);
;         float ang = (float)spos * inv;
;         double rv = (double)ang * 0.15915494309189535; rv -= floor(rv);
;         float fr = (float)rv;
;         float cs = __builtin_amdgcn_cosf(fr), sn = __builtin_amdgcn_sinf(fr);
;         oa[q] = a * cs - bb * sn; ob[q] = bb * cs + a * sn;
	v_cvt_pk_bf16_f32 v8, v4, v5
	v_cvt_pk_bf16_f32 v9, v14, v15
	global_store_dwordx4 v[10:11], v[6:9], off offset:32
	v_lshlrev_b32_e32 v0, 16, v130
	v_and_b32_e32 v1, 0xffff0000, v130
	v_lshlrev_b32_e32 v2, 16, v131
	v_and_b32_e32 v3, 0xffff0000, v131
	v_lshlrev_b32_e32 v4, 16, v132
	v_and_b32_e32 v5, 0xffff0000, v132
	v_lshlrev_b32_e32 v14, 16, v133
	v_and_b32_e32 v15, 0xffff0000, v133
	v_pk_mul_f32 v[0:1], v[12:13], v[0:1] op_sel_hi:[0,1]
	v_pk_mul_f32 v[2:3], v[12:13], v[2:3] op_sel_hi:[0,1]
	v_pk_mul_f32 v[4:5], v[12:13], v[4:5] op_sel_hi:[0,1]
	v_pk_mul_f32 v[14:15], v[12:13], v[14:15] op_sel_hi:[0,1]
	v_pk_mul_f32 v[0:1], v[88:89], v[0:1]
	v_pk_mul_f32 v[2:3], v[90:91], v[2:3]
	v_pk_mul_f32 v[4:5], v[92:93], v[4:5]
	v_pk_mul_f32 v[14:15], v[94:95], v[14:15]
	s_nop 0
	v_cvt_pk_bf16_f32 v6, v0, v1
	v_cvt_pk_bf16_f32 v7, v2, v3
	v_cvt_pk_bf16_f32 v8, v4, v5
	v_cvt_pk_bf16_f32 v9, v14, v15
	global_store_dwordx4 v[10:11], v[6:9], off offset:48
	v_lshlrev_b32_e32 v0, 16, v134
	v_and_b32_e32 v1, 0xffff0000, v134
	v_lshlrev_b32_e32 v2, 16, v135
	v_and_b32_e32 v3, 0xffff0000, v135
	v_lshlrev_b32_e32 v4, 16, v136
	v_and_b32_e32 v5, 0xffff0000, v136
	v_lshlrev_b32_e32 v14, 16, v137
	v_and_b32_e32 v15, 0xffff0000, v137
	v_pk_mul_f32 v[0:1], v[12:13], v[0:1] op_sel_hi:[0,1]
	v_pk_mul_f32 v[2:3], v[12:13], v[2:3] op_sel_hi:[0,1]
	v_pk_mul_f32 v[4:5], v[12:13], v[4:5] op_sel_hi:[0,1]
	v_pk_mul_f32 v[14:15], v[12:13], v[14:15] op_sel_hi:[0,1]
	v_pk_mul_f32 v[0:1], v[96:97], v[0:1]
	v_pk_mul_f32 v[2:3], v[98:99], v[2:3]
	v_pk_mul_f32 v[4:5], v[100:101], v[4:5]
	v_pk_mul_f32 v[14:15], v[102:103], v[14:15]
	s_nop 0
	v_cvt_pk_bf16_f32 v6, v0, v1
	v_cvt_pk_bf16_f32 v7, v2, v3
	v_cvt_pk_bf16_f32 v8, v4, v5
	v_cvt_pk_bf16_f32 v9, v14, v15
	global_store_dwordx4 v[10:11], v[6:9], off offset:64
	v_lshlrev_b32_e32 v0, 16, v138
	v_and_b32_e32 v1, 0xffff0000, v138
	v_lshlrev_b32_e32 v2, 16, v139
	v_and_b32_e32 v3, 0xffff0000, v139
	v_lshlrev_b32_e32 v4, 16, v140
	v_and_b32_e32 v5, 0xffff0000, v140
	v_lshlrev_b32_e32 v14, 16, v141
	v_and_b32_e32 v15, 0xffff0000, v141
	v_pk_mul_f32 v[0:1], v[12:13], v[0:1] op_sel_hi:[0,1]
	v_pk_mul_f32 v[2:3], v[12:13], v[2:3] op_sel_hi:[0,1]
	v_pk_mul_f32 v[4:5], v[12:13], v[4:5] op_sel_hi:[0,1]
	v_pk_mul_f32 v[14:15], v[12:13], v[14:15] op_sel_hi:[0,1]
	v_pk_mul_f32 v[0:1], v[104:105], v[0:1]
	v_pk_mul_f32 v[2:3], v[106:107], v[2:3]
	v_pk_mul_f32 v[4:5], v[108:109], v[4:5]
	v_pk_mul_f32 v[14:15], v[110:111], v[14:15]
	s_nop 0
	v_cvt_pk_bf16_f32 v6, v0, v1
	v_cvt_pk_bf16_f32 v7, v2, v3
	v_cvt_pk_bf16_f32 v8, v4, v5
	v_cvt_pk_bf16_f32 v9, v14, v15
	global_store_dwordx4 v[10:11], v[6:9], off offset:80
	v_lshlrev_b32_e32 v0, 16, v142
	v_and_b32_e32 v1, 0xffff0000, v142
	v_lshlrev_b32_e32 v2, 16, v143
	v_and_b32_e32 v3, 0xffff0000, v143
	v_lshlrev_b32_e32 v4, 16, v144
	v_and_b32_e32 v5, 0xffff0000, v144
	v_lshlrev_b32_e32 v14, 16, v145
	v_and_b32_e32 v15, 0xffff0000, v145
	v_pk_mul_f32 v[0:1], v[12:13], v[0:1] op_sel_hi:[0,1]
	v_pk_mul_f32 v[2:3], v[12:13], v[2:3] op_sel_hi:[0,1]
	v_pk_mul_f32 v[4:5], v[12:13], v[4:5] op_sel_hi:[0,1]
	v_pk_mul_f32 v[14:15], v[12:13], v[14:15] op_sel_hi:[0,1]
	v_pk_mul_f32 v[0:1], v[112:113], v[0:1]
	v_pk_mul_f32 v[2:3], v[114:115], v[2:3]
	v_pk_mul_f32 v[4:5], v[166:167], v[4:5]
	v_pk_mul_f32 v[14:15], v[168:169], v[14:15]
	s_nop 0
	v_cvt_pk_bf16_f32 v6, v0, v1
	v_cvt_pk_bf16_f32 v7, v2, v3
	v_cvt_pk_bf16_f32 v8, v4, v5
	v_cvt_pk_bf16_f32 v9, v14, v15
	global_store_dwordx4 v[10:11], v[6:9], off offset:96
	v_lshlrev_b32_e32 v0, 16, v146
	v_and_b32_e32 v1, 0xffff0000, v146
	v_lshlrev_b32_e32 v2, 16, v147
	v_and_b32_e32 v3, 0xffff0000, v147
	v_lshlrev_b32_e32 v4, 16, v148
	v_and_b32_e32 v5, 0xffff0000, v148
	v_lshlrev_b32_e32 v14, 16, v149
	v_and_b32_e32 v15, 0xffff0000, v149
	v_pk_mul_f32 v[0:1], v[12:13], v[0:1] op_sel_hi:[0,1]
	v_pk_mul_f32 v[2:3], v[12:13], v[2:3] op_sel_hi:[0,1]
	v_pk_mul_f32 v[4:5], v[12:13], v[4:5] op_sel_hi:[0,1]
	v_pk_mul_f32 v[14:15], v[12:13], v[14:15] op_sel_hi:[0,1]
	v_pk_mul_f32 v[0:1], v[170:171], v[0:1]
	v_pk_mul_f32 v[2:3], v[172:173], v[2:3]
	v_pk_mul_f32 v[4:5], v[174:175], v[4:5]
	v_pk_mul_f32 v[14:15], v[176:177], v[14:15]
	s_nop 0
	v_cvt_pk_bf16_f32 v6, v0, v1
	v_cvt_pk_bf16_f32 v7, v2, v3
	v_cvt_pk_bf16_f32 v8, v4, v5
	v_cvt_pk_bf16_f32 v9, v14, v15
	global_store_dwordx4 v[10:11], v[6:9], off offset:112
	v_lshlrev_b32_e32 v0, 16, v150
	v_and_b32_e32 v1, 0xffff0000, v150
	v_lshlrev_b32_e32 v2, 16, v158
	v_and_b32_e32 v3, 0xffff0000, v158
	v_pk_mul_f32 v[0:1], v[12:13], v[0:1] op_sel_hi:[0,1]
	v_pk_mul_f32 v[2:3], v[12:13], v[2:3] op_sel_hi:[0,1]
	v_pk_mul_f32 v[0:1], v[0:1], v[178:179]
	v_pk_mul_f32 v[2:3], v[2:3], v[202:203]
	v_pk_mul_f32 v[4:5], v[18:19], v[2:3]
	v_pk_mul_f32 v[14:15], v[20:21], v[2:3]
	v_pk_fma_f32 v[4:5], v[20:21], v[0:1], v[4:5]
	v_pk_fma_f32 v[14:15], v[18:19], v[0:1], v[14:15] neg_lo:[0,0,1] neg_hi:[0,0,1]
; DI unsigned pk2(float a, float b) { f32x2_t v = {a, b}; bf16x2_t r_ = __builtin_convertvector(v, bf16x2_t); return __builtin_bit_cast(unsigned, r_); }
; DI float bflo(unsigned u) { return __uint_as_float(u << 16); }
; DI float bfhi(unsigned u) { return __uint_as_float(u & 0xffff0000u); }
; DI void mlaprep_item(const Params& p, int L, int item, char* smem) {
;     ...
;     for (int c = 0; c < 2; ++c) {
;       u32x4 va = *(const u32x4*)(srcB + c * 8);
;       u32x4 vb = *(const u32x4*)(srcB + 16 + c * 8);
;       float oa[8], ob[8];
; #pragma unroll
;       for (int q = 0; q < 8; ++q) {
;         const int i2 = c * 8 + q;
;         float a = ((q & 1) ? bfhi(va[q >> 1]) : bflo(va[q >> 1])) * rs * g[64 + i2];
;         float bb = ((q & 1) ? bfhi(vb[q >> 1]) : bflo(vb[q >> 1])) * rs * g[80 + i2];
;         float inv = expf(-9.210340371976184f * (float)i2 / 16.f);
;         float ang = (float)spos * inv;
;         double rv = (double)ang * 0.15915494309189535; rv -= floor(rv);
;         float fr = (float)rv;
;         float cs = __builtin_amdgcn_cosf(fr), sn = __builtin_amdgcn_sinf(fr);
;         oa[q] = a * cs - bb * sn; ob[q] = bb * cs + a * sn;
;       }
;       *(u32x4*)(dst + 64 + c * 8) = (u32x4){pk2(oa[0], oa[1]), pk2(oa[2], oa[3]), pk2(oa[4], oa[5]), pk2(oa[6], oa[7])};
;       *(u32x4*)(dst + 80 + c * 8) = (u32x4){pk2(ob[0], ob[1]), pk2(ob[2], ob[3]), pk2(ob[4], ob[5]), pk2(ob[6], ob[7])};
;     }
;   }
;   bfu* T = (bfu*)smem;
;   __syncthreads();
	s_nop 0
	v_cvt_pk_bf16_f32 v248, v4, v5
	v_cvt_pk_bf16_f32 v6, v14, v15
	v_lshlrev_b32_e32 v0, 16, v151
	v_and_b32_e32 v1, 0xffff0000, v151
	v_lshlrev_b32_e32 v2, 16, v159
	v_and_b32_e32 v3, 0xffff0000, v159
	v_pk_mul_f32 v[0:1], v[12:13], v[0:1] op_sel_hi:[0,1]
	v_pk_mul_f32 v[2:3], v[12:13], v[2:3] op_sel_hi:[0,1]
	v_pk_mul_f32 v[0:1], v[0:1], v[180:181]
	v_pk_mul_f32 v[2:3], v[2:3], v[204:205]
	v_pk_mul_f32 v[4:5], v[22:23], v[2:3]
	v_pk_mul_f32 v[14:15], v[24:25], v[2:3]
	v_pk_fma_f32 v[4:5], v[24:25], v[0:1], v[4:5]
	v_pk_fma_f32 v[14:15], v[22:23], v[0:1], v[14:15] neg_lo:[0,0,1] neg_hi:[0,0,1]
	s_nop 0
	v_cvt_pk_bf16_f32 v249, v4, v5
	v_cvt_pk_bf16_f32 v7, v14, v15
	v_lshlrev_b32_e32 v0, 16, v152
	v_and_b32_e32 v1, 0xffff0000, v152
	v_lshlrev_b32_e32 v2, 16, v160
	v_and_b32_e32 v3, 0xffff0000, v160
	v_pk_mul_f32 v[0:1], v[12:13], v[0:1] op_sel_hi:[0,1]
	v_pk_mul_f32 v[2:3], v[12:13], v[2:3] op_sel_hi:[0,1]
	v_pk_mul_f32 v[0:1], v[0:1], v[190:191]
	v_pk_mul_f32 v[2:3], v[2:3], v[206:207]
	v_pk_mul_f32 v[4:5], v[26:27], v[2:3]
	v_pk_mul_f32 v[14:15], v[28:29], v[2:3]
	v_pk_fma_f32 v[4:5], v[28:29], v[0:1], v[4:5]
	v_pk_fma_f32 v[14:15], v[26:27], v[0:1], v[14:15] neg_lo:[0,0,1] neg_hi:[0,0,1]
	s_nop 0
	v_cvt_pk_bf16_f32 v250, v4, v5
	v_cvt_pk_bf16_f32 v8, v14, v15
	v_lshlrev_b32_e32 v0, 16, v153
	v_and_b32_e32 v1, 0xffff0000, v153
	v_lshlrev_b32_e32 v2, 16, v161
	v_and_b32_e32 v3, 0xffff0000, v161
	v_pk_mul_f32 v[0:1], v[12:13], v[0:1] op_sel_hi:[0,1]
	v_pk_mul_f32 v[2:3], v[12:13], v[2:3] op_sel_hi:[0,1]
	v_pk_mul_f32 v[0:1], v[0:1], v[192:193]
	v_pk_mul_f32 v[2:3], v[2:3], v[208:209]
	v_pk_mul_f32 v[4:5], v[30:31], v[2:3]
	v_pk_mul_f32 v[14:15], v[32:33], v[2:3]
	v_pk_fma_f32 v[4:5], v[32:33], v[0:1], v[4:5]
	v_pk_fma_f32 v[14:15], v[30:31], v[0:1], v[14:15] neg_lo:[0,0,1] neg_hi:[0,0,1]
	s_nop 0
	v_cvt_pk_bf16_f32 v251, v4, v5
	v_cvt_pk_bf16_f32 v9, v14, v15
	global_store_dwordx4 v[10:11], v[6:9], off offset:128
	global_store_dwordx4 v[10:11], v[248:251], off offset:160
	v_lshlrev_b32_e32 v0, 16, v154
	v_and_b32_e32 v1, 0xffff0000, v154
	v_lshlrev_b32_e32 v2, 16, v162
	v_and_b32_e32 v3, 0xffff0000, v162
	v_pk_mul_f32 v[0:1], v[12:13], v[0:1] op_sel_hi:[0,1]
	v_pk_mul_f32 v[2:3], v[12:13], v[2:3] op_sel_hi:[0,1]
	v_pk_mul_f32 v[0:1], v[0:1], v[194:195]
	v_pk_mul_f32 v[2:3], v[2:3], v[240:241]
	v_pk_mul_f32 v[4:5], v[34:35], v[2:3]
	v_pk_mul_f32 v[14:15], v[36:37], v[2:3]
	v_pk_fma_f32 v[4:5], v[36:37], v[0:1], v[4:5]
	v_pk_fma_f32 v[14:15], v[34:35], v[0:1], v[14:15] neg_lo:[0,0,1] neg_hi:[0,0,1]
	s_nop 0
	v_cvt_pk_bf16_f32 v248, v4, v5
	v_cvt_pk_bf16_f32 v6, v14, v15
	v_lshlrev_b32_e32 v0, 16, v155
	v_and_b32_e32 v1, 0xffff0000, v155
	v_lshlrev_b32_e32 v2, 16, v163
	v_and_b32_e32 v3, 0xffff0000, v163
	v_pk_mul_f32 v[0:1], v[12:13], v[0:1] op_sel_hi:[0,1]
	v_pk_mul_f32 v[2:3], v[12:13], v[2:3] op_sel_hi:[0,1]
	v_pk_mul_f32 v[0:1], v[0:1], v[196:197]
	v_pk_mul_f32 v[2:3], v[2:3], v[242:243]
	v_pk_mul_f32 v[4:5], v[38:39], v[2:3]
	v_pk_mul_f32 v[14:15], v[40:41], v[2:3]
	v_pk_fma_f32 v[4:5], v[40:41], v[0:1], v[4:5]
	v_pk_fma_f32 v[14:15], v[38:39], v[0:1], v[14:15] neg_lo:[0,0,1] neg_hi:[0,0,1]
	s_nop 0
	v_cvt_pk_bf16_f32 v249, v4, v5
	v_cvt_pk_bf16_f32 v7, v14, v15
	v_lshlrev_b32_e32 v0, 16, v156
	v_and_b32_e32 v1, 0xffff0000, v156
	v_lshlrev_b32_e32 v2, 16, v164
	v_and_b32_e32 v3, 0xffff0000, v164
	v_pk_mul_f32 v[0:1], v[12:13], v[0:1] op_sel_hi:[0,1]
	v_pk_mul_f32 v[2:3], v[12:13], v[2:3] op_sel_hi:[0,1]
	v_pk_mul_f32 v[0:1], v[0:1], v[198:199]
	v_pk_mul_f32 v[2:3], v[2:3], v[244:245]
	v_pk_mul_f32 v[4:5], v[42:43], v[2:3]
	v_pk_mul_f32 v[14:15], v[44:45], v[2:3]
	v_pk_fma_f32 v[4:5], v[44:45], v[0:1], v[4:5]
	v_pk_fma_f32 v[14:15], v[42:43], v[0:1], v[14:15] neg_lo:[0,0,1] neg_hi:[0,0,1]
	s_nop 0
	v_cvt_pk_bf16_f32 v250, v4, v5
	v_cvt_pk_bf16_f32 v8, v14, v15
	v_lshlrev_b32_e32 v0, 16, v157
	v_and_b32_e32 v1, 0xffff0000, v157
	v_lshlrev_b32_e32 v2, 16, v165
	v_and_b32_e32 v3, 0xffff0000, v165
	v_pk_mul_f32 v[0:1], v[12:13], v[0:1] op_sel_hi:[0,1]
	v_pk_mul_f32 v[2:3], v[12:13], v[2:3] op_sel_hi:[0,1]
	v_pk_mul_f32 v[0:1], v[0:1], v[200:201]
	v_pk_mul_f32 v[2:3], v[2:3], v[246:247]
	v_pk_mul_f32 v[4:5], v[46:47], v[2:3]
	v_pk_mul_f32 v[14:15], v[48:49], v[2:3]
	v_pk_fma_f32 v[4:5], v[48:49], v[0:1], v[4:5]
	v_pk_fma_f32 v[14:15], v[46:47], v[0:1], v[14:15] neg_lo:[0,0,1] neg_hi:[0,0,1]
	s_nop 0
	v_cvt_pk_bf16_f32 v251, v4, v5
	v_cvt_pk_bf16_f32 v9, v14, v15
	global_store_dwordx4 v[10:11], v[6:9], off offset:144
	global_store_dwordx4 v[10:11], v[248:251], off offset:176
	s_cbranch_vccz .LBB0_198
	s_lshl_b32 s3, s9, 9
	s_lshl_b32 s2, s8, 20
	s_and_b32 s3, s3, 0xf8000
	s_or_b32 s96, s2, s3
	s_lshr_b32 s4, s9, 6
	s_lshl_b64 s[2:3], s[96:97], 1
	v_readlane_b32 s5, v255, 20
	s_add_u32 s2, s5, s2
	v_readlane_b32 s5, v255, 21
	s_addc_u32 s3, s5, s3
	s_mov_b32 s5, 0
	s_barrier

; DI int TID() { int t = threadIdx.x; asm volatile("" : "+v"(t)); return t; }
; DI unsigned pk2(float a, float b) { f32x2_t v = {a, b}; bf16x2_t r_ = __builtin_convertvector(v, bf16x2_t); return __builtin_bit_cast(unsigned, r_); }
; template <bool MAP = false>
; DI void conv_tile(const float* __restrict__ src, int N, int K, bfu* __restrict__ dst, const float* __restrict__ g,
;                   int tk, int tn, char* smem, int ldk = -1) {
;   const int LK = ldk < 0 ? K : ldk;
;   float* T = (float*)smem;
;   const int tid = TID();
;   __syncthreads();
; #pragma unroll
;   for (int j = 0; j < 4; ++j) {
;     int k = (tid >> 4) + 16 * j, n4 = (tid & 15) * 4;
;     int gn = tn * 64 + n4, gk = tk * 64 + k;
;     float4 v = make_float4(0.f, 0.f, 0.f, 0.f);
;     const int og = MAP ? in_colmap(gn) : (gn < N ? gn : -1);
;     if (og >= 0) v = *(const float4*)(src + (size_t)gk * N + og);
;     float gg = g ? g[gk] : 1.f;
;     T[k * 65 + n4 + 0] = v.x * gg; T[k * 65 + n4 + 1] = v.y * gg; T[k * 65 + n4 + 2] = v.z * gg; T[k * 65 + n4 + 3] = v.w * gg;
;   }
;   __syncthreads();
; #pragma unroll
;   for (int j = 0; j < 2; ++j) {
;     int n = (tid >> 3) + 32 * j, kc = tid & 7;
;     float e[8];
; #pragma unroll
;     for (int q = 0; q < 8; ++q) e[q] = T[(kc * 8 + q) * 65 + n];
;     u32x4 o = {pk2(e[0], e[1]), pk2(e[2], e[3]), pk2(e[4], e[5]), pk2(e[6], e[7])};
;     *(u32x4*)(dst + (size_t)(tn * 64 + n) * LK + tk * 64 + kc * 8) = o;
;   }
; DI void conv_item_C(const Params& p, int L, int it, char* smem) {
;     ...
;   else if (it < 2880) { int t = it - 2816; conv_tile(p.w_ple_proj + (size_t)L * 256 * D, D, 256, p.wt_pp, nullptr, t / 16, t % 16, smem); }
.LBB0_1918:
	s_andn2_b64 vcc, exec, s[2:3]
	s_cbranch_vccnz .LBB0_1920
	v_mov_b32_e32 v8, v224
	s_lshl_b32 s3, s12, 2
	s_lshl_b32 s2, s12, 6
	v_lshlrev_b32_e32 v0, 2, v8
	s_and_b32 s3, s3, 0x3fc0
	v_ashrrev_i32_e32 v2, 4, v8
	v_and_b32_e32 v3, 60, v0
	s_and_b32 s2, s2, 0x3c0
	s_add_i32 s96, s3, 0xffffd400
	v_or_b32_e32 v0, s2, v3
	v_add_u32_e32 v6, s96, v2
	v_lshlrev_b32_e32 v188, 2, v0
	v_ashrrev_i32_e32 v7, 31, v6
	v_lshl_add_u64 v[4:5], s[62:63], 0, v[188:189]
	v_lshlrev_b64 v[0:1], 12, v[6:7]
	s_movk_i32 s3, 0x104
	v_lshl_add_u64 v[0:1], v[4:5], 0, v[0:1]
	v_mul_lo_u32 v2, v2, s3
	s_waitcnt vmcnt(63) expcnt(7) lgkmcnt(15)
	s_barrier
	v_lshl_add_u32 v7, v3, 2, v2
	v_add_u32_e32 v210, 16, v6
	v_ashrrev_i32_e32 v211, 31, v210
	v_lshlrev_b64 v[210:211], 12, v[210:211]
	v_lshl_add_u64 v[210:211], v[4:5], 0, v[210:211]
	global_load_dwordx4 v[240:243], v[210:211], off nt
	v_add_u32_e32 v210, 32, v6
	v_ashrrev_i32_e32 v211, 31, v210
	v_lshlrev_b64 v[210:211], 12, v[210:211]
	v_lshl_add_u64 v[210:211], v[4:5], 0, v[210:211]
	global_load_dwordx4 v[244:247], v[210:211], off nt
	v_add_u32_e32 v210, 48, v6
	v_ashrrev_i32_e32 v211, 31, v210
	v_lshlrev_b64 v[210:211], 12, v[210:211]
	v_lshl_add_u64 v[210:211], v[4:5], 0, v[210:211]
	global_load_dwordx4 v[248:251], v[210:211], off nt
	global_load_dwordx4 v[0:3], v[0:1], off
	v_add_u32_e32 v9, 0x1040, v7
	v_ashrrev_i32_e32 v22, 3, v8
	v_readlane_b32 s16, v253, 48
	s_lshl_b64 s[4:5], s[96:97], 1
	v_readlane_b32 s30, v253, 62
	v_readlane_b32 s31, v253, 63
	s_add_u32 s4, s30, s4
	s_addc_u32 s5, s31, s5
	v_readlane_b32 s17, v253, 49
	v_readlane_b32 s18, v253, 50
	v_readlane_b32 s19, v253, 51
	v_readlane_b32 s20, v253, 52
	v_readlane_b32 s21, v253, 53
	v_readlane_b32 s22, v253, 54
	v_readlane_b32 s23, v253, 55
	v_readlane_b32 s24, v253, 56
	v_readlane_b32 s25, v253, 57
	v_readlane_b32 s26, v253, 58
	v_readlane_b32 s27, v253, 59
	v_readlane_b32 s28, v253, 60
	v_readlane_b32 s29, v253, 61
	s_waitcnt vmcnt(0)
	ds_write2_b32 v7, v0, v1 offset1:1
	ds_write2_b32 v7, v2, v3 offset0:2 offset1:3
	v_add_u32_e32 v0, 16, v6
	v_ashrrev_i32_e32 v1, 31, v0
	v_lshlrev_b64 v[0:1], 12, v[0:1]
	v_lshl_add_u64 v[0:1], v[4:5], 0, v[0:1]
	v_mov_b32_e32 v0, v240
	v_mov_b32_e32 v1, v241
	v_mov_b32_e32 v2, v242
	v_mov_b32_e32 v3, v243
	s_waitcnt vmcnt(0)
	ds_write2_b32 v9, v0, v1 offset1:1
	v_add_u32_e32 v0, 0x1048, v7
	ds_write2_b32 v0, v2, v3 offset1:1
	v_add_u32_e32 v0, 32, v6
	v_ashrrev_i32_e32 v1, 31, v0
	v_lshlrev_b64 v[0:1], 12, v[0:1]
	v_lshl_add_u64 v[0:1], v[4:5], 0, v[0:1]
	v_mov_b32_e32 v0, v244
	v_mov_b32_e32 v1, v245
	v_mov_b32_e32 v2, v246
	v_mov_b32_e32 v3, v247
	v_add_u32_e32 v9, 0x2080, v7
	s_waitcnt vmcnt(0)
	ds_write2_b32 v9, v0, v1 offset1:1
	v_add_u32_e32 v0, 0x2088, v7
	ds_write2_b32 v0, v2, v3 offset1:1
	v_add_u32_e32 v0, 48, v6
	v_ashrrev_i32_e32 v1, 31, v0
	v_lshlrev_b64 v[0:1], 12, v[0:1]
	v_lshl_add_u64 v[0:1], v[4:5], 0, v[0:1]
	v_mov_b32_e32 v0, v248
	v_mov_b32_e32 v1, v249
	v_mov_b32_e32 v2, v250
	v_mov_b32_e32 v3, v251
	v_add_u32_e32 v4, 0x30c0, v7
	s_waitcnt vmcnt(0)
	ds_write2_b32 v4, v0, v1 offset1:1
	v_add_u32_e32 v0, 0x30c8, v7
	ds_write2_b32 v0, v2, v3 offset1:1
	v_lshlrev_b32_e32 v0, 3, v8
	v_and_b32_e32 v2, 56, v0
	v_lshlrev_b32_e32 v188, 1, v2
	v_mul_u32_u24_e32 v2, 0x104, v2
	v_lshl_add_u32 v2, v22, 2, v2
	s_waitcnt lgkmcnt(0)
	s_barrier
	ds_read2_b32 v[6:7], v2 offset1:32
	ds_read2_b32 v[8:9], v2 offset0:65 offset1:97
	ds_read2_b32 v[10:11], v2 offset0:130 offset1:162
	ds_read2_b32 v[12:13], v2 offset0:195 offset1:227
	v_add_u32_e32 v2, 0x400, v2
	ds_read2_b32 v[14:15], v2 offset0:4 offset1:36
	ds_read2_b32 v[16:17], v2 offset0:69 offset1:101
	ds_read2_b32 v[18:19], v2 offset0:134 offset1:166
	ds_read2_b32 v[20:21], v2 offset0:199 offset1:231
	v_add_u32_e32 v22, s2, v22
	v_ashrrev_i32_e32 v23, 31, v22
	v_lshl_add_u64 v[0:1], s[4:5], 0, v[188:189]
	v_lshlrev_b64 v[24:25], 9, v[22:23]
	s_waitcnt lgkmcnt(6)
	v_cvt_pk_bf16_f32 v2, v6, v8
	s_waitcnt lgkmcnt(4)
	v_cvt_pk_bf16_f32 v3, v10, v12
	s_waitcnt lgkmcnt(2)
	v_cvt_pk_bf16_f32 v4, v14, v16
	s_waitcnt lgkmcnt(0)
	v_cvt_pk_bf16_f32 v5, v18, v20
	v_lshl_add_u64 v[24:25], v[0:1], 0, v[24:25]
	v_add_u32_e32 v6, 32, v22
	global_store_dwordx4 v[24:25], v[2:5], off
	s_nop 1
	v_cvt_pk_bf16_f32 v2, v7, v9
	v_ashrrev_i32_e32 v7, 31, v6
	v_lshlrev_b64 v[6:7], 9, v[6:7]
	v_cvt_pk_bf16_f32 v3, v11, v13
	v_cvt_pk_bf16_f32 v4, v15, v17
	v_cvt_pk_bf16_f32 v5, v19, v21
	v_lshl_add_u64 v[0:1], v[0:1], 0, v[6:7]
	global_store_dwordx4 v[0:1], v[2:5], off

; template <bool MAP = false>
; DI void conv_tile(const float* __restrict__ src, int N, int K, bfu* __restrict__ dst, const float* __restrict__ g,
;                   int tk, int tn, char* smem, int ldk = -1) {
;     ...
;   for (int j = 0; j < 4; ++j) {
;     int k = (tid >> 4) + 16 * j, n4 = (tid & 15) * 4;
;     int gn = tn * 64 + n4, gk = tk * 64 + k;
;     float4 v = make_float4(0.f, 0.f, 0.f, 0.f);
;     const int og = MAP ? in_colmap(gn) : (gn < N ? gn : -1);
;     if (og >= 0) v = *(const float4*)(src + (size_t)gk * N + og);
;     float gg = g ? g[gk] : 1.f;
;     T[k * 65 + n4 + 0] = v.x * gg; T[k * 65 + n4 + 1] = v.y * gg; T[k * 65 + n4 + 2] = v.z * gg; T[k * 65 + n4 + 3] = v.w * gg;
; DI void conv_item_C(const Params& p, int L, int it, char* smem) {
;     ...
;   else if (it < 2816) { int t = it - 2560; conv_tile(p.w_ple_gate + (size_t)L * D * D, D, D, p.wt_pg, p.norm_ple_g + L * D, t / 16, t % 16, smem); }
.LBB0_1921:
	s_andn2_b64 vcc, exec, s[2:3]
	s_cbranch_vccnz .LBB0_1931
	s_lshl_b32 s2, s12, 6
	v_mov_b32_e32 v11, v224
	s_and_b32 s4, s2, 0x3c0
	s_lshl_b32 s2, s12, 2
	s_and_b32 s2, s2, 0x3fc0
	v_lshlrev_b32_e32 v0, 2, v11
	v_ashrrev_i32_e32 v13, 4, v11
	v_and_b32_e32 v14, 60, v0
	s_add_i32 s96, s2, 0xffffd800
	v_or_b32_e32 v0, s4, v14
	v_add_u32_e32 v8, s96, v13
	v_lshlrev_b32_e32 v188, 2, v0
	v_ashrrev_i32_e32 v9, 31, v8
	v_lshl_add_u64 v[6:7], s[64:65], 0, v[188:189]
	v_lshlrev_b64 v[0:1], 12, v[8:9]
	v_lshl_add_u64 v[0:1], v[6:7], 0, v[0:1]
	s_waitcnt vmcnt(63) expcnt(7) lgkmcnt(15)
	s_barrier
	v_add_u32_e32 v210, 16, v8
	v_ashrrev_i32_e32 v211, 31, v210
	v_lshlrev_b64 v[210:211], 12, v[210:211]
	v_lshl_add_u64 v[210:211], v[6:7], 0, v[210:211]
	global_load_dwordx4 v[240:243], v[210:211], off nt
	v_add_u32_e32 v210, 32, v8
	v_ashrrev_i32_e32 v211, 31, v210
	v_lshlrev_b64 v[210:211], 12, v[210:211]
	v_lshl_add_u64 v[210:211], v[6:7], 0, v[210:211]
	global_load_dwordx4 v[244:247], v[210:211], off nt
	v_add_u32_e32 v210, 48, v8
	v_ashrrev_i32_e32 v211, 31, v210
	v_lshlrev_b64 v[210:211], 12, v[210:211]
	v_lshl_add_u64 v[210:211], v[6:7], 0, v[210:211]
	global_load_dwordx4 v[248:251], v[210:211], off nt
	global_load_dwordx4 v[0:3], v[0:1], off
	v_readlane_b32 s16, v255, 4
	v_readlane_b32 s17, v255, 5
	v_mov_b32_e32 v10, 1.0
	s_andn2_b64 vcc, exec, s[16:17]
	v_cndmask_b32_e64 v4, 0, 1, s[16:17]
	v_cmp_ne_u32_e64 s[2:3], 1, v4
	v_lshl_add_u64 v[4:5], v[8:9], 2, s[66:67]
	v_mov_b32_e32 v12, 1.0
	s_cbranch_vccnz .LBB0_1924
	global_load_dword v12, v[4:5], off

; DI int TID() { int t = threadIdx.x; asm volatile("" : "+v"(t)); return t; }
; DI unsigned pk2(float a, float b) { f32x2_t v = {a, b}; bf16x2_t r_ = __builtin_convertvector(v, bf16x2_t); return __builtin_bit_cast(unsigned, r_); }
; template <bool MAP = false>
; DI void conv_tile(const float* __restrict__ src, int N, int K, bfu* __restrict__ dst, const float* __restrict__ g,
;                   int tk, int tn, char* smem, int ldk = -1) {
;   const int LK = ldk < 0 ? K : ldk;
;   float* T = (float*)smem;
;   const int tid = TID();
;   __syncthreads();
; #pragma unroll
;   for (int j = 0; j < 4; ++j) {
;     int k = (tid >> 4) + 16 * j, n4 = (tid & 15) * 4;
;     int gn = tn * 64 + n4, gk = tk * 64 + k;
;     float4 v = make_float4(0.f, 0.f, 0.f, 0.f);
;     const int og = MAP ? in_colmap(gn) : (gn < N ? gn : -1);
;     if (og >= 0) v = *(const float4*)(src + (size_t)gk * N + og);
;     float gg = g ? g[gk] : 1.f;
;     T[k * 65 + n4 + 0] = v.x * gg; T[k * 65 + n4 + 1] = v.y * gg; T[k * 65 + n4 + 2] = v.z * gg; T[k * 65 + n4 + 3] = v.w * gg;
;   }
;   __syncthreads();
; #pragma unroll
;   for (int j = 0; j < 2; ++j) {
;     int n = (tid >> 3) + 32 * j, kc = tid & 7;
;     float e[8];
; #pragma unroll
;     for (int q = 0; q < 8; ++q) e[q] = T[(kc * 8 + q) * 65 + n];
;     u32x4 o = {pk2(e[0], e[1]), pk2(e[2], e[3]), pk2(e[4], e[5]), pk2(e[6], e[7])};
;     *(u32x4*)(dst + (size_t)(tn * 64 + n) * LK + tk * 64 + kc * 8) = o;
;   }
; DI void conv_item_C(const Params& p, int L, int it, char* smem) {
;     ...
;   else if (it < 2560) { int t = it - 1536; conv_tile(p.w_down + (size_t)L * DFF * D, D, DFF, p.wt_down, nullptr, t / 16, t % 16, smem); }
.LBB0_1932:
	s_andn2_b64 vcc, exec, s[2:3]
	s_cbranch_vccnz .LBB0_1934
	v_mov_b32_e32 v8, v224
	s_lshl_b32 s3, s12, 2
	s_lshl_b32 s2, s12, 6
	v_lshlrev_b32_e32 v0, 2, v8
	s_and_b32 s3, s3, 0x3fc0
	v_ashrrev_i32_e32 v2, 4, v8
	v_and_b32_e32 v3, 60, v0
	s_and_b32 s2, s2, 0x3c0
	s_add_i32 s96, s3, 0xffffe800
	v_or_b32_e32 v0, s2, v3
	v_add_u32_e32 v6, s96, v2
	v_lshlrev_b32_e32 v188, 2, v0
	v_ashrrev_i32_e32 v7, 31, v6
	v_lshl_add_u64 v[4:5], s[92:93], 0, v[188:189]
	v_lshlrev_b64 v[0:1], 12, v[6:7]
	s_movk_i32 s3, 0x104
	v_lshl_add_u64 v[0:1], v[4:5], 0, v[0:1]
	v_mul_lo_u32 v2, v2, s3
	s_waitcnt vmcnt(63) expcnt(7) lgkmcnt(15)
	s_barrier
	v_lshl_add_u32 v7, v3, 2, v2
	v_add_u32_e32 v210, 16, v6
	v_ashrrev_i32_e32 v211, 31, v210
	v_lshlrev_b64 v[210:211], 12, v[210:211]
	v_lshl_add_u64 v[210:211], v[4:5], 0, v[210:211]
	global_load_dwordx4 v[240:243], v[210:211], off nt
	v_add_u32_e32 v210, 32, v6
	v_ashrrev_i32_e32 v211, 31, v210
	v_lshlrev_b64 v[210:211], 12, v[210:211]
	v_lshl_add_u64 v[210:211], v[4:5], 0, v[210:211]
	global_load_dwordx4 v[244:247], v[210:211], off nt
	v_add_u32_e32 v210, 48, v6
	v_ashrrev_i32_e32 v211, 31, v210
	v_lshlrev_b64 v[210:211], 12, v[210:211]
	v_lshl_add_u64 v[210:211], v[4:5], 0, v[210:211]
	global_load_dwordx4 v[248:251], v[210:211], off nt
	global_load_dwordx4 v[0:3], v[0:1], off
	v_add_u32_e32 v9, 0x1040, v7
	v_ashrrev_i32_e32 v22, 3, v8
	v_readlane_b32 s16, v253, 48
	s_lshl_b64 s[4:5], s[96:97], 1
	v_readlane_b32 s26, v253, 58
	v_readlane_b32 s27, v253, 59
	s_add_u32 s4, s26, s4
	s_addc_u32 s5, s27, s5
	v_readlane_b32 s17, v253, 49
	v_readlane_b32 s18, v253, 50
	v_readlane_b32 s19, v253, 51
	v_readlane_b32 s20, v253, 52
	v_readlane_b32 s21, v253, 53
	v_readlane_b32 s22, v253, 54
	v_readlane_b32 s23, v253, 55
	v_readlane_b32 s24, v253, 56
	v_readlane_b32 s25, v253, 57
	v_readlane_b32 s28, v253, 60
	v_readlane_b32 s29, v253, 61
	v_readlane_b32 s30, v253, 62
	v_readlane_b32 s31, v253, 63
	s_waitcnt vmcnt(0)
	ds_write2_b32 v7, v0, v1 offset1:1
	ds_write2_b32 v7, v2, v3 offset0:2 offset1:3
	v_add_u32_e32 v0, 16, v6
	v_ashrrev_i32_e32 v1, 31, v0
	v_lshlrev_b64 v[0:1], 12, v[0:1]
	v_lshl_add_u64 v[0:1], v[4:5], 0, v[0:1]
	v_mov_b32_e32 v0, v240
	v_mov_b32_e32 v1, v241
	v_mov_b32_e32 v2, v242
	v_mov_b32_e32 v3, v243
	s_waitcnt vmcnt(0)
	ds_write2_b32 v9, v0, v1 offset1:1
	v_add_u32_e32 v0, 0x1048, v7
	ds_write2_b32 v0, v2, v3 offset1:1
	v_add_u32_e32 v0, 32, v6
	v_ashrrev_i32_e32 v1, 31, v0
	v_lshlrev_b64 v[0:1], 12, v[0:1]
	v_lshl_add_u64 v[0:1], v[4:5], 0, v[0:1]
	v_mov_b32_e32 v0, v244
	v_mov_b32_e32 v1, v245
	v_mov_b32_e32 v2, v246
	v_mov_b32_e32 v3, v247
	v_add_u32_e32 v9, 0x2080, v7
	s_waitcnt vmcnt(0)
	ds_write2_b32 v9, v0, v1 offset1:1
	v_add_u32_e32 v0, 0x2088, v7
	ds_write2_b32 v0, v2, v3 offset1:1
	v_add_u32_e32 v0, 48, v6
	v_ashrrev_i32_e32 v1, 31, v0
	v_lshlrev_b64 v[0:1], 12, v[0:1]
	v_lshl_add_u64 v[0:1], v[4:5], 0, v[0:1]
	v_mov_b32_e32 v0, v248
	v_mov_b32_e32 v1, v249
	v_mov_b32_e32 v2, v250
	v_mov_b32_e32 v3, v251
	v_add_u32_e32 v4, 0x30c0, v7
	s_waitcnt vmcnt(0)
	ds_write2_b32 v4, v0, v1 offset1:1
	v_add_u32_e32 v0, 0x30c8, v7
	ds_write2_b32 v0, v2, v3 offset1:1
	v_lshlrev_b32_e32 v0, 3, v8
	v_and_b32_e32 v2, 56, v0
	v_lshlrev_b32_e32 v188, 1, v2
	v_mul_u32_u24_e32 v2, 0x104, v2
	v_lshl_add_u32 v2, v22, 2, v2
	s_waitcnt lgkmcnt(0)
	s_barrier
	ds_read2_b32 v[6:7], v2 offset1:32
	ds_read2_b32 v[8:9], v2 offset0:65 offset1:97
	ds_read2_b32 v[10:11], v2 offset0:130 offset1:162
	ds_read2_b32 v[12:13], v2 offset0:195 offset1:227
	v_add_u32_e32 v2, 0x400, v2
	ds_read2_b32 v[14:15], v2 offset0:4 offset1:36
	ds_read2_b32 v[16:17], v2 offset0:69 offset1:101
	ds_read2_b32 v[18:19], v2 offset0:134 offset1:166
	ds_read2_b32 v[20:21], v2 offset0:199 offset1:231
	v_add_u32_e32 v22, s2, v22
	v_ashrrev_i32_e32 v23, 31, v22
	v_lshl_add_u64 v[0:1], s[4:5], 0, v[188:189]
	v_lshlrev_b64 v[24:25], 13, v[22:23]
	s_waitcnt lgkmcnt(6)
	v_cvt_pk_bf16_f32 v2, v6, v8
	s_waitcnt lgkmcnt(4)
	v_cvt_pk_bf16_f32 v3, v10, v12
	s_waitcnt lgkmcnt(2)
	v_cvt_pk_bf16_f32 v4, v14, v16
	s_waitcnt lgkmcnt(0)
	v_cvt_pk_bf16_f32 v5, v18, v20
	v_lshl_add_u64 v[24:25], v[0:1], 0, v[24:25]
	v_add_u32_e32 v6, 32, v22
	global_store_dwordx4 v[24:25], v[2:5], off
	s_nop 1
	v_cvt_pk_bf16_f32 v2, v7, v9
	v_ashrrev_i32_e32 v7, 31, v6
	v_lshlrev_b64 v[6:7], 13, v[6:7]
	v_cvt_pk_bf16_f32 v3, v11, v13
	v_cvt_pk_bf16_f32 v4, v15, v17
	v_cvt_pk_bf16_f32 v5, v19, v21
	v_lshl_add_u64 v[0:1], v[0:1], 0, v[6:7]
	global_store_dwordx4 v[0:1], v[2:5], off

; template <bool MAP = false>
; DI void conv_tile(const float* __restrict__ src, int N, int K, bfu* __restrict__ dst, const float* __restrict__ g,
;                   int tk, int tn, char* smem, int ldk = -1) {
;     ...
;   for (int j = 0; j < 4; ++j) {
;     int k = (tid >> 4) + 16 * j, n4 = (tid & 15) * 4;
;     int gn = tn * 64 + n4, gk = tk * 64 + k;
;     float4 v = make_float4(0.f, 0.f, 0.f, 0.f);
;     const int og = MAP ? in_colmap(gn) : (gn < N ? gn : -1);
;     if (og >= 0) v = *(const float4*)(src + (size_t)gk * N + og);
;     float gg = g ? g[gk] : 1.f;
;     T[k * 65 + n4 + 0] = v.x * gg; T[k * 65 + n4 + 1] = v.y * gg; T[k * 65 + n4 + 2] = v.z * gg; T[k * 65 + n4 + 3] = v.w * gg;
; DI void conv_item_C(const Params& p, int L, int it, char* smem) {
;     ...
;   else if (it < 1536) { int t = it - 512; conv_tile(p.w_up + (size_t)L * D * DFF, DFF, D, p.wt_up, p.norm_mlp_g + L * D, t / 64, t % 64, smem); }
.LBB0_1935:
	s_andn2_b64 vcc, exec, s[2:3]
	s_cbranch_vccnz .LBB0_1945
	v_mov_b32_e32 v11, v224
	s_and_b32 s4, s12, 0x7c0
	s_lshl_b32 s2, s12, 6
	v_lshlrev_b32_e32 v0, 2, v11
	s_add_i32 s96, s4, 0xfffffe00
	v_ashrrev_i32_e32 v8, 4, v11
	v_and_b32_e32 v13, 60, v0
	s_and_b32 s84, s2, 0xfc0
	v_or_b32_e32 v0, s84, v13
	v_add_u32_e32 v6, s96, v8
	v_lshlrev_b32_e32 v188, 2, v0
	v_ashrrev_i32_e32 v7, 31, v6
	v_lshl_add_u64 v[4:5], s[90:91], 0, v[188:189]
	v_lshlrev_b64 v[0:1], 14, v[6:7]
	v_lshl_add_u64 v[0:1], v[4:5], 0, v[0:1]
	s_waitcnt vmcnt(63) expcnt(7) lgkmcnt(15)
	s_barrier
	v_add_u32_e32 v210, 16, v6
	v_ashrrev_i32_e32 v211, 31, v210
	v_lshlrev_b64 v[210:211], 14, v[210:211]
	v_lshl_add_u64 v[210:211], v[4:5], 0, v[210:211]
	global_load_dwordx4 v[240:243], v[210:211], off nt
	v_add_u32_e32 v210, 32, v6
	v_ashrrev_i32_e32 v211, 31, v210
	v_lshlrev_b64 v[210:211], 14, v[210:211]
	v_lshl_add_u64 v[210:211], v[4:5], 0, v[210:211]
	global_load_dwordx4 v[244:247], v[210:211], off nt
	v_add_u32_e32 v210, 48, v6
	v_ashrrev_i32_e32 v211, 31, v210
	v_lshlrev_b64 v[210:211], 14, v[210:211]
	v_lshl_add_u64 v[210:211], v[4:5], 0, v[210:211]
	global_load_dwordx4 v[248:251], v[210:211], off nt
	global_load_dwordx4 v[0:3], v[0:1], off
	v_readlane_b32 s16, v255, 6
	v_readlane_b32 s17, v255, 7
	v_mov_b32_e32 v10, 1.0
	s_andn2_b64 vcc, exec, s[16:17]
	v_cndmask_b32_e64 v9, 0, 1, s[16:17]
	v_cmp_ne_u32_e64 s[2:3], 1, v9
	v_mov_b32_e32 v12, 1.0
	s_cbranch_vccnz .LBB0_1938
	v_ashrrev_i32_e32 v9, 31, v8
	s_mov_b32 s5, s97
	v_lshl_add_u64 v[14:15], v[8:9], 0, s[4:5]
	v_lshl_add_u64 v[14:15], v[14:15], 2, s[94:95]
	global_load_dword v12, v[14:15], off offset:-2048

; DI int TID() { int t = threadIdx.x; asm volatile("" : "+v"(t)); return t; }
; DI unsigned pk2(float a, float b) { f32x2_t v = {a, b}; bf16x2_t r_ = __builtin_convertvector(v, bf16x2_t); return __builtin_bit_cast(unsigned, r_); }
; template <bool MAP = false>
; DI void conv_tile(const float* __restrict__ src, int N, int K, bfu* __restrict__ dst, const float* __restrict__ g,
;                   int tk, int tn, char* smem, int ldk = -1) {
;   const int LK = ldk < 0 ? K : ldk;
;   float* T = (float*)smem;
;   const int tid = TID();
;   __syncthreads();
; #pragma unroll
;   for (int j = 0; j < 4; ++j) {
;     int k = (tid >> 4) + 16 * j, n4 = (tid & 15) * 4;
;     int gn = tn * 64 + n4, gk = tk * 64 + k;
;     float4 v = make_float4(0.f, 0.f, 0.f, 0.f);
;     const int og = MAP ? in_colmap(gn) : (gn < N ? gn : -1);
;     if (og >= 0) v = *(const float4*)(src + (size_t)gk * N + og);
;     float gg = g ? g[gk] : 1.f;
;     T[k * 65 + n4 + 0] = v.x * gg; T[k * 65 + n4 + 1] = v.y * gg; T[k * 65 + n4 + 2] = v.z * gg; T[k * 65 + n4 + 3] = v.w * gg;
;   }
;   __syncthreads();
; #pragma unroll
;   for (int j = 0; j < 2; ++j) {
;     int n = (tid >> 3) + 32 * j, kc = tid & 7;
;     float e[8];
; #pragma unroll
;     for (int q = 0; q < 8; ++q) e[q] = T[(kc * 8 + q) * 65 + n];
;     u32x4 o = {pk2(e[0], e[1]), pk2(e[2], e[3]), pk2(e[4], e[5]), pk2(e[6], e[7])};
;     *(u32x4*)(dst + (size_t)(tn * 64 + n) * LK + tk * 64 + kc * 8) = o;
;   }
; DI void conv_item_C(const Params& p, int L, int it, char* smem) {
;     ...
;   else if (it < 512) { int t = it - 256; conv_tile(p.w_o + (size_t)L * D * D, D, D, p.wt_o, nullptr, t / 16, t % 16, smem); }
.LBB0_1946:
	s_andn2_b64 vcc, exec, s[2:3]
	s_cbranch_vccnz .LBB0_1948
	v_mov_b32_e32 v8, v224
	s_lshl_b32 s3, s12, 2
	s_lshl_b32 s2, s12, 6
	v_lshlrev_b32_e32 v0, 2, v8
	s_and_b32 s3, s3, 0x7c0
	v_ashrrev_i32_e32 v2, 4, v8
	v_and_b32_e32 v3, 60, v0
	s_and_b32 s2, s2, 0x3c0
	s_add_i32 s96, s3, 0xfffffc00
	v_or_b32_e32 v0, s2, v3
	v_add_u32_e32 v6, s96, v2
	v_lshlrev_b32_e32 v188, 2, v0
	v_ashrrev_i32_e32 v7, 31, v6
	v_lshl_add_u64 v[4:5], s[52:53], 0, v[188:189]
	v_lshlrev_b64 v[0:1], 12, v[6:7]
	s_movk_i32 s3, 0x104
	v_lshl_add_u64 v[0:1], v[4:5], 0, v[0:1]
	v_mul_lo_u32 v2, v2, s3
	s_waitcnt vmcnt(63) expcnt(7) lgkmcnt(15)
	s_barrier
	v_lshl_add_u32 v7, v3, 2, v2
	v_add_u32_e32 v210, 16, v6
	v_ashrrev_i32_e32 v211, 31, v210
	v_lshlrev_b64 v[210:211], 12, v[210:211]
	v_lshl_add_u64 v[210:211], v[4:5], 0, v[210:211]
	global_load_dwordx4 v[240:243], v[210:211], off nt
	v_add_u32_e32 v210, 32, v6
	v_ashrrev_i32_e32 v211, 31, v210
	v_lshlrev_b64 v[210:211], 12, v[210:211]
	v_lshl_add_u64 v[210:211], v[4:5], 0, v[210:211]
	global_load_dwordx4 v[244:247], v[210:211], off nt
	v_add_u32_e32 v210, 48, v6
	v_ashrrev_i32_e32 v211, 31, v210
	v_lshlrev_b64 v[210:211], 12, v[210:211]
	v_lshl_add_u64 v[210:211], v[4:5], 0, v[210:211]
	global_load_dwordx4 v[248:251], v[210:211], off nt
	global_load_dwordx4 v[0:3], v[0:1], off
	v_add_u32_e32 v9, 0x1040, v7
	v_ashrrev_i32_e32 v22, 3, v8
	v_readlane_b32 s16, v253, 48
	s_lshl_b64 s[4:5], s[96:97], 1
	v_readlane_b32 s22, v253, 54
	v_readlane_b32 s23, v253, 55
	s_add_u32 s4, s22, s4
	s_addc_u32 s5, s23, s5
	v_readlane_b32 s17, v253, 49
	v_readlane_b32 s18, v253, 50
	v_readlane_b32 s19, v253, 51
	v_readlane_b32 s20, v253, 52
	v_readlane_b32 s21, v253, 53
	v_readlane_b32 s24, v253, 56
	v_readlane_b32 s25, v253, 57
	v_readlane_b32 s26, v253, 58
	v_readlane_b32 s27, v253, 59
	v_readlane_b32 s28, v253, 60
	v_readlane_b32 s29, v253, 61
	v_readlane_b32 s30, v253, 62
	v_readlane_b32 s31, v253, 63
	s_waitcnt vmcnt(0)
	ds_write2_b32 v7, v0, v1 offset1:1
	ds_write2_b32 v7, v2, v3 offset0:2 offset1:3
	v_add_u32_e32 v0, 16, v6
	v_ashrrev_i32_e32 v1, 31, v0
	v_lshlrev_b64 v[0:1], 12, v[0:1]
	v_lshl_add_u64 v[0:1], v[4:5], 0, v[0:1]
	v_mov_b32_e32 v0, v240
	v_mov_b32_e32 v1, v241
	v_mov_b32_e32 v2, v242
	v_mov_b32_e32 v3, v243
	s_waitcnt vmcnt(0)
	ds_write2_b32 v9, v0, v1 offset1:1
	v_add_u32_e32 v0, 0x1048, v7
	ds_write2_b32 v0, v2, v3 offset1:1
	v_add_u32_e32 v0, 32, v6
	v_ashrrev_i32_e32 v1, 31, v0
	v_lshlrev_b64 v[0:1], 12, v[0:1]
	v_lshl_add_u64 v[0:1], v[4:5], 0, v[0:1]
	v_mov_b32_e32 v0, v244
	v_mov_b32_e32 v1, v245
	v_mov_b32_e32 v2, v246
	v_mov_b32_e32 v3, v247
	v_add_u32_e32 v9, 0x2080, v7
	s_waitcnt vmcnt(0)
	ds_write2_b32 v9, v0, v1 offset1:1
	v_add_u32_e32 v0, 0x2088, v7
	ds_write2_b32 v0, v2, v3 offset1:1
	v_add_u32_e32 v0, 48, v6
	v_ashrrev_i32_e32 v1, 31, v0
	v_lshlrev_b64 v[0:1], 12, v[0:1]
	v_lshl_add_u64 v[0:1], v[4:5], 0, v[0:1]
	v_mov_b32_e32 v0, v248
	v_mov_b32_e32 v1, v249
	v_mov_b32_e32 v2, v250
	v_mov_b32_e32 v3, v251
	v_add_u32_e32 v4, 0x30c0, v7
	s_waitcnt vmcnt(0)
	ds_write2_b32 v4, v0, v1 offset1:1
	v_add_u32_e32 v0, 0x30c8, v7
	ds_write2_b32 v0, v2, v3 offset1:1
	v_lshlrev_b32_e32 v0, 3, v8
	v_and_b32_e32 v2, 56, v0
	v_lshlrev_b32_e32 v188, 1, v2
	v_mul_u32_u24_e32 v2, 0x104, v2
	v_lshl_add_u32 v2, v22, 2, v2
	s_waitcnt lgkmcnt(0)
	s_barrier
	ds_read2_b32 v[6:7], v2 offset1:32
	ds_read2_b32 v[8:9], v2 offset0:65 offset1:97
	ds_read2_b32 v[10:11], v2 offset0:130 offset1:162
	ds_read2_b32 v[12:13], v2 offset0:195 offset1:227
	v_add_u32_e32 v2, 0x400, v2
	ds_read2_b32 v[14:15], v2 offset0:4 offset1:36
	ds_read2_b32 v[16:17], v2 offset0:69 offset1:101
	ds_read2_b32 v[18:19], v2 offset0:134 offset1:166
	ds_read2_b32 v[20:21], v2 offset0:199 offset1:231
	v_add_u32_e32 v22, s2, v22
	v_ashrrev_i32_e32 v23, 31, v22
	v_lshl_add_u64 v[0:1], s[4:5], 0, v[188:189]
	v_lshlrev_b64 v[24:25], 11, v[22:23]
	s_waitcnt lgkmcnt(6)
	v_cvt_pk_bf16_f32 v2, v6, v8
	s_waitcnt lgkmcnt(4)
	v_cvt_pk_bf16_f32 v3, v10, v12
	s_waitcnt lgkmcnt(2)
	v_cvt_pk_bf16_f32 v4, v14, v16
	s_waitcnt lgkmcnt(0)
	v_cvt_pk_bf16_f32 v5, v18, v20
	v_lshl_add_u64 v[24:25], v[0:1], 0, v[24:25]
	v_add_u32_e32 v6, 32, v22
	global_store_dwordx4 v[24:25], v[2:5], off
	s_nop 1
	v_cvt_pk_bf16_f32 v2, v7, v9
	v_ashrrev_i32_e32 v7, 31, v6
	v_lshlrev_b64 v[6:7], 11, v[6:7]
	v_cvt_pk_bf16_f32 v3, v11, v13
	v_cvt_pk_bf16_f32 v4, v15, v17
	v_cvt_pk_bf16_f32 v5, v19, v21
	v_lshl_add_u64 v[0:1], v[0:1], 0, v[6:7]
	global_store_dwordx4 v[0:1], v[2:5], off

; DI int TID() { int t = threadIdx.x; asm volatile("" : "+v"(t)); return t; }
; DI unsigned pk2(float a, float b) { f32x2_t v = {a, b}; bf16x2_t r_ = __builtin_convertvector(v, bf16x2_t); return __builtin_bit_cast(unsigned, r_); }
; template <bool MAP = false>
; DI void conv_tile(const float* __restrict__ src, int N, int K, bfu* __restrict__ dst, const float* __restrict__ g,
;                   int tk, int tn, char* smem, int ldk = -1) {
;   const int LK = ldk < 0 ? K : ldk;
;   float* T = (float*)smem;
;   const int tid = TID();
;   __syncthreads();
; #pragma unroll
;   for (int j = 0; j < 4; ++j) {
;     int k = (tid >> 4) + 16 * j, n4 = (tid & 15) * 4;
;     int gn = tn * 64 + n4, gk = tk * 64 + k;
;     float4 v = make_float4(0.f, 0.f, 0.f, 0.f);
;     const int og = MAP ? in_colmap(gn) : (gn < N ? gn : -1);
;     if (og >= 0) v = *(const float4*)(src + (size_t)gk * N + og);
;     float gg = g ? g[gk] : 1.f;
;     T[k * 65 + n4 + 0] = v.x * gg; T[k * 65 + n4 + 1] = v.y * gg; T[k * 65 + n4 + 2] = v.z * gg; T[k * 65 + n4 + 3] = v.w * gg;
;   }
;   __syncthreads();
; #pragma unroll
;   for (int j = 0; j < 2; ++j) {
;     int n = (tid >> 3) + 32 * j, kc = tid & 7;
;     float e[8];
; #pragma unroll
;     for (int q = 0; q < 8; ++q) e[q] = T[(kc * 8 + q) * 65 + n];
;     u32x4 o = {pk2(e[0], e[1]), pk2(e[2], e[3]), pk2(e[4], e[5]), pk2(e[6], e[7])};
;     *(u32x4*)(dst + (size_t)(tn * 64 + n) * LK + tk * 64 + kc * 8) = o;
;   }
; DI void conv_item_C(const Params& p, int L, int it, char* smem) {
;   if (it < 256) { int t = it; int n = t >> 6; t &= 63; conv_tile(p.w_branch + ((size_t)L * 4 + n) * 256 * D, D, 256, p.wt_br + (size_t)n * 256, nullptr, t / 16, t % 16, smem, 1024); }
.LBB0_1949:
	s_andn2_b64 vcc, exec, s[2:3]
	s_cbranch_vccnz .LBB0_1951
	s_lshr_b32 s96, s12, 6
	s_lshl_b64 s[2:3], s[96:97], 20
	s_add_u32 s4, s89, s2
	v_readlane_b32 s2, v255, 31
	v_readlane_b32 s16, v253, 48
	s_addc_u32 s5, s2, s3
	s_lshl_b64 s[2:3], s[96:97], 9
	v_readlane_b32 s20, v253, 52
	v_readlane_b32 s21, v253, 53
	s_add_u32 s20, s20, s2
	v_mov_b32_e32 v8, v224
	s_addc_u32 s3, s21, s3
	s_lshl_b32 s2, s12, 6
	v_lshlrev_b32_e32 v0, 2, v8
	s_lshl_b32 s12, s12, 2
	v_ashrrev_i32_e32 v2, 4, v8
	v_and_b32_e32 v3, 60, v0
	s_and_b32 s2, s2, 0x3c0
	s_and_b32 s12, s12, 0xc0
	v_or_b32_e32 v0, s2, v3
	v_add_u32_e32 v6, s12, v2
	v_lshlrev_b32_e32 v188, 2, v0
	v_ashrrev_i32_e32 v7, 31, v6
	v_lshl_add_u64 v[4:5], s[4:5], 0, v[188:189]
	v_lshlrev_b64 v[0:1], 12, v[6:7]
	s_movk_i32 s4, 0x104
	v_lshl_add_u64 v[0:1], v[4:5], 0, v[0:1]
	v_mul_lo_u32 v2, v2, s4
	s_waitcnt vmcnt(63) expcnt(7) lgkmcnt(15)
	s_barrier
	v_lshl_add_u32 v7, v3, 2, v2
	v_add_u32_e32 v210, 16, v6
	v_ashrrev_i32_e32 v211, 31, v210
	v_lshlrev_b64 v[210:211], 12, v[210:211]
	v_lshl_add_u64 v[210:211], v[4:5], 0, v[210:211]
	global_load_dwordx4 v[240:243], v[210:211], off nt
	v_add_u32_e32 v210, 32, v6
	v_ashrrev_i32_e32 v211, 31, v210
	v_lshlrev_b64 v[210:211], 12, v[210:211]
	v_lshl_add_u64 v[210:211], v[4:5], 0, v[210:211]
	global_load_dwordx4 v[244:247], v[210:211], off nt
	v_add_u32_e32 v210, 48, v6
	v_ashrrev_i32_e32 v211, 31, v210
	v_lshlrev_b64 v[210:211], 12, v[210:211]
	v_lshl_add_u64 v[210:211], v[4:5], 0, v[210:211]
	global_load_dwordx4 v[248:251], v[210:211], off nt
	global_load_dwordx4 v[0:3], v[0:1], off
	v_add_u32_e32 v9, 0x1040, v7
	v_ashrrev_i32_e32 v22, 3, v8
	s_lshl_b32 s4, s12, 1
	s_add_u32 s4, s20, s4
	s_addc_u32 s5, s3, 0
	v_readlane_b32 s17, v253, 49
	v_readlane_b32 s18, v253, 50
	v_readlane_b32 s19, v253, 51
	v_readlane_b32 s22, v253, 54
	v_readlane_b32 s23, v253, 55
	v_readlane_b32 s24, v253, 56
	v_readlane_b32 s25, v253, 57
	v_readlane_b32 s26, v253, 58
	v_readlane_b32 s27, v253, 59
	v_readlane_b32 s28, v253, 60
	v_readlane_b32 s29, v253, 61
	v_readlane_b32 s30, v253, 62
	v_readlane_b32 s31, v253, 63
	s_waitcnt vmcnt(0)
	ds_write2_b32 v7, v0, v1 offset1:1
	ds_write2_b32 v7, v2, v3 offset0:2 offset1:3
	v_add_u32_e32 v0, 16, v6
	v_ashrrev_i32_e32 v1, 31, v0
	v_lshlrev_b64 v[0:1], 12, v[0:1]
	v_lshl_add_u64 v[0:1], v[4:5], 0, v[0:1]
	v_mov_b32_e32 v0, v240
	v_mov_b32_e32 v1, v241
	v_mov_b32_e32 v2, v242
	v_mov_b32_e32 v3, v243
	s_waitcnt vmcnt(0)
	ds_write2_b32 v9, v0, v1 offset1:1
	v_add_u32_e32 v0, 0x1048, v7
	ds_write2_b32 v0, v2, v3 offset1:1
	v_add_u32_e32 v0, 32, v6
	v_ashrrev_i32_e32 v1, 31, v0
	v_lshlrev_b64 v[0:1], 12, v[0:1]
	v_lshl_add_u64 v[0:1], v[4:5], 0, v[0:1]
	v_mov_b32_e32 v0, v244
	v_mov_b32_e32 v1, v245
	v_mov_b32_e32 v2, v246
	v_mov_b32_e32 v3, v247
	v_add_u32_e32 v9, 0x2080, v7
	s_waitcnt vmcnt(0)
	ds_write2_b32 v9, v0, v1 offset1:1
	v_add_u32_e32 v0, 0x2088, v7
	ds_write2_b32 v0, v2, v3 offset1:1
	v_add_u32_e32 v0, 48, v6
	v_ashrrev_i32_e32 v1, 31, v0
	v_lshlrev_b64 v[0:1], 12, v[0:1]
	v_lshl_add_u64 v[0:1], v[4:5], 0, v[0:1]
	v_mov_b32_e32 v0, v248
	v_mov_b32_e32 v1, v249
	v_mov_b32_e32 v2, v250
	v_mov_b32_e32 v3, v251
	v_add_u32_e32 v4, 0x30c0, v7
	s_waitcnt vmcnt(0)
	ds_write2_b32 v4, v0, v1 offset1:1
	v_add_u32_e32 v0, 0x30c8, v7
	ds_write2_b32 v0, v2, v3 offset1:1
	v_lshlrev_b32_e32 v0, 3, v8
	v_and_b32_e32 v2, 56, v0
	v_lshlrev_b32_e32 v188, 1, v2
	v_mul_u32_u24_e32 v2, 0x104, v2
	v_lshl_add_u32 v2, v22, 2, v2
	s_waitcnt lgkmcnt(0)
	s_barrier
	ds_read2_b32 v[6:7], v2 offset1:32
	ds_read2_b32 v[8:9], v2 offset0:65 offset1:97
	ds_read2_b32 v[10:11], v2 offset0:130 offset1:162
	ds_read2_b32 v[12:13], v2 offset0:195 offset1:227
	v_add_u32_e32 v2, 0x400, v2
	ds_read2_b32 v[14:15], v2 offset0:4 offset1:36
	ds_read2_b32 v[16:17], v2 offset0:69 offset1:101
	ds_read2_b32 v[18:19], v2 offset0:134 offset1:166
	ds_read2_b32 v[20:21], v2 offset0:199 offset1:231
	v_add_u32_e32 v22, s2, v22
	v_ashrrev_i32_e32 v23, 31, v22
	v_lshl_add_u64 v[0:1], s[4:5], 0, v[188:189]
	v_lshlrev_b64 v[24:25], 11, v[22:23]
	s_waitcnt lgkmcnt(6)
	v_cvt_pk_bf16_f32 v2, v6, v8
	s_waitcnt lgkmcnt(4)
	v_cvt_pk_bf16_f32 v3, v10, v12
	s_waitcnt lgkmcnt(2)
	v_cvt_pk_bf16_f32 v4, v14, v16
	s_waitcnt lgkmcnt(0)
	v_cvt_pk_bf16_f32 v5, v18, v20
	v_lshl_add_u64 v[24:25], v[0:1], 0, v[24:25]
	v_add_u32_e32 v6, 32, v22
	global_store_dwordx4 v[24:25], v[2:5], off
	s_nop 1
	v_cvt_pk_bf16_f32 v2, v7, v9
	v_ashrrev_i32_e32 v7, 31, v6
	v_lshlrev_b64 v[6:7], 11, v[6:7]
	v_cvt_pk_bf16_f32 v3, v11, v13
	v_cvt_pk_bf16_f32 v4, v15, v17
	v_cvt_pk_bf16_f32 v5, v19, v21
	v_lshl_add_u64 v[0:1], v[0:1], 0, v[6:7]
	global_store_dwordx4 v[0:1], v[2:5], off

; template <bool MAP = false>
; DI void conv_tile(const float* __restrict__ src, int N, int K, bfu* __restrict__ dst, const float* __restrict__ g,
;                   int tk, int tn, char* smem, int ldk = -1) {
;     ...
;   for (int j = 0; j < 4; ++j) {
;     int k = (tid >> 4) + 16 * j, n4 = (tid & 15) * 4;
;     int gn = tn * 64 + n4, gk = tk * 64 + k;
;     float4 v = make_float4(0.f, 0.f, 0.f, 0.f);
;     const int og = MAP ? in_colmap(gn) : (gn < N ? gn : -1);
;     if (og >= 0) v = *(const float4*)(src + (size_t)gk * N + og);
;     float gg = g ? g[gk] : 1.f;
;     T[k * 65 + n4 + 0] = v.x * gg; T[k * 65 + n4 + 1] = v.y * gg; T[k * 65 + n4 + 2] = v.z * gg; T[k * 65 + n4 + 3] = v.w * gg;
; DI void conv_item_B(const Params& p, int L, int it, char* smem) {
;     ...
;   else if (it < 52) { int t = it - 36; conv_tile(p.mla_w_ukv + (size_t)L * 128 * 512, 512, 128, p.wt_ukv, p.mla_ckv_g + L * 128, t / 8, t % 8, smem); }
.LBB0_1972:
	s_add_i32 s2, s33, 0xfffff91c
	v_mov_b32_e32 v11, v224
	s_lshl_b32 s3, s2, 6
	v_lshlrev_b32_e32 v0, 2, v11
	s_lshl_b32 s2, s2, 3
	v_ashrrev_i32_e32 v13, 4, v11
	v_and_b32_e32 v14, 60, v0
	s_and_b32 s4, s3, 0x1c0
	s_and_b32 s5, s2, 0x7fffffc0
	v_or_b32_e32 v0, s4, v14
	v_add_u32_e32 v8, s5, v13
	v_lshlrev_b32_e32 v188, 2, v0
	v_ashrrev_i32_e32 v9, 31, v8
	v_lshl_add_u64 v[6:7], s[8:9], 0, v[188:189]
	v_lshlrev_b64 v[0:1], 11, v[8:9]
	v_lshl_add_u64 v[0:1], v[6:7], 0, v[0:1]
	s_waitcnt vmcnt(63) expcnt(7) lgkmcnt(15)
	s_barrier
	v_add_u32_e32 v210, 16, v8
	v_ashrrev_i32_e32 v211, 31, v210
	v_lshlrev_b64 v[210:211], 11, v[210:211]
	v_lshl_add_u64 v[210:211], v[6:7], 0, v[210:211]
	global_load_dwordx4 v[240:243], v[210:211], off nt
	v_add_u32_e32 v210, 32, v8
	v_ashrrev_i32_e32 v211, 31, v210
	v_lshlrev_b64 v[210:211], 11, v[210:211]
	v_lshl_add_u64 v[210:211], v[6:7], 0, v[210:211]
	global_load_dwordx4 v[244:247], v[210:211], off nt
	v_add_u32_e32 v210, 48, v8
	v_ashrrev_i32_e32 v211, 31, v210
	v_lshlrev_b64 v[210:211], 11, v[210:211]
	v_lshl_add_u64 v[210:211], v[6:7], 0, v[210:211]
	global_load_dwordx4 v[248:251], v[210:211], off nt
	global_load_dwordx4 v[0:3], v[0:1], off
	v_readlane_b32 s16, v254, 42
	v_readlane_b32 s17, v254, 43
	v_mov_b32_e32 v10, 1.0
	s_andn2_b64 vcc, exec, s[16:17]
	v_cndmask_b32_e64 v4, 0, 1, s[16:17]
	v_cmp_ne_u32_e64 s[2:3], 1, v4
	v_lshl_add_u64 v[4:5], v[8:9], 2, s[10:11]
	v_mov_b32_e32 v12, 1.0
	s_cbranch_vccnz .LBB0_1974
	global_load_dword v12, v[4:5], off

; DI int in_colmap(int n) {
;   if (n < 1280) return n;
;   if (n < 1920) return n + 32;
;   if (n < 2688) return n + 44;
;   if (n < 2720) return n - 2688 + 1280;
;   if (n < 2732) return n - 2720 + 1952;
;   if (n < 2736) return n;
;   if (n < 2752) return -1;
;   if (n < 6848) return n - 16;
;   return -1;
; }
; template <bool MAP = false>
; DI void conv_tile(const float* __restrict__ src, int N, int K, bfu* __restrict__ dst, const float* __restrict__ g,
;                   int tk, int tn, char* smem, int ldk = -1) {
;     ...
;     int gn = tn * 64 + n4, gk = tk * 64 + k;
;     float4 v = make_float4(0.f, 0.f, 0.f, 0.f);
;     const int og = MAP ? in_colmap(gn) : (gn < N ? gn : -1);
;     if (og >= 0) v = *(const float4*)(src + (size_t)gk * N + og);
;     float gg = g ? g[gk] : 1.f;
.LBB0_1993:
	s_andn2_b64 vcc, exec, s[2:3]
	s_cbranch_vccnz .LBB0_1905
	s_mul_hi_i32 s2, s33, 0x4bda12f7
	s_lshr_b32 s3, s2, 31
	s_ashr_i32 s2, s2, 5
	s_add_i32 s2, s2, s3
	s_mul_i32 s3, s2, 0x6c
	v_mov_b32_e32 v9, v224
	s_sub_i32 s3, s33, s3
	s_lshl_b32 s12, s3, 6
	v_lshlrev_b32_e32 v0, 2, v9
	v_and_b32_e32 v5, 60, v0
	s_lshl_b32 s20, s2, 6
	v_or_b32_e32 v0, s12, v5
	s_movk_i32 s2, 0x500
	s_cmpk_lt_u32 s12, 0xa80
	v_cmp_gt_i32_e32 vcc, s2, v0
	s_cselect_b64 s[4:5], -1, 0
	s_add_i32 s2, s12, 0xfffff540
	s_cmpk_lt_u32 s2, 0x1000
	v_add_u32_e32 v1, -16, v0
	s_cselect_b64 s[2:3], -1, 0
	v_cndmask_b32_e64 v1, -1, v1, s[2:3]
	s_movk_i32 s2, 0xab0
	v_cmp_gt_u32_e64 s[2:3], s2, v0
	v_add_u32_e32 v2, 0xfffffd00, v0
	v_add_u32_e32 v3, 0xfffffa80, v0
	v_cndmask_b32_e64 v1, v1, v0, s[2:3]
	s_movk_i32 s2, 0xaac
	v_cmp_gt_u32_e64 s[2:3], s2, v0
	v_ashrrev_i32_e32 v4, 4, v9
	v_add_u32_e32 v6, s20, v4
	v_cndmask_b32_e64 v1, v1, v2, s[2:3]
	s_movk_i32 s2, 0xaa0
	v_cmp_gt_u32_e64 s[2:3], s2, v0
	s_waitcnt vmcnt(63) expcnt(7) lgkmcnt(15)
	s_barrier
	v_cndmask_b32_e64 v1, v1, v3, s[2:3]
	s_or_b64 s[2:3], vcc, s[4:5]
	s_cmpk_lt_u32 s12, 0x780
	s_cselect_b32 s4, 32, 44
	v_mov_b32_e32 v2, s4
	v_cndmask_b32_e64 v2, v2, 0, vcc
	v_add_u32_e32 v0, v2, v0
	v_cndmask_b32_e64 v188, v1, v0, s[2:3]
	v_mov_b32_e32 v0, 0
	v_cmp_lt_i32_e64 s[2:3], -1, v188
	v_mov_b32_e32 v1, v0
	v_mov_b32_e32 v2, v0
	v_mov_b32_e32 v3, v0
	s_and_saveexec_b64 s[4:5], s[2:3]
	s_cbranch_execz .LBB0_1996
	v_mov_b64_e32 v[0:1], s[34:35]
	s_movk_i32 s16, 0x6ac0
	v_mad_i64_i32 v[0:1], s[84:85], v6, s16, v[0:1]
	v_lshl_add_u64 v[0:1], v[188:189], 2, v[0:1]
	v_add_u32_e32 v210, 16, v6
	v_mov_b64_e32 v[212:213], s[34:35]
	v_mad_i64_i32 v[212:213], s[98:99], v210, s16, v[212:213]
	v_lshl_add_u64 v[212:213], v[188:189], 2, v[212:213]
	global_load_dwordx4 v[240:243], v[212:213], off nt
	v_add_u32_e32 v210, 32, v6
	v_mov_b64_e32 v[212:213], s[34:35]
	v_mad_i64_i32 v[212:213], s[98:99], v210, s16, v[212:213]
	v_lshl_add_u64 v[212:213], v[188:189], 2, v[212:213]
	global_load_dwordx4 v[244:247], v[212:213], off nt
	v_add_u32_e32 v210, 48, v6
	v_mov_b64_e32 v[212:213], s[34:35]
	v_mad_i64_i32 v[212:213], s[98:99], v210, s16, v[212:213]
	v_lshl_add_u64 v[212:213], v[188:189], 2, v[212:213]
	global_load_dwordx4 v[248:251], v[212:213], off nt
	global_load_dwordx4 v[0:3], v[0:1], off
